# P5a pk1 staging: counted waits so LDS writes start as each load lands
# baseline (speedup 1.0000x reference)
; #define RAW_WAIT_BARRIER(n) do { asm volatile("s_waitcnt vmcnt(" #n ") lgkmcnt(0)" ::: "memory"); __builtin_amdgcn_s_barrier(); } while (0)
; DI void gemm2_f8(f32x16 (&accA)[4], f32x16 (&accB)[4], const unsigned char* __restrict__ Wb, const unsigned char* __restrict__ Tb,
;                  int K  , u16* smem) {
;     ...
;   for (int kt = 0; kt < nk; ++kt) {
;     RAW_WAIT_BARRIER(6);
;     {
;       const int ktn = kt + 2 < nk ? kt + 2 : nk - 1;
;       int stn = st + 2; if (stn >= 3) stn -= 3;
;       glds2_stage(W16, K2, T16, K2, ktn * 32, smem + stn * G2_STAGE, w, lane);
;     }
;     const u16* sW = smem + st * G2_STAGE;
;     const u16* sT = sW + 8192;
; #pragma unroll
;     for (int ks = 0; ks < 4; ++ks) {
;       const int cs = ((ks ^ swr) * 8) + 4 * h;
;       const long bfr = *(const long*)(sT + (32 * w + r) * 32 + cs);
;       long afr[8];
; #pragma unroll
;       for (int m = 0; m < 8; ++m) afr[m] = *(const long*)(sW + (32 * m + r) * 32 + cs);
; #pragma unroll
;       for (int m = 0; m < 4; ++m) {
;         accA[m] = __builtin_amdgcn_mfma_f32_32x32x16_fp8_fp8(afr[m], bfr, accA[m], 0, 0, 0);
;         accB[m] = __builtin_amdgcn_mfma_f32_32x32x16_fp8_fp8(afr[4 + m], bfr, accB[m], 0, 0, 0);
;       }
;     }
;     st = st + 1; if (st >= 3) st = 0;
;   }
.LBB0_360:
	s_min_u32 s89, s88, 13
	s_cmp_gt_i32 s87, 0
	s_cselect_b32 s90, -1, 2
	s_lshl_b32 s89, s89, 6
	s_add_i32 s90, s90, s87
	s_mul_i32 s93, s90, 0x6000
	s_add_u32 s90, s28, s89
	s_addc_u32 s91, s29, 0
	s_add_i32 s94, s93, s83
	v_lshl_add_u64 v[172:173], s[90:91], 0, v[128:129]
	s_add_i32 s95, s93, s84
	v_lshl_add_u64 v[174:175], s[90:91], 0, v[130:131]
	v_lshl_add_u64 v[172:173], v[172:173], 0, s[24:25]
	s_mov_b32 m0, s94
	s_waitcnt vmcnt(6) lgkmcnt(0)
	s_barrier
	v_lshl_add_u64 v[176:177], v[132:133], 1, s[90:91]
	v_lshl_add_u64 v[174:175], v[174:175], 0, s[24:25]
	global_load_lds_dwordx4 v[172:173], off
	s_mov_b32 m0, s95
	v_lshl_add_u64 v[176:177], v[176:177], 0, s[24:25]
	global_load_lds_dwordx4 v[174:175], off
	s_add_i32 m0, s93, s85
	v_lshl_add_u64 v[178:179], v[154:155], 1, s[90:91]
	global_load_lds_dwordx4 v[176:177], off
	s_add_i32 m0, s93, s86
	s_add_u32 s90, s30, s89
	s_addc_u32 s91, s31, 0
	v_lshl_add_u64 v[178:179], v[178:179], 0, s[24:25]
	v_lshl_add_u64 v[172:173], s[90:91], 0, v[128:129]
	s_mul_i32 s92, s87, 0x6000
	global_load_lds_dwordx4 v[178:179], off
	s_add_i32 m0, s94, 0x4000
	v_lshl_add_u64 v[174:175], s[90:91], 0, v[130:131]
	v_lshl_add_u64 v[172:173], v[172:173], 0, s[24:25]
	v_or_b32_e32 v139, s92, v200
	s_add_i32 s92, s92, s10
	v_lshl_add_u64 v[174:175], v[174:175], 0, s[24:25]
	global_load_lds_dwordx4 v[172:173], off
	s_add_i32 m0, s95, 0x4000
	v_add_u32_e32 v141, v139, v159
	v_add_u32_e32 v143, s92, v200
	global_load_lds_dwordx4 v[174:175], off
	v_add_u32_e32 v145, v143, v159
	v_add_u32_e32 v147, v143, v160
	v_add_u32_e32 v149, v143, v161
	v_add_u32_e32 v143, v143, v162
	ds_read2st64_b64 v[172:175], v141 offset1:4
	ds_read_b64 v[180:181], v145 offset:16384
	ds_read_b64 v[182:183], v147 offset:16384
	ds_read_b64 v[184:185], v149 offset:16384
	ds_read_b64 v[186:187], v143 offset:16384
	ds_read2st64_b64 v[176:179], v141 offset0:16 offset1:20
	s_waitcnt lgkmcnt(0)
	v_mfma_f32_32x32x16_fp8_fp8 v[80:95], v[172:173], v[180:181], v[80:95]
	s_add_i32 s89, s87, 1
	s_cmp_lt_i32 s87, 2
	s_cselect_b32 s87, s89, 0
	s_add_i32 s88, s88, 1
	s_cmp_lg_u32 s88, 16
	v_mfma_f32_32x32x16_fp8_fp8 v[112:127], v[176:177], v[180:181], v[112:127]
	v_mfma_f32_32x32x16_fp8_fp8 v[48:63], v[174:175], v[180:181], v[48:63]
	ds_read2st64_b64 v[172:175], v141 offset0:8 offset1:12
	v_mfma_f32_32x32x16_fp8_fp8 v[96:111], v[178:179], v[180:181], v[96:111]
	ds_read2st64_b64 v[176:179], v141 offset0:24 offset1:28
	v_add_u32_e32 v141, v139, v160
	s_waitcnt lgkmcnt(0)
	v_mfma_f32_32x32x16_fp8_fp8 v[16:31], v[172:173], v[180:181], v[16:31]
	v_mfma_f32_32x32x16_fp8_fp8 v[64:79], v[176:177], v[180:181], v[64:79]
	v_mfma_f32_32x32x16_fp8_fp8 v[0:15], v[174:175], v[180:181], v[0:15]
	ds_read2st64_b64 v[172:175], v141 offset1:4
	v_mfma_f32_32x32x16_fp8_fp8 v[32:47], v[178:179], v[180:181], v[32:47]
	ds_read2st64_b64 v[176:179], v141 offset0:16 offset1:20
	s_waitcnt lgkmcnt(0)
	v_mfma_f32_32x32x16_fp8_fp8 v[80:95], v[172:173], v[182:183], v[80:95]
	v_mfma_f32_32x32x16_fp8_fp8 v[112:127], v[176:177], v[182:183], v[112:127]
	v_mfma_f32_32x32x16_fp8_fp8 v[48:63], v[174:175], v[182:183], v[48:63]
	ds_read2st64_b64 v[172:175], v141 offset0:8 offset1:12
	v_mfma_f32_32x32x16_fp8_fp8 v[96:111], v[178:179], v[182:183], v[96:111]
	ds_read2st64_b64 v[176:179], v141 offset0:24 offset1:28
	v_add_u32_e32 v141, v139, v161
	v_add_u32_e32 v139, v139, v162
	s_waitcnt lgkmcnt(0)
	v_mfma_f32_32x32x16_fp8_fp8 v[16:31], v[172:173], v[182:183], v[16:31]
	v_mfma_f32_32x32x16_fp8_fp8 v[64:79], v[176:177], v[182:183], v[64:79]
	v_mfma_f32_32x32x16_fp8_fp8 v[0:15], v[174:175], v[182:183], v[0:15]
	ds_read2st64_b64 v[172:175], v141 offset1:4
	v_mfma_f32_32x32x16_fp8_fp8 v[32:47], v[178:179], v[182:183], v[32:47]
	ds_read2st64_b64 v[176:179], v141 offset0:16 offset1:20
	s_waitcnt lgkmcnt(0)
	v_mfma_f32_32x32x16_fp8_fp8 v[80:95], v[172:173], v[184:185], v[80:95]
	v_mfma_f32_32x32x16_fp8_fp8 v[112:127], v[176:177], v[184:185], v[112:127]
	v_mfma_f32_32x32x16_fp8_fp8 v[48:63], v[174:175], v[184:185], v[48:63]
	ds_read2st64_b64 v[172:175], v141 offset0:8 offset1:12
	v_mfma_f32_32x32x16_fp8_fp8 v[96:111], v[178:179], v[184:185], v[96:111]
	ds_read2st64_b64 v[176:179], v141 offset0:24 offset1:28
	s_waitcnt lgkmcnt(0)
	v_mfma_f32_32x32x16_fp8_fp8 v[16:31], v[172:173], v[184:185], v[16:31]
	v_mfma_f32_32x32x16_fp8_fp8 v[64:79], v[176:177], v[184:185], v[64:79]
	v_mfma_f32_32x32x16_fp8_fp8 v[0:15], v[174:175], v[184:185], v[0:15]
	ds_read2st64_b64 v[172:175], v139 offset1:4
	v_mfma_f32_32x32x16_fp8_fp8 v[32:47], v[178:179], v[184:185], v[32:47]
	ds_read2st64_b64 v[176:179], v139 offset0:16 offset1:20
	s_waitcnt lgkmcnt(0)
	v_mfma_f32_32x32x16_fp8_fp8 v[80:95], v[172:173], v[186:187], v[80:95]
	v_mfma_f32_32x32x16_fp8_fp8 v[112:127], v[176:177], v[186:187], v[112:127]
	v_mfma_f32_32x32x16_fp8_fp8 v[48:63], v[174:175], v[186:187], v[48:63]
	ds_read2st64_b64 v[172:175], v139 offset0:8 offset1:12
	v_mfma_f32_32x32x16_fp8_fp8 v[96:111], v[178:179], v[186:187], v[96:111]
	ds_read2st64_b64 v[176:179], v139 offset0:24 offset1:28
	s_waitcnt lgkmcnt(0)
	v_mfma_f32_32x32x16_fp8_fp8 v[16:31], v[172:173], v[186:187], v[16:31]
	v_mfma_f32_32x32x16_fp8_fp8 v[64:79], v[176:177], v[186:187], v[64:79]
	v_mfma_f32_32x32x16_fp8_fp8 v[0:15], v[174:175], v[186:187], v[0:15]
	v_mfma_f32_32x32x16_fp8_fp8 v[32:47], v[178:179], v[186:187], v[32:47]
	s_cbranch_scc1 .LBB0_360
; #define MFMA32(a, b, c) __builtin_amdgcn_mfma_f32_32x32x16_bf16((a), (b), (c), 0, 0, 0)
; DI void p5a_half(const bf16x8 (&qf)[8], const u16* __restrict__ pk, float rs, int (&Lh)[16], u16* smem, int tid, int r, int h) {
; #pragma unroll
;   for (int i = 0; i < 8; ++i) {
;     int pidx = tid + 256 * i; int row = pidx >> 4, ch = pidx & 15;
;     uint4 v = *(const uint4*)(pk + row * 128 + ch * 8);
;     uint2* d = (uint2*)(smem + row * LPK + ch * 8);
;     d[0] = make_uint2(v.x, v.y); d[1] = make_uint2(v.z, v.w);
;   }
;   __syncthreads();
; #pragma unroll
;   for (int j = 0; j < 16; ++j) Lh[j] = (int)0x80000000;
; #pragma unroll
;   for (int kt = 0; kt < 4; ++kt) {
;     f32x16 Y = zero16();
; #pragma unroll
;     for (int ks = 0; ks < 8; ++ks) {
;       const int m = ks >> 1, s = ks & 1;
;       const u16* pp = smem + (kt * 32 + r) * LPK + 32 * m + 16 * s + 4 * h;
;       s16x4 lo = *(const s16x4*)pp;
;       s16x4 hi = *(const s16x4*)(pp + 8);
;       bf16x8 a = __builtin_shufflevector(lo, hi, 0, 1, 2, 3, 4, 5, 6, 7);
;       Y = MFMA32(a, qf[ks], Y);
; DI void phase5a(const Params& p, u16* smem) {
;     ...
;       gemm2_f8(accA, accB, ws + OFF_WPQT + (size_t)hd * 256 * 1024, ws + OFF_H8 + (size_t)t0 * 1024, 1024, smem);
;       const float rs = 1.0f / 32.0f;
;       bf16x8 qfA[8], qfB[8];
; #pragma unroll
;       for (int m = 0; m < 4; ++m) {
;         qfA[2 * m] = pack8(accA[m], 0); qfA[2 * m + 1] = pack8(accA[m], 1);
;         qfB[2 * m] = pack8(accB[m], 0); qfB[2 * m + 1] = pack8(accB[m], 1);
;       }
;       __builtin_amdgcn_sched_barrier(0);
	s_waitcnt vmcnt(0) lgkmcnt(0)
	s_nop 0
	v_cvt_pk_bf16_f32 v88, v88, v89
	v_cvt_pk_bf16_f32 v89, v90, v91
	v_cvt_pk_bf16_f32 v91, v94, v95
	v_cvt_pk_bf16_f32 v94, v52, v53
	v_cvt_pk_bf16_f32 v52, v96, v97
	v_cvt_pk_bf16_f32 v53, v98, v99
	s_nop 0
	v_cvt_pk_bf16_f32 v96, v16, v17
	v_cvt_pk_bf16_f32 v97, v18, v19
	v_cvt_pk_bf16_f32 v98, v20, v21
	v_cvt_pk_bf16_f32 v20, v64, v65
	v_cvt_pk_bf16_f32 v21, v66, v67
	v_cvt_pk_bf16_f32 v16, v72, v73
	v_cvt_pk_bf16_f32 v17, v74, v75
	v_cvt_pk_bf16_f32 v18, v76, v77
	v_cvt_pk_bf16_f32 v19, v78, v79
	s_barrier
	v_cvt_pk_bf16_f32 v128, v80, v81
	v_cvt_pk_bf16_f32 v129, v82, v83
	v_cvt_pk_bf16_f32 v130, v84, v85
	v_cvt_pk_bf16_f32 v131, v86, v87
	v_cvt_pk_bf16_f32 v90, v92, v93
	v_cvt_pk_bf16_f32 v80, v112, v113
	v_cvt_pk_bf16_f32 v81, v114, v115
	v_cvt_pk_bf16_f32 v82, v116, v117
	v_cvt_pk_bf16_f32 v83, v118, v119
	v_cvt_pk_bf16_f32 v84, v120, v121
	v_cvt_pk_bf16_f32 v85, v122, v123
	v_cvt_pk_bf16_f32 v86, v124, v125
	v_cvt_pk_bf16_f32 v87, v126, v127
	v_cvt_pk_bf16_f32 v92, v48, v49
	v_cvt_pk_bf16_f32 v93, v50, v51
	v_cvt_pk_bf16_f32 v95, v54, v55
	v_cvt_pk_bf16_f32 v56, v56, v57
	v_cvt_pk_bf16_f32 v57, v58, v59
	v_cvt_pk_bf16_f32 v58, v60, v61
	v_cvt_pk_bf16_f32 v59, v62, v63
	v_cvt_pk_bf16_f32 v54, v100, v101
	v_cvt_pk_bf16_f32 v55, v102, v103
	v_cvt_pk_bf16_f32 v48, v104, v105
	v_cvt_pk_bf16_f32 v49, v106, v107
	v_cvt_pk_bf16_f32 v50, v108, v109
	v_cvt_pk_bf16_f32 v51, v110, v111
	v_cvt_pk_bf16_f32 v99, v22, v23
	v_cvt_pk_bf16_f32 v60, v24, v25
	v_cvt_pk_bf16_f32 v61, v26, v27
	v_cvt_pk_bf16_f32 v62, v28, v29
	v_cvt_pk_bf16_f32 v63, v30, v31
	v_cvt_pk_bf16_f32 v22, v68, v69
	v_cvt_pk_bf16_f32 v23, v70, v71
	v_cvt_pk_bf16_f32 v68, v0, v1
	v_cvt_pk_bf16_f32 v69, v2, v3
	v_cvt_pk_bf16_f32 v70, v4, v5
	v_cvt_pk_bf16_f32 v71, v6, v7
	v_cvt_pk_bf16_f32 v64, v8, v9
	v_cvt_pk_bf16_f32 v65, v10, v11
	v_cvt_pk_bf16_f32 v66, v12, v13
	v_cvt_pk_bf16_f32 v67, v14, v15
	v_cvt_pk_bf16_f32 v28, v32, v33
	v_cvt_pk_bf16_f32 v29, v34, v35
	v_cvt_pk_bf16_f32 v30, v36, v37
	v_cvt_pk_bf16_f32 v31, v38, v39
	v_cvt_pk_bf16_f32 v24, v40, v41
	v_cvt_pk_bf16_f32 v25, v42, v43
	v_cvt_pk_bf16_f32 v26, v44, v45
	v_cvt_pk_bf16_f32 v27, v46, v47
	s_lshl_b32 s10, s81, 15
	v_lshl_add_u64 v[40:41], v[134:135], 0, s[10:11]
	v_mov_b32_e32 v139, v133
	v_mov_b32_e32 v141, v133
	v_mov_b32_e32 v143, v133
	v_mov_b32_e32 v145, v133
	v_mov_b32_e32 v147, v133
	v_mov_b32_e32 v149, v133
	v_mov_b32_e32 v151, v133
	v_mov_b32_e32 v153, v133
	v_lshl_add_u64 v[0:1], v[40:41], 0, v[138:139]
	v_lshl_add_u64 v[4:5], v[40:41], 0, v[140:141]
	v_lshl_add_u64 v[8:9], v[40:41], 0, v[142:143]
	v_lshl_add_u64 v[12:13], v[40:41], 0, v[144:145]
	v_lshl_add_u64 v[32:33], v[40:41], 0, v[146:147]
	v_lshl_add_u64 v[36:37], v[40:41], 0, v[148:149]
	v_lshl_add_u64 v[42:43], v[40:41], 0, v[150:151]
	v_lshl_add_u64 v[44:45], v[40:41], 0, v[152:153]
	global_load_dwordx4 v[0:3], v[0:1], off
	s_nop 0
	global_load_dwordx4 v[4:7], v[4:5], off
	s_nop 0
	global_load_dwordx4 v[8:11], v[8:9], off
	s_nop 0
	global_load_dwordx4 v[12:15], v[12:13], off
	s_nop 0
	global_load_dwordx4 v[32:35], v[32:33], off
	s_nop 0
	global_load_dwordx4 v[36:39], v[36:37], off
	s_nop 0
	global_load_dwordx4 v[40:43], v[42:43], off
	s_nop 0
	global_load_dwordx4 v[44:47], v[44:45], off
	v_add_u32_e32 v75, 0x4200, v163
	s_waitcnt vmcnt(7)
	ds_write2_b64 v163, v[0:1], v[2:3] offset1:1
	s_waitcnt vmcnt(6)
	ds_write2_b64 v164, v[4:5], v[6:7] offset1:1
	s_waitcnt vmcnt(5)
	ds_write2_b64 v165, v[8:9], v[10:11] offset1:1
	s_waitcnt vmcnt(4)
	ds_write2_b64 v166, v[12:13], v[14:15] offset1:1
	s_waitcnt vmcnt(3)
	ds_write2_b64 v75, v[32:33], v[34:35] offset1:1
	s_waitcnt vmcnt(2)
	ds_write2_b64 v167, v[36:37], v[38:39] offset1:1
	s_waitcnt vmcnt(1)
	ds_write2_b64 v168, v[40:41], v[42:43] offset1:1
	s_waitcnt vmcnt(0)
	ds_write2_b64 v169, v[44:45], v[46:47] offset1:1
	s_waitcnt lgkmcnt(0)
	s_barrier
	ds_read2_b64 v[0:3], v156 offset1:2
	ds_read2_b64 v[32:35], v156 offset0:4 offset1:6
	s_waitcnt lgkmcnt(1)
	v_mfma_f32_32x32x16_bf16 v[0:15], v[0:3], v[128:131], 0
	s_waitcnt lgkmcnt(0)
	v_mfma_f32_32x32x16_bf16 v[0:15], v[32:35], v[88:91], v[0:15]
	ds_read2_b64 v[32:35], v156 offset0:8 offset1:10
	s_waitcnt lgkmcnt(0)
	v_mfma_f32_32x32x16_bf16 v[0:15], v[32:35], v[92:95], v[0:15]
	ds_read2_b64 v[32:35], v156 offset0:12 offset1:14
	s_waitcnt lgkmcnt(0)
	v_mfma_f32_32x32x16_bf16 v[0:15], v[32:35], v[56:59], v[0:15]
	ds_read2_b64 v[32:35], v156 offset0:16 offset1:18
	s_waitcnt lgkmcnt(0)
	v_mfma_f32_32x32x16_bf16 v[0:15], v[32:35], v[96:99], v[0:15]
	ds_read2_b64 v[32:35], v156 offset0:20 offset1:22
	s_waitcnt lgkmcnt(0)
	v_mfma_f32_32x32x16_bf16 v[0:15], v[32:35], v[60:63], v[0:15]
	ds_read2_b64 v[32:35], v156 offset0:24 offset1:26
	s_waitcnt lgkmcnt(0)
	v_mfma_f32_32x32x16_bf16 v[0:15], v[32:35], v[68:71], v[0:15]
	ds_read2_b64 v[32:35], v156 offset0:28 offset1:30
	s_waitcnt lgkmcnt(0)
; DI int med3i(int a, int b, int c) { int r; asm("v_med3_i32 %0, %1, %2, %3" : "=v"(r) : "v"(a), "v"(b), "v"(c)); return r; }
; DI void insert16(int (&L)[16], int x) {
; #pragma unroll
;   for (int j = 15; j >= 1; --j) L[j] = med3i(L[j - 1], L[j], x);
;   L[0] = max(L[0], x);
; }
; DI int f2sort(float f) { int b = __float_as_int(f); return b ^ ((b >> 31) & 0x7fffffff); }
; DI float sort2f(int b) { return __int_as_float(b ^ ((b >> 31) & 0x7fffffff)); }
; DI void p5a_half(const bf16x8 (&qf)[8], const u16* __restrict__ pk, float rs, int (&Lh)[16], u16* smem, int tid, int r, int h) {
;     ...
; #pragma unroll
;     for (int i = 0; i < 16; ++i) {
;       const int keyc = kt * 32 + (i & 3) + 8 * (i >> 2);
;       int sb = (f2sort(Y[i] * rs) & ~127) | keyc;
;       insert16(Lh, sb);
;     }
	v_mfma_f32_32x32x16_bf16 v[0:15], v[32:35], v[64:67], v[0:15]
	s_nop 11
	v_pk_mul_f32 v[0:1], v[0:1], s[26:27] op_sel_hi:[1,0]
	v_pk_mul_f32 v[2:3], v[2:3], s[26:27] op_sel_hi:[1,0]
	v_ashrrev_i32_e32 v32, 31, v0
	v_and_b32_e32 v0, 0xffffff80, v0
	v_ashrrev_i32_e32 v33, 31, v1
	v_pk_mul_f32 v[4:5], v[4:5], s[26:27] op_sel_hi:[1,0]
	v_pk_mul_f32 v[6:7], v[6:7], s[26:27] op_sel_hi:[1,0]
	v_pk_mul_f32 v[8:9], v[8:9], s[26:27] op_sel_hi:[1,0]
	v_pk_mul_f32 v[10:11], v[10:11], s[26:27] op_sel_hi:[1,0]
	v_and_b32_e32 v1, 0xffffff80, v1
	v_ashrrev_i32_e32 v34, 31, v2
	v_bitop3_b32 v0, v32, v0, s37 bitop3:0x6c
	v_and_b32_e32 v32, 0x7fffff80, v33
	v_and_b32_e32 v2, 0xffffff80, v2
	v_ashrrev_i32_e32 v35, 31, v3
	v_ashrrev_i32_e32 v36, 31, v4
	v_ashrrev_i32_e32 v37, 31, v5
	v_ashrrev_i32_e32 v38, 31, v6
	v_ashrrev_i32_e32 v39, 31, v7
	v_ashrrev_i32_e32 v40, 31, v8
	v_ashrrev_i32_e32 v41, 31, v9
	v_ashrrev_i32_e32 v42, 31, v10
	v_and_b32_e32 v33, 0x7fffff80, v34
	v_bitop3_b32 v1, v32, 1, v1 bitop3:0xde
	v_and_b32_e32 v3, 0xffffff80, v3
	v_and_b32_e32 v34, 0x7fffff80, v35
	v_and_b32_e32 v35, 0x7fffff80, v36
	v_and_b32_e32 v36, 0x7fffff80, v37
	v_and_b32_e32 v37, 0x7fffff80, v38
	v_and_b32_e32 v38, 0x7fffff80, v39
	v_and_b32_e32 v39, 0x7fffff80, v40
	v_and_b32_e32 v40, 0x7fffff80, v41
	v_and_b32_e32 v41, 0x7fffff80, v42
	v_med3_i32 v42, v170, v170, v0
	v_bitop3_b32 v2, v33, 2, v2 bitop3:0xde
	v_med3_i32 v32, v42, v42, v1
	v_med3_i32 v33, v0, v42, v1
	v_max_i32_e32 v0, v0, v1
	v_and_b32_e32 v4, 0xffffff80, v4
	v_bitop3_b32 v3, v34, 3, v3 bitop3:0xde
	v_med3_i32 v1, v32, v32, v2
	v_med3_i32 v32, v33, v32, v2
	v_med3_i32 v33, v0, v33, v2
	v_max_i32_e32 v0, v0, v2
	v_and_b32_e32 v5, 0xffffff80, v5
	v_bitop3_b32 v4, v35, 8, v4 bitop3:0xde
	v_med3_i32 v2, v1, v1, v3
	v_med3_i32 v1, v32, v1, v3
	v_med3_i32 v32, v33, v32, v3
	v_med3_i32 v33, v0, v33, v3
	v_max_i32_e32 v0, v0, v3
	v_and_b32_e32 v6, 0xffffff80, v6
	v_bitop3_b32 v5, v36, 9, v5 bitop3:0xde
	v_med3_i32 v3, v2, v2, v4
	v_med3_i32 v2, v1, v2, v4
	v_med3_i32 v1, v32, v1, v4
	v_med3_i32 v32, v33, v32, v4
	v_med3_i32 v33, v0, v33, v4
	v_max_i32_e32 v0, v0, v4
	v_and_b32_e32 v7, 0xffffff80, v7
	v_bitop3_b32 v6, v37, 10, v6 bitop3:0xde
	v_med3_i32 v4, v3, v3, v5
	v_med3_i32 v3, v2, v3, v5
	v_med3_i32 v2, v1, v2, v5
	v_med3_i32 v1, v32, v1, v5
	v_med3_i32 v32, v33, v32, v5
	v_med3_i32 v33, v0, v33, v5
	v_max_i32_e32 v0, v0, v5
	v_and_b32_e32 v8, 0xffffff80, v8
	v_bitop3_b32 v7, v38, 11, v7 bitop3:0xde
	v_med3_i32 v5, v4, v4, v6
	v_med3_i32 v4, v3, v4, v6
	v_med3_i32 v3, v2, v3, v6
	v_med3_i32 v2, v1, v2, v6
	v_med3_i32 v1, v32, v1, v6
	v_med3_i32 v32, v33, v32, v6
	v_med3_i32 v33, v0, v33, v6
	v_max_i32_e32 v0, v0, v6
	v_and_b32_e32 v9, 0xffffff80, v9
	v_bitop3_b32 v8, v39, 16, v8 bitop3:0xde
	v_med3_i32 v6, v5, v5, v7
	v_med3_i32 v5, v4, v5, v7
	v_med3_i32 v4, v3, v4, v7
	v_med3_i32 v3, v2, v3, v7
	v_med3_i32 v2, v1, v2, v7
	v_med3_i32 v1, v32, v1, v7
	v_med3_i32 v32, v33, v32, v7
	v_med3_i32 v33, v0, v33, v7
	v_max_i32_e32 v0, v0, v7
	v_and_b32_e32 v10, 0xffffff80, v10
	v_bitop3_b32 v9, v40, 17, v9 bitop3:0xde
	v_med3_i32 v7, v6, v6, v8
	v_med3_i32 v6, v5, v6, v8
	v_med3_i32 v5, v4, v5, v8
	v_med3_i32 v4, v3, v4, v8
	v_med3_i32 v3, v2, v3, v8
	v_med3_i32 v2, v1, v2, v8
	v_med3_i32 v1, v32, v1, v8
	v_med3_i32 v32, v33, v32, v8
	v_med3_i32 v33, v0, v33, v8
	v_max_i32_e32 v0, v0, v8
	v_bitop3_b32 v10, v41, 18, v10 bitop3:0xde
	v_med3_i32 v8, v7, v7, v9
	v_med3_i32 v7, v6, v7, v9
	v_med3_i32 v6, v5, v6, v9
	v_med3_i32 v5, v4, v5, v9
	v_med3_i32 v4, v3, v4, v9
	v_med3_i32 v3, v2, v3, v9
	v_med3_i32 v2, v1, v2, v9
	v_med3_i32 v1, v32, v1, v9
	v_med3_i32 v32, v33, v32, v9
	v_med3_i32 v33, v0, v33, v9
	v_max_i32_e32 v0, v0, v9
	v_med3_i32 v9, v8, v8, v10
	v_med3_i32 v8, v7, v8, v10
	v_med3_i32 v7, v6, v7, v10
	v_med3_i32 v6, v5, v6, v10
	v_med3_i32 v5, v4, v5, v10
	v_med3_i32 v4, v3, v4, v10
	v_med3_i32 v3, v2, v3, v10
	v_med3_i32 v2, v1, v2, v10
	v_med3_i32 v1, v32, v1, v10
	v_med3_i32 v32, v33, v32, v10
	v_med3_i32 v33, v0, v33, v10
	v_max_i32_e32 v0, v0, v10
	v_ashrrev_i32_e32 v10, 31, v11
	v_and_b32_e32 v10, 0x7fffff80, v10
	v_and_b32_e32 v11, 0xffffff80, v11
	v_bitop3_b32 v10, v10, 19, v11 bitop3:0xde
	v_med3_i32 v11, v9, v9, v10
	v_med3_i32 v9, v8, v9, v10
	v_med3_i32 v8, v7, v8, v10
	v_med3_i32 v7, v6, v7, v10
	v_med3_i32 v6, v5, v6, v10
	v_med3_i32 v5, v4, v5, v10
	v_med3_i32 v4, v3, v4, v10
	v_med3_i32 v3, v2, v3, v10
	v_med3_i32 v2, v1, v2, v10
	v_med3_i32 v34, v32, v1, v10
	v_med3_i32 v32, v33, v32, v10
	v_med3_i32 v33, v0, v33, v10
	v_max_i32_e32 v10, v0, v10
	v_pk_mul_f32 v[0:1], v[12:13], s[26:27] op_sel_hi:[1,0]
	s_nop 0
	v_ashrrev_i32_e32 v12, 31, v0
	v_and_b32_e32 v12, 0x7fffff80, v12
	v_and_b32_e32 v0, 0xffffff80, v0
	v_bitop3_b32 v0, v12, 24, v0 bitop3:0xde
	v_med3_i32 v12, v11, v11, v0
	v_med3_i32 v11, v9, v11, v0
	v_med3_i32 v9, v8, v9, v0
	v_med3_i32 v8, v7, v8, v0
	v_med3_i32 v7, v6, v7, v0
	v_med3_i32 v6, v5, v6, v0
	v_med3_i32 v5, v4, v5, v0
	v_med3_i32 v4, v3, v4, v0
	v_med3_i32 v3, v2, v3, v0
	v_med3_i32 v2, v34, v2, v0
	v_med3_i32 v13, v32, v34, v0
	v_med3_i32 v32, v33, v32, v0
	v_med3_i32 v33, v10, v33, v0
	v_max_i32_e32 v0, v10, v0
	v_ashrrev_i32_e32 v10, 31, v1
	v_and_b32_e32 v10, 0x7fffff80, v10
	v_and_b32_e32 v1, 0xffffff80, v1
	v_bitop3_b32 v1, v10, 25, v1 bitop3:0xde
	v_med3_i32 v10, v12, v12, v1
	v_med3_i32 v12, v11, v12, v1
	v_med3_i32 v11, v9, v11, v1
	v_med3_i32 v9, v8, v9, v1
	v_med3_i32 v8, v7, v8, v1
	v_med3_i32 v7, v6, v7, v1
	v_med3_i32 v6, v5, v6, v1
	v_med3_i32 v5, v4, v5, v1
	v_med3_i32 v4, v3, v4, v1
	v_med3_i32 v3, v2, v3, v1
	v_med3_i32 v2, v13, v2, v1
; #define MFMA32(a, b, c) __builtin_amdgcn_mfma_f32_32x32x16_bf16((a), (b), (c), 0, 0, 0)
; DI int med3i(int a, int b, int c) { int r; asm("v_med3_i32 %0, %1, %2, %3" : "=v"(r) : "v"(a), "v"(b), "v"(c)); return r; }
; DI void insert16(int (&L)[16], int x) {
; #pragma unroll
;   for (int j = 15; j >= 1; --j) L[j] = med3i(L[j - 1], L[j], x);
;   L[0] = max(L[0], x);
; }
; DI int f2sort(float f) { int b = __float_as_int(f); return b ^ ((b >> 31) & 0x7fffffff); }
; DI void p5a_half(const bf16x8 (&qf)[8], const u16* __restrict__ pk, float rs, int (&Lh)[16], u16* smem, int tid, int r, int h) {
;     ...
;   for (int kt = 0; kt < 4; ++kt) {
;     f32x16 Y = zero16();
; #pragma unroll
;     for (int ks = 0; ks < 8; ++ks) {
;       const int m = ks >> 1, s = ks & 1;
;       const u16* pp = smem + (kt * 32 + r) * LPK + 32 * m + 16 * s + 4 * h;
;       s16x4 lo = *(const s16x4*)pp;
;       s16x4 hi = *(const s16x4*)(pp + 8);
;       bf16x8 a = __builtin_shufflevector(lo, hi, 0, 1, 2, 3, 4, 5, 6, 7);
;       Y = MFMA32(a, qf[ks], Y);
;     }
; #pragma unroll
;     for (int i = 0; i < 16; ++i) {
;       const int keyc = kt * 32 + (i & 3) + 8 * (i >> 2);
;       int sb = (f2sort(Y[i] * rs) & ~127) | keyc;
;       insert16(Lh, sb);
;     }
;     __builtin_amdgcn_sched_barrier(0);
	v_med3_i32 v13, v32, v13, v1
	v_med3_i32 v32, v33, v32, v1
	v_med3_i32 v33, v0, v33, v1
	v_max_i32_e32 v34, v0, v1
	v_pk_mul_f32 v[0:1], v[14:15], s[26:27] op_sel_hi:[1,0]
	s_nop 0
	v_ashrrev_i32_e32 v14, 31, v0
	v_and_b32_e32 v14, 0x7fffff80, v14
	v_and_b32_e32 v0, 0xffffff80, v0
	v_bitop3_b32 v0, v14, 26, v0 bitop3:0xde
	v_med3_i32 v14, v10, v10, v0
	v_med3_i32 v10, v12, v10, v0
	v_med3_i32 v12, v11, v12, v0
	v_med3_i32 v11, v9, v11, v0
	v_med3_i32 v9, v8, v9, v0
	v_med3_i32 v8, v7, v8, v0
	v_med3_i32 v7, v6, v7, v0
	v_med3_i32 v6, v5, v6, v0
	v_med3_i32 v5, v4, v5, v0
	v_med3_i32 v4, v3, v4, v0
	v_med3_i32 v3, v2, v3, v0
	v_med3_i32 v2, v13, v2, v0
	v_med3_i32 v13, v32, v13, v0
	v_med3_i32 v15, v33, v32, v0
	v_med3_i32 v32, v34, v33, v0
	v_ashrrev_i32_e32 v33, 31, v1
	v_and_b32_e32 v33, 0x7fffff80, v33
	v_and_b32_e32 v1, 0xffffff80, v1
	v_max_i32_e32 v0, v34, v0
	v_bitop3_b32 v1, v33, 27, v1 bitop3:0xde
	v_med3_i32 v36, v10, v14, v1
	v_med3_i32 v37, v12, v10, v1
	v_med3_i32 v38, v11, v12, v1
	v_med3_i32 v39, v9, v11, v1
	v_med3_i32 v40, v8, v9, v1
	v_med3_i32 v41, v7, v8, v1
	v_med3_i32 v42, v6, v7, v1
	v_med3_i32 v43, v5, v6, v1
	v_med3_i32 v44, v4, v5, v1
	v_med3_i32 v45, v3, v4, v1
	v_med3_i32 v46, v2, v3, v1
	v_med3_i32 v47, v13, v2, v1
	v_med3_i32 v73, v15, v13, v1
	v_med3_i32 v74, v32, v15, v1
	v_med3_i32 v76, v0, v32, v1
	v_max_i32_e32 v77, v0, v1
	v_add_u32_e32 v72, 0x2000, v156
	ds_read2_b64 v[0:3], v72 offset0:32 offset1:34
	ds_read2_b64 v[32:35], v72 offset0:36 offset1:38
	s_waitcnt lgkmcnt(1)
	v_mfma_f32_32x32x16_bf16 v[0:15], v[0:3], v[128:131], 0
	s_waitcnt lgkmcnt(0)
	v_mfma_f32_32x32x16_bf16 v[0:15], v[32:35], v[88:91], v[0:15]
	ds_read2_b64 v[32:35], v72 offset0:40 offset1:42
	s_waitcnt lgkmcnt(0)
	v_mfma_f32_32x32x16_bf16 v[0:15], v[32:35], v[92:95], v[0:15]
	ds_read2_b64 v[32:35], v72 offset0:44 offset1:46
	s_waitcnt lgkmcnt(0)
	v_mfma_f32_32x32x16_bf16 v[0:15], v[32:35], v[56:59], v[0:15]
	ds_read2_b64 v[32:35], v72 offset0:48 offset1:50
	s_waitcnt lgkmcnt(0)
	v_mfma_f32_32x32x16_bf16 v[0:15], v[32:35], v[96:99], v[0:15]
	ds_read2_b64 v[32:35], v72 offset0:52 offset1:54
	s_waitcnt lgkmcnt(0)
	v_mfma_f32_32x32x16_bf16 v[0:15], v[32:35], v[60:63], v[0:15]
	ds_read2_b64 v[32:35], v72 offset0:56 offset1:58
	s_waitcnt lgkmcnt(0)
	v_mfma_f32_32x32x16_bf16 v[0:15], v[32:35], v[68:71], v[0:15]
	ds_read2_b64 v[32:35], v72 offset0:60 offset1:62
	s_waitcnt lgkmcnt(0)
	v_mfma_f32_32x32x16_bf16 v[0:15], v[32:35], v[64:67], v[0:15]
	s_nop 11
	v_pk_mul_f32 v[0:1], v[0:1], s[26:27] op_sel_hi:[1,0]
	v_pk_mul_f32 v[2:3], v[2:3], s[26:27] op_sel_hi:[1,0]
	v_ashrrev_i32_e32 v32, 31, v0
	v_and_b32_e32 v0, 0xffffff80, v0
	v_ashrrev_i32_e32 v33, 31, v1
	v_ashrrev_i32_e32 v34, 31, v2
	v_and_b32_e32 v32, 0x7fffff80, v32
	v_and_b32_e32 v1, 0xffffff80, v1
	v_and_b32_e32 v2, 0xffffff80, v2
	v_and_b32_e32 v33, 0x7fffff80, v33
	v_and_b32_e32 v34, 0x7fffff80, v34
	v_bitop3_b32 v0, v32, 32, v0 bitop3:0xde
	v_bitop3_b32 v1, v33, 33, v1 bitop3:0xde
	v_bitop3_b32 v2, v34, 34, v2 bitop3:0xde
	v_med3_i32 v32, v37, v36, v0
	v_med3_i32 v33, v38, v37, v0
	v_med3_i32 v34, v39, v38, v0
	v_med3_i32 v36, v40, v39, v0
	v_med3_i32 v37, v41, v40, v0
	v_med3_i32 v38, v42, v41, v0
	v_med3_i32 v39, v43, v42, v0
	v_med3_i32 v40, v44, v43, v0
	v_med3_i32 v41, v45, v44, v0
	v_med3_i32 v42, v46, v45, v0
	v_med3_i32 v43, v47, v46, v0
	v_med3_i32 v44, v73, v47, v0
	v_med3_i32 v45, v74, v73, v0
	v_med3_i32 v46, v76, v74, v0
	v_med3_i32 v47, v77, v76, v0
	v_max_i32_e32 v0, v77, v0
	v_ashrrev_i32_e32 v35, 31, v3
	v_med3_i32 v32, v33, v32, v1
	v_med3_i32 v33, v34, v33, v1
	v_med3_i32 v34, v36, v34, v1
	v_med3_i32 v36, v37, v36, v1
	v_med3_i32 v37, v38, v37, v1
	v_med3_i32 v38, v39, v38, v1
	v_med3_i32 v39, v40, v39, v1
	v_med3_i32 v40, v41, v40, v1
	v_med3_i32 v41, v42, v41, v1
	v_med3_i32 v42, v43, v42, v1
	v_med3_i32 v43, v44, v43, v1
	v_med3_i32 v44, v45, v44, v1
	v_med3_i32 v45, v46, v45, v1
	v_med3_i32 v46, v47, v46, v1
	v_med3_i32 v47, v0, v47, v1
	v_max_i32_e32 v0, v0, v1
	v_and_b32_e32 v35, 0x7fffff80, v35
	v_med3_i32 v1, v33, v32, v2
	v_med3_i32 v32, v34, v33, v2
	v_med3_i32 v33, v36, v34, v2
	v_med3_i32 v34, v37, v36, v2
	v_med3_i32 v36, v38, v37, v2
	v_med3_i32 v37, v39, v38, v2
	v_med3_i32 v38, v40, v39, v2
	v_med3_i32 v39, v41, v40, v2
	v_med3_i32 v40, v42, v41, v2
	v_med3_i32 v41, v43, v42, v2
	v_med3_i32 v42, v44, v43, v2
	v_med3_i32 v43, v45, v44, v2
	v_med3_i32 v44, v46, v45, v2
	v_med3_i32 v45, v47, v46, v2
	v_med3_i32 v46, v0, v47, v2
	v_max_i32_e32 v0, v0, v2
	v_and_b32_e32 v2, 0xffffff80, v3
	v_bitop3_b32 v2, v35, 35, v2 bitop3:0xde
	v_med3_i32 v3, v32, v1, v2
	v_med3_i32 v32, v33, v32, v2
	v_med3_i32 v33, v34, v33, v2
	v_med3_i32 v34, v36, v34, v2
	v_med3_i32 v35, v37, v36, v2
	v_med3_i32 v36, v38, v37, v2
	v_med3_i32 v37, v39, v38, v2
	v_med3_i32 v38, v40, v39, v2
	v_med3_i32 v39, v41, v40, v2
	v_med3_i32 v40, v42, v41, v2
	v_med3_i32 v41, v43, v42, v2
	v_med3_i32 v42, v44, v43, v2
	v_med3_i32 v43, v45, v44, v2
	v_med3_i32 v44, v46, v45, v2
	v_med3_i32 v45, v0, v46, v2
	v_max_i32_e32 v2, v0, v2
	v_pk_mul_f32 v[0:1], v[4:5], s[26:27] op_sel_hi:[1,0]
	s_nop 0
	v_ashrrev_i32_e32 v4, 31, v0
	v_and_b32_e32 v4, 0x7fffff80, v4
	v_and_b32_e32 v0, 0xffffff80, v0
	v_bitop3_b32 v0, v4, 40, v0 bitop3:0xde
	v_med3_i32 v3, v32, v3, v0
	v_med3_i32 v4, v33, v32, v0
	v_med3_i32 v5, v34, v33, v0
	v_med3_i32 v32, v35, v34, v0
	v_med3_i32 v33, v36, v35, v0
	v_med3_i32 v34, v37, v36, v0
	v_med3_i32 v35, v38, v37, v0
	v_med3_i32 v36, v39, v38, v0
	v_med3_i32 v37, v40, v39, v0
	v_med3_i32 v38, v41, v40, v0
	v_med3_i32 v39, v42, v41, v0
	v_med3_i32 v40, v43, v42, v0
; DI int med3i(int a, int b, int c) { int r; asm("v_med3_i32 %0, %1, %2, %3" : "=v"(r) : "v"(a), "v"(b), "v"(c)); return r; }
; DI void insert16(int (&L)[16], int x) {
; #pragma unroll
;   for (int j = 15; j >= 1; --j) L[j] = med3i(L[j - 1], L[j], x);
;   L[0] = max(L[0], x);
; }
; DI int f2sort(float f) { int b = __float_as_int(f); return b ^ ((b >> 31) & 0x7fffffff); }
; DI void p5a_half(const bf16x8 (&qf)[8], const u16* __restrict__ pk, float rs, int (&Lh)[16], u16* smem, int tid, int r, int h) {
;     ...
; #pragma unroll
;     for (int i = 0; i < 16; ++i) {
;       const int keyc = kt * 32 + (i & 3) + 8 * (i >> 2);
;       int sb = (f2sort(Y[i] * rs) & ~127) | keyc;
;       insert16(Lh, sb);
;     }
;     __builtin_amdgcn_sched_barrier(0);
	v_med3_i32 v41, v44, v43, v0
	v_med3_i32 v42, v45, v44, v0
	v_med3_i32 v43, v2, v45, v0
	v_max_i32_e32 v0, v2, v0
	v_ashrrev_i32_e32 v2, 31, v1
	v_and_b32_e32 v2, 0x7fffff80, v2
	v_and_b32_e32 v1, 0xffffff80, v1
	v_bitop3_b32 v1, v2, 41, v1 bitop3:0xde
	v_med3_i32 v2, v4, v3, v1
	v_med3_i32 v3, v5, v4, v1
	v_med3_i32 v4, v32, v5, v1
	v_med3_i32 v5, v33, v32, v1
	v_med3_i32 v32, v34, v33, v1
	v_med3_i32 v33, v35, v34, v1
	v_med3_i32 v34, v36, v35, v1
	v_med3_i32 v35, v37, v36, v1
	v_med3_i32 v36, v38, v37, v1
	v_med3_i32 v37, v39, v38, v1
	v_med3_i32 v38, v40, v39, v1
	v_med3_i32 v39, v41, v40, v1
	v_med3_i32 v40, v42, v41, v1
	v_med3_i32 v41, v43, v42, v1
	v_med3_i32 v42, v0, v43, v1
	v_max_i32_e32 v43, v0, v1
	v_pk_mul_f32 v[0:1], v[6:7], s[26:27] op_sel_hi:[1,0]
	s_nop 0
	v_ashrrev_i32_e32 v6, 31, v0
	v_and_b32_e32 v6, 0x7fffff80, v6
	v_and_b32_e32 v0, 0xffffff80, v0
	v_bitop3_b32 v0, v6, 42, v0 bitop3:0xde
	v_med3_i32 v2, v3, v2, v0
	v_med3_i32 v3, v4, v3, v0
	v_med3_i32 v4, v5, v4, v0
	v_med3_i32 v5, v32, v5, v0
	v_med3_i32 v6, v33, v32, v0
	v_med3_i32 v7, v34, v33, v0
	v_med3_i32 v32, v35, v34, v0
	v_med3_i32 v33, v36, v35, v0
	v_med3_i32 v34, v37, v36, v0
	v_med3_i32 v35, v38, v37, v0
	v_med3_i32 v36, v39, v38, v0
	v_med3_i32 v37, v40, v39, v0
	v_med3_i32 v38, v41, v40, v0
	v_med3_i32 v39, v42, v41, v0
	v_ashrrev_i32_e32 v41, 31, v1
	v_and_b32_e32 v41, 0x7fffff80, v41
	v_and_b32_e32 v1, 0xffffff80, v1
	v_med3_i32 v40, v43, v42, v0
	v_max_i32_e32 v0, v43, v0
	v_bitop3_b32 v1, v41, 43, v1 bitop3:0xde
	v_med3_i32 v2, v3, v2, v1
	v_med3_i32 v3, v4, v3, v1
	v_med3_i32 v4, v5, v4, v1
	v_med3_i32 v5, v6, v5, v1
	v_med3_i32 v6, v7, v6, v1
	v_med3_i32 v7, v32, v7, v1
	v_med3_i32 v32, v33, v32, v1
	v_med3_i32 v33, v34, v33, v1
	v_med3_i32 v34, v35, v34, v1
	v_med3_i32 v35, v36, v35, v1
	v_med3_i32 v36, v37, v36, v1
	v_med3_i32 v37, v38, v37, v1
	v_med3_i32 v38, v39, v38, v1
	v_med3_i32 v39, v40, v39, v1
	v_med3_i32 v40, v0, v40, v1
	v_max_i32_e32 v41, v0, v1
	v_pk_mul_f32 v[0:1], v[8:9], s[26:27] op_sel_hi:[1,0]
	s_nop 0
	v_ashrrev_i32_e32 v8, 31, v0
	v_and_b32_e32 v8, 0x7fffff80, v8
	v_and_b32_e32 v0, 0xffffff80, v0
	v_bitop3_b32 v0, v8, 48, v0 bitop3:0xde
	v_med3_i32 v2, v3, v2, v0
	v_med3_i32 v3, v4, v3, v0
	v_med3_i32 v4, v5, v4, v0
	v_med3_i32 v5, v6, v5, v0
	v_med3_i32 v6, v7, v6, v0
	v_med3_i32 v7, v32, v7, v0
	v_med3_i32 v8, v33, v32, v0
	v_med3_i32 v9, v34, v33, v0
	v_med3_i32 v32, v35, v34, v0
	v_med3_i32 v33, v36, v35, v0
	v_med3_i32 v34, v37, v36, v0
	v_med3_i32 v35, v38, v37, v0
	v_med3_i32 v36, v39, v38, v0
	v_med3_i32 v37, v40, v39, v0
	v_ashrrev_i32_e32 v39, 31, v1
	v_and_b32_e32 v39, 0x7fffff80, v39
	v_and_b32_e32 v1, 0xffffff80, v1
	v_med3_i32 v38, v41, v40, v0
	v_max_i32_e32 v0, v41, v0
	v_bitop3_b32 v1, v39, 49, v1 bitop3:0xde
	v_med3_i32 v2, v3, v2, v1
	v_med3_i32 v3, v4, v3, v1
	v_med3_i32 v4, v5, v4, v1
	v_med3_i32 v5, v6, v5, v1
	v_med3_i32 v6, v7, v6, v1
	v_med3_i32 v7, v8, v7, v1
	v_med3_i32 v8, v9, v8, v1
	v_med3_i32 v9, v32, v9, v1
	v_med3_i32 v32, v33, v32, v1
	v_med3_i32 v33, v34, v33, v1
	v_med3_i32 v34, v35, v34, v1
	v_med3_i32 v35, v36, v35, v1
	v_med3_i32 v36, v37, v36, v1
	v_med3_i32 v37, v38, v37, v1
	v_med3_i32 v38, v0, v38, v1
	v_max_i32_e32 v39, v0, v1
	v_pk_mul_f32 v[0:1], v[10:11], s[26:27] op_sel_hi:[1,0]
	s_nop 0
	v_ashrrev_i32_e32 v10, 31, v0
	v_and_b32_e32 v10, 0x7fffff80, v10
	v_and_b32_e32 v0, 0xffffff80, v0
	v_bitop3_b32 v0, v10, 50, v0 bitop3:0xde
	v_med3_i32 v2, v3, v2, v0
	v_med3_i32 v3, v4, v3, v0
	v_med3_i32 v4, v5, v4, v0
	v_med3_i32 v5, v6, v5, v0
	v_med3_i32 v6, v7, v6, v0
	v_med3_i32 v7, v8, v7, v0
	v_med3_i32 v8, v9, v8, v0
	v_med3_i32 v9, v32, v9, v0
	v_med3_i32 v10, v33, v32, v0
	v_med3_i32 v11, v34, v33, v0
	v_med3_i32 v32, v35, v34, v0
	v_med3_i32 v33, v36, v35, v0
	v_med3_i32 v34, v37, v36, v0
	v_med3_i32 v35, v38, v37, v0
	v_ashrrev_i32_e32 v37, 31, v1
	v_and_b32_e32 v37, 0x7fffff80, v37
	v_and_b32_e32 v1, 0xffffff80, v1
	v_med3_i32 v36, v39, v38, v0
	v_max_i32_e32 v0, v39, v0
	v_bitop3_b32 v1, v37, 51, v1 bitop3:0xde
	v_med3_i32 v2, v3, v2, v1
	v_med3_i32 v3, v4, v3, v1
	v_med3_i32 v4, v5, v4, v1
	v_med3_i32 v5, v6, v5, v1
	v_med3_i32 v6, v7, v6, v1
	v_med3_i32 v7, v8, v7, v1
	v_med3_i32 v8, v9, v8, v1
	v_med3_i32 v9, v10, v9, v1
	v_med3_i32 v10, v11, v10, v1
	v_med3_i32 v11, v32, v11, v1
	v_med3_i32 v32, v33, v32, v1
	v_med3_i32 v33, v34, v33, v1
	v_med3_i32 v34, v35, v34, v1
	v_med3_i32 v35, v36, v35, v1
	v_med3_i32 v36, v0, v36, v1
	v_max_i32_e32 v37, v0, v1
	v_pk_mul_f32 v[0:1], v[12:13], s[26:27] op_sel_hi:[1,0]
	s_nop 0
	v_ashrrev_i32_e32 v12, 31, v0
	v_and_b32_e32 v12, 0x7fffff80, v12
	v_and_b32_e32 v0, 0xffffff80, v0
	v_bitop3_b32 v0, v12, 56, v0 bitop3:0xde
	v_med3_i32 v2, v3, v2, v0
	v_med3_i32 v3, v4, v3, v0
	v_med3_i32 v4, v5, v4, v0
	v_med3_i32 v5, v6, v5, v0
	v_med3_i32 v6, v7, v6, v0
	v_med3_i32 v7, v8, v7, v0
	v_med3_i32 v8, v9, v8, v0
	v_med3_i32 v9, v10, v9, v0
	v_med3_i32 v10, v11, v10, v0
	v_med3_i32 v11, v32, v11, v0
	v_med3_i32 v12, v33, v32, v0
	v_med3_i32 v13, v34, v33, v0
	v_med3_i32 v32, v35, v34, v0
	v_med3_i32 v33, v36, v35, v0
	v_ashrrev_i32_e32 v35, 31, v1
	v_and_b32_e32 v35, 0x7fffff80, v35
	v_and_b32_e32 v1, 0xffffff80, v1
	v_med3_i32 v34, v37, v36, v0
	v_max_i32_e32 v0, v37, v0
	v_bitop3_b32 v1, v35, 57, v1 bitop3:0xde
	v_med3_i32 v2, v3, v2, v1
	v_med3_i32 v3, v4, v3, v1
	v_med3_i32 v4, v5, v4, v1
	v_med3_i32 v5, v6, v5, v1
	v_med3_i32 v6, v7, v6, v1
	v_med3_i32 v7, v8, v7, v1
	v_med3_i32 v8, v9, v8, v1
	v_med3_i32 v9, v10, v9, v1
	v_med3_i32 v10, v11, v10, v1
	v_med3_i32 v11, v12, v11, v1
	v_med3_i32 v12, v13, v12, v1
	v_med3_i32 v13, v32, v13, v1
; #define MFMA32(a, b, c) __builtin_amdgcn_mfma_f32_32x32x16_bf16((a), (b), (c), 0, 0, 0)
; DI int med3i(int a, int b, int c) { int r; asm("v_med3_i32 %0, %1, %2, %3" : "=v"(r) : "v"(a), "v"(b), "v"(c)); return r; }
; DI void insert16(int (&L)[16], int x) {
; #pragma unroll
;   for (int j = 15; j >= 1; --j) L[j] = med3i(L[j - 1], L[j], x);
;   L[0] = max(L[0], x);
; }
; DI int f2sort(float f) { int b = __float_as_int(f); return b ^ ((b >> 31) & 0x7fffffff); }
; DI void p5a_half(const bf16x8 (&qf)[8], const u16* __restrict__ pk, float rs, int (&Lh)[16], u16* smem, int tid, int r, int h) {
;     ...
;   for (int kt = 0; kt < 4; ++kt) {
;     f32x16 Y = zero16();
; #pragma unroll
;     for (int ks = 0; ks < 8; ++ks) {
;       const int m = ks >> 1, s = ks & 1;
;       const u16* pp = smem + (kt * 32 + r) * LPK + 32 * m + 16 * s + 4 * h;
;       s16x4 lo = *(const s16x4*)pp;
;       s16x4 hi = *(const s16x4*)(pp + 8);
;       bf16x8 a = __builtin_shufflevector(lo, hi, 0, 1, 2, 3, 4, 5, 6, 7);
;       Y = MFMA32(a, qf[ks], Y);
;     }
; #pragma unroll
;     for (int i = 0; i < 16; ++i) {
;       const int keyc = kt * 32 + (i & 3) + 8 * (i >> 2);
;       int sb = (f2sort(Y[i] * rs) & ~127) | keyc;
;       insert16(Lh, sb);
;     }
;     __builtin_amdgcn_sched_barrier(0);
	v_med3_i32 v32, v33, v32, v1
	v_med3_i32 v33, v34, v33, v1
	v_med3_i32 v34, v0, v34, v1
	v_max_i32_e32 v35, v0, v1
	v_pk_mul_f32 v[0:1], v[14:15], s[26:27] op_sel_hi:[1,0]
	s_nop 0
	v_ashrrev_i32_e32 v14, 31, v0
	v_and_b32_e32 v14, 0x7fffff80, v14
	v_and_b32_e32 v0, 0xffffff80, v0
	v_bitop3_b32 v0, v14, 58, v0 bitop3:0xde
	v_med3_i32 v14, v33, v32, v0
	v_med3_i32 v15, v34, v33, v0
	v_ashrrev_i32_e32 v33, 31, v1
	v_and_b32_e32 v33, 0x7fffff80, v33
	v_and_b32_e32 v1, 0xffffff80, v1
	v_med3_i32 v2, v3, v2, v0
	v_med3_i32 v3, v4, v3, v0
	v_med3_i32 v4, v5, v4, v0
	v_med3_i32 v5, v6, v5, v0
	v_med3_i32 v6, v7, v6, v0
	v_med3_i32 v7, v8, v7, v0
	v_med3_i32 v8, v9, v8, v0
	v_med3_i32 v9, v10, v9, v0
	v_med3_i32 v10, v11, v10, v0
	v_med3_i32 v11, v12, v11, v0
	v_med3_i32 v12, v13, v12, v0
	v_med3_i32 v13, v32, v13, v0
	v_med3_i32 v32, v35, v34, v0
	v_max_i32_e32 v0, v35, v0
	v_bitop3_b32 v1, v33, 59, v1 bitop3:0xde
	v_med3_i32 v36, v3, v2, v1
	v_med3_i32 v37, v4, v3, v1
	v_med3_i32 v38, v5, v4, v1
	v_med3_i32 v39, v6, v5, v1
	v_med3_i32 v40, v7, v6, v1
	v_med3_i32 v41, v8, v7, v1
	v_med3_i32 v42, v9, v8, v1
	v_med3_i32 v43, v10, v9, v1
	v_med3_i32 v44, v11, v10, v1
	v_med3_i32 v45, v12, v11, v1
	v_med3_i32 v46, v13, v12, v1
	v_med3_i32 v47, v14, v13, v1
	v_med3_i32 v74, v15, v14, v1
	v_med3_i32 v76, v32, v15, v1
	v_med3_i32 v77, v0, v32, v1
	v_max_i32_e32 v78, v0, v1
	v_add_u32_e32 v73, 0x4000, v156
	ds_read2_b64 v[0:3], v73 offset0:64 offset1:66
	ds_read2_b64 v[32:35], v73 offset0:68 offset1:70
	s_waitcnt lgkmcnt(1)
	v_mfma_f32_32x32x16_bf16 v[0:15], v[0:3], v[128:131], 0
	s_waitcnt lgkmcnt(0)
	v_mfma_f32_32x32x16_bf16 v[0:15], v[32:35], v[88:91], v[0:15]
	ds_read2_b64 v[32:35], v73 offset0:72 offset1:74
	s_waitcnt lgkmcnt(0)
	v_mfma_f32_32x32x16_bf16 v[0:15], v[32:35], v[92:95], v[0:15]
	ds_read2_b64 v[32:35], v73 offset0:76 offset1:78
	s_waitcnt lgkmcnt(0)
	v_mfma_f32_32x32x16_bf16 v[0:15], v[32:35], v[56:59], v[0:15]
	ds_read2_b64 v[32:35], v73 offset0:80 offset1:82
	s_waitcnt lgkmcnt(0)
	v_mfma_f32_32x32x16_bf16 v[0:15], v[32:35], v[96:99], v[0:15]
	ds_read2_b64 v[32:35], v73 offset0:84 offset1:86
	s_waitcnt lgkmcnt(0)
	v_mfma_f32_32x32x16_bf16 v[0:15], v[32:35], v[60:63], v[0:15]
	ds_read2_b64 v[32:35], v73 offset0:88 offset1:90
	s_waitcnt lgkmcnt(0)
	v_mfma_f32_32x32x16_bf16 v[0:15], v[32:35], v[68:71], v[0:15]
	ds_read2_b64 v[32:35], v73 offset0:92 offset1:94
	s_waitcnt lgkmcnt(0)
	v_mfma_f32_32x32x16_bf16 v[0:15], v[32:35], v[64:67], v[0:15]
	s_nop 11
	v_pk_mul_f32 v[0:1], v[0:1], s[26:27] op_sel_hi:[1,0]
	v_pk_mul_f32 v[2:3], v[2:3], s[26:27] op_sel_hi:[1,0]
	v_ashrrev_i32_e32 v32, 31, v0
	v_and_b32_e32 v0, 0xffffff80, v0
	v_ashrrev_i32_e32 v33, 31, v1
	v_ashrrev_i32_e32 v34, 31, v2
	v_and_b32_e32 v32, 0x7fffff80, v32
	v_and_b32_e32 v1, 0xffffff80, v1
	v_and_b32_e32 v2, 0xffffff80, v2
	v_and_b32_e32 v33, 0x7fffff80, v33
	v_and_b32_e32 v34, 0x7fffff80, v34
	v_bitop3_b32 v0, v32, 64, v0 bitop3:0xde
	v_bitop3_b32 v1, v33, s38, v1 bitop3:0xde
	v_bitop3_b32 v2, v34, s39, v2 bitop3:0xde
	v_med3_i32 v32, v37, v36, v0
	v_med3_i32 v33, v38, v37, v0
	v_med3_i32 v34, v39, v38, v0
	v_med3_i32 v36, v40, v39, v0
	v_med3_i32 v37, v41, v40, v0
	v_med3_i32 v38, v42, v41, v0
	v_med3_i32 v39, v43, v42, v0
	v_med3_i32 v40, v44, v43, v0
	v_med3_i32 v41, v45, v44, v0
	v_med3_i32 v42, v46, v45, v0
	v_med3_i32 v43, v47, v46, v0
	v_med3_i32 v44, v74, v47, v0
	v_med3_i32 v45, v76, v74, v0
	v_med3_i32 v46, v77, v76, v0
	v_med3_i32 v47, v78, v77, v0
	v_max_i32_e32 v0, v78, v0
	v_ashrrev_i32_e32 v35, 31, v3
	v_med3_i32 v32, v33, v32, v1
	v_med3_i32 v33, v34, v33, v1
	v_med3_i32 v34, v36, v34, v1
	v_med3_i32 v36, v37, v36, v1
	v_med3_i32 v37, v38, v37, v1
	v_med3_i32 v38, v39, v38, v1
	v_med3_i32 v39, v40, v39, v1
	v_med3_i32 v40, v41, v40, v1
	v_med3_i32 v41, v42, v41, v1
	v_med3_i32 v42, v43, v42, v1
	v_med3_i32 v43, v44, v43, v1
	v_med3_i32 v44, v45, v44, v1
	v_med3_i32 v45, v46, v45, v1
	v_med3_i32 v46, v47, v46, v1
	v_med3_i32 v47, v0, v47, v1
	v_max_i32_e32 v0, v0, v1
	v_and_b32_e32 v35, 0x7fffff80, v35
	v_med3_i32 v1, v33, v32, v2
	v_med3_i32 v32, v34, v33, v2
	v_med3_i32 v33, v36, v34, v2
	v_med3_i32 v34, v37, v36, v2
	v_med3_i32 v36, v38, v37, v2
	v_med3_i32 v37, v39, v38, v2
	v_med3_i32 v38, v40, v39, v2
	v_med3_i32 v39, v41, v40, v2
	v_med3_i32 v40, v42, v41, v2
	v_med3_i32 v41, v43, v42, v2
	v_med3_i32 v42, v44, v43, v2
	v_med3_i32 v43, v45, v44, v2
	v_med3_i32 v44, v46, v45, v2
	v_med3_i32 v45, v47, v46, v2
	v_med3_i32 v46, v0, v47, v2
	v_max_i32_e32 v0, v0, v2
	v_and_b32_e32 v2, 0xffffff80, v3
	v_bitop3_b32 v2, v35, s40, v2 bitop3:0xde
	v_med3_i32 v3, v32, v1, v2
	v_med3_i32 v32, v33, v32, v2
	v_med3_i32 v33, v34, v33, v2
	v_med3_i32 v34, v36, v34, v2
	v_med3_i32 v35, v37, v36, v2
	v_med3_i32 v36, v38, v37, v2
	v_med3_i32 v37, v39, v38, v2
	v_med3_i32 v38, v40, v39, v2
	v_med3_i32 v39, v41, v40, v2
	v_med3_i32 v40, v42, v41, v2
	v_med3_i32 v41, v43, v42, v2
	v_med3_i32 v42, v44, v43, v2
	v_med3_i32 v43, v45, v44, v2
	v_med3_i32 v44, v46, v45, v2
	v_med3_i32 v45, v0, v46, v2
	v_max_i32_e32 v2, v0, v2
	v_pk_mul_f32 v[0:1], v[4:5], s[26:27] op_sel_hi:[1,0]
	s_nop 0
	v_ashrrev_i32_e32 v4, 31, v0
	v_and_b32_e32 v4, 0x7fffff80, v4
	v_and_b32_e32 v0, 0xffffff80, v0
	v_bitop3_b32 v0, v4, s41, v0 bitop3:0xde
	v_med3_i32 v3, v32, v3, v0
	v_med3_i32 v4, v33, v32, v0
	v_med3_i32 v5, v34, v33, v0
	v_med3_i32 v32, v35, v34, v0
	v_med3_i32 v33, v36, v35, v0
	v_med3_i32 v34, v37, v36, v0
	v_med3_i32 v35, v38, v37, v0
	v_med3_i32 v36, v39, v38, v0
	v_med3_i32 v37, v40, v39, v0
	v_med3_i32 v38, v41, v40, v0
	v_med3_i32 v39, v42, v41, v0
	v_med3_i32 v40, v43, v42, v0
; DI int med3i(int a, int b, int c) { int r; asm("v_med3_i32 %0, %1, %2, %3" : "=v"(r) : "v"(a), "v"(b), "v"(c)); return r; }
; DI void insert16(int (&L)[16], int x) {
; #pragma unroll
;   for (int j = 15; j >= 1; --j) L[j] = med3i(L[j - 1], L[j], x);
;   L[0] = max(L[0], x);
; }
; DI int f2sort(float f) { int b = __float_as_int(f); return b ^ ((b >> 31) & 0x7fffffff); }
; DI void p5a_half(const bf16x8 (&qf)[8], const u16* __restrict__ pk, float rs, int (&Lh)[16], u16* smem, int tid, int r, int h) {
;     ...
; #pragma unroll
;     for (int i = 0; i < 16; ++i) {
;       const int keyc = kt * 32 + (i & 3) + 8 * (i >> 2);
;       int sb = (f2sort(Y[i] * rs) & ~127) | keyc;
;       insert16(Lh, sb);
;     }
;     __builtin_amdgcn_sched_barrier(0);
	v_med3_i32 v41, v44, v43, v0
	v_med3_i32 v42, v45, v44, v0
	v_med3_i32 v43, v2, v45, v0
	v_max_i32_e32 v0, v2, v0
	v_ashrrev_i32_e32 v2, 31, v1
	v_and_b32_e32 v2, 0x7fffff80, v2
	v_and_b32_e32 v1, 0xffffff80, v1
	v_bitop3_b32 v1, v2, s42, v1 bitop3:0xde
	v_med3_i32 v2, v4, v3, v1
	v_med3_i32 v3, v5, v4, v1
	v_med3_i32 v4, v32, v5, v1
	v_med3_i32 v5, v33, v32, v1
	v_med3_i32 v32, v34, v33, v1
	v_med3_i32 v33, v35, v34, v1
	v_med3_i32 v34, v36, v35, v1
	v_med3_i32 v35, v37, v36, v1
	v_med3_i32 v36, v38, v37, v1
	v_med3_i32 v37, v39, v38, v1
	v_med3_i32 v38, v40, v39, v1
	v_med3_i32 v39, v41, v40, v1
	v_med3_i32 v40, v42, v41, v1
	v_med3_i32 v41, v43, v42, v1
	v_med3_i32 v42, v0, v43, v1
	v_max_i32_e32 v43, v0, v1
	v_pk_mul_f32 v[0:1], v[6:7], s[26:27] op_sel_hi:[1,0]
	s_nop 0
	v_ashrrev_i32_e32 v6, 31, v0
	v_and_b32_e32 v6, 0x7fffff80, v6
	v_and_b32_e32 v0, 0xffffff80, v0
	v_bitop3_b32 v0, v6, s43, v0 bitop3:0xde
	v_med3_i32 v2, v3, v2, v0
	v_med3_i32 v3, v4, v3, v0
	v_med3_i32 v4, v5, v4, v0
	v_med3_i32 v5, v32, v5, v0
	v_med3_i32 v6, v33, v32, v0
	v_med3_i32 v7, v34, v33, v0
	v_med3_i32 v32, v35, v34, v0
	v_med3_i32 v33, v36, v35, v0
	v_med3_i32 v34, v37, v36, v0
	v_med3_i32 v35, v38, v37, v0
	v_med3_i32 v36, v39, v38, v0
	v_med3_i32 v37, v40, v39, v0
	v_med3_i32 v38, v41, v40, v0
	v_med3_i32 v39, v42, v41, v0
	v_ashrrev_i32_e32 v41, 31, v1
	v_and_b32_e32 v41, 0x7fffff80, v41
	v_and_b32_e32 v1, 0xffffff80, v1
	v_med3_i32 v40, v43, v42, v0
	v_max_i32_e32 v0, v43, v0
	v_bitop3_b32 v1, v41, s44, v1 bitop3:0xde
	v_med3_i32 v2, v3, v2, v1
	v_med3_i32 v3, v4, v3, v1
	v_med3_i32 v4, v5, v4, v1
	v_med3_i32 v5, v6, v5, v1
	v_med3_i32 v6, v7, v6, v1
	v_med3_i32 v7, v32, v7, v1
	v_med3_i32 v32, v33, v32, v1
	v_med3_i32 v33, v34, v33, v1
	v_med3_i32 v34, v35, v34, v1
	v_med3_i32 v35, v36, v35, v1
	v_med3_i32 v36, v37, v36, v1
	v_med3_i32 v37, v38, v37, v1
	v_med3_i32 v38, v39, v38, v1
	v_med3_i32 v39, v40, v39, v1
	v_med3_i32 v40, v0, v40, v1
	v_max_i32_e32 v41, v0, v1
	v_pk_mul_f32 v[0:1], v[8:9], s[26:27] op_sel_hi:[1,0]
	s_nop 0
	v_ashrrev_i32_e32 v8, 31, v0
	v_and_b32_e32 v8, 0x7fffff80, v8
	v_and_b32_e32 v0, 0xffffff80, v0
	v_bitop3_b32 v0, v8, s45, v0 bitop3:0xde
	v_med3_i32 v2, v3, v2, v0
	v_med3_i32 v3, v4, v3, v0
	v_med3_i32 v4, v5, v4, v0
	v_med3_i32 v5, v6, v5, v0
	v_med3_i32 v6, v7, v6, v0
	v_med3_i32 v7, v32, v7, v0
	v_med3_i32 v8, v33, v32, v0
	v_med3_i32 v9, v34, v33, v0
	v_med3_i32 v32, v35, v34, v0
	v_med3_i32 v33, v36, v35, v0
	v_med3_i32 v34, v37, v36, v0
	v_med3_i32 v35, v38, v37, v0
	v_med3_i32 v36, v39, v38, v0
	v_med3_i32 v37, v40, v39, v0
	v_ashrrev_i32_e32 v39, 31, v1
	v_and_b32_e32 v39, 0x7fffff80, v39
	v_and_b32_e32 v1, 0xffffff80, v1
	v_med3_i32 v38, v41, v40, v0
	v_max_i32_e32 v0, v41, v0
	v_bitop3_b32 v1, v39, s46, v1 bitop3:0xde
	v_med3_i32 v2, v3, v2, v1
	v_med3_i32 v3, v4, v3, v1
	v_med3_i32 v4, v5, v4, v1
	v_med3_i32 v5, v6, v5, v1
	v_med3_i32 v6, v7, v6, v1
	v_med3_i32 v7, v8, v7, v1
	v_med3_i32 v8, v9, v8, v1
	v_med3_i32 v9, v32, v9, v1
	v_med3_i32 v32, v33, v32, v1
	v_med3_i32 v33, v34, v33, v1
	v_med3_i32 v34, v35, v34, v1
	v_med3_i32 v35, v36, v35, v1
	v_med3_i32 v36, v37, v36, v1
	v_med3_i32 v37, v38, v37, v1
	v_med3_i32 v38, v0, v38, v1
	v_max_i32_e32 v39, v0, v1
	v_pk_mul_f32 v[0:1], v[10:11], s[26:27] op_sel_hi:[1,0]
	s_nop 0
	v_ashrrev_i32_e32 v10, 31, v0
	v_and_b32_e32 v10, 0x7fffff80, v10
	v_and_b32_e32 v0, 0xffffff80, v0
	v_bitop3_b32 v0, v10, s47, v0 bitop3:0xde
	v_med3_i32 v2, v3, v2, v0
	v_med3_i32 v3, v4, v3, v0
	v_med3_i32 v4, v5, v4, v0
	v_med3_i32 v5, v6, v5, v0
	v_med3_i32 v6, v7, v6, v0
	v_med3_i32 v7, v8, v7, v0
	v_med3_i32 v8, v9, v8, v0
	v_med3_i32 v9, v32, v9, v0
	v_med3_i32 v10, v33, v32, v0
	v_med3_i32 v11, v34, v33, v0
	v_med3_i32 v32, v35, v34, v0
	v_med3_i32 v33, v36, v35, v0
	v_med3_i32 v34, v37, v36, v0
	v_med3_i32 v35, v38, v37, v0
	v_ashrrev_i32_e32 v37, 31, v1
	v_and_b32_e32 v37, 0x7fffff80, v37
	v_and_b32_e32 v1, 0xffffff80, v1
	v_med3_i32 v36, v39, v38, v0
	v_max_i32_e32 v0, v39, v0
	v_bitop3_b32 v1, v37, s48, v1 bitop3:0xde
	v_med3_i32 v2, v3, v2, v1
	v_med3_i32 v3, v4, v3, v1
	v_med3_i32 v4, v5, v4, v1
	v_med3_i32 v5, v6, v5, v1
	v_med3_i32 v6, v7, v6, v1
	v_med3_i32 v7, v8, v7, v1
	v_med3_i32 v8, v9, v8, v1
	v_med3_i32 v9, v10, v9, v1
	v_med3_i32 v10, v11, v10, v1
	v_med3_i32 v11, v32, v11, v1
	v_med3_i32 v32, v33, v32, v1
	v_med3_i32 v33, v34, v33, v1
	v_med3_i32 v34, v35, v34, v1
	v_med3_i32 v35, v36, v35, v1
	v_med3_i32 v36, v0, v36, v1
	v_max_i32_e32 v37, v0, v1
	v_pk_mul_f32 v[0:1], v[12:13], s[26:27] op_sel_hi:[1,0]
	s_nop 0
	v_ashrrev_i32_e32 v12, 31, v0
	v_and_b32_e32 v12, 0x7fffff80, v12
	v_and_b32_e32 v0, 0xffffff80, v0
	v_bitop3_b32 v0, v12, s49, v0 bitop3:0xde
	v_med3_i32 v2, v3, v2, v0
	v_med3_i32 v3, v4, v3, v0
	v_med3_i32 v4, v5, v4, v0
	v_med3_i32 v5, v6, v5, v0
	v_med3_i32 v6, v7, v6, v0
	v_med3_i32 v7, v8, v7, v0
	v_med3_i32 v8, v9, v8, v0
	v_med3_i32 v9, v10, v9, v0
	v_med3_i32 v10, v11, v10, v0
	v_med3_i32 v11, v32, v11, v0
	v_med3_i32 v12, v33, v32, v0
	v_med3_i32 v13, v34, v33, v0
	v_med3_i32 v32, v35, v34, v0
	v_med3_i32 v33, v36, v35, v0
	v_ashrrev_i32_e32 v35, 31, v1
	v_and_b32_e32 v35, 0x7fffff80, v35
	v_and_b32_e32 v1, 0xffffff80, v1
	v_med3_i32 v34, v37, v36, v0
	v_max_i32_e32 v0, v37, v0
	v_bitop3_b32 v1, v35, s50, v1 bitop3:0xde
	v_med3_i32 v2, v3, v2, v1
	v_med3_i32 v3, v4, v3, v1
	v_med3_i32 v4, v5, v4, v1
	v_med3_i32 v5, v6, v5, v1
	v_med3_i32 v6, v7, v6, v1
	v_med3_i32 v7, v8, v7, v1
	v_med3_i32 v8, v9, v8, v1
	v_med3_i32 v9, v10, v9, v1
	v_med3_i32 v10, v11, v10, v1
	v_med3_i32 v11, v12, v11, v1
	v_med3_i32 v12, v13, v12, v1
; #define MFMA32(a, b, c) __builtin_amdgcn_mfma_f32_32x32x16_bf16((a), (b), (c), 0, 0, 0)
; DI int med3i(int a, int b, int c) { int r; asm("v_med3_i32 %0, %1, %2, %3" : "=v"(r) : "v"(a), "v"(b), "v"(c)); return r; }
; DI void insert16(int (&L)[16], int x) {
; #pragma unroll
;   for (int j = 15; j >= 1; --j) L[j] = med3i(L[j - 1], L[j], x);
;   L[0] = max(L[0], x);
; }
; DI int f2sort(float f) { int b = __float_as_int(f); return b ^ ((b >> 31) & 0x7fffffff); }
; DI void p5a_half(const bf16x8 (&qf)[8], const u16* __restrict__ pk, float rs, int (&Lh)[16], u16* smem, int tid, int r, int h) {
;     ...
;   for (int kt = 0; kt < 4; ++kt) {
;     f32x16 Y = zero16();
; #pragma unroll
;     for (int ks = 0; ks < 8; ++ks) {
;       const int m = ks >> 1, s = ks & 1;
;       const u16* pp = smem + (kt * 32 + r) * LPK + 32 * m + 16 * s + 4 * h;
;       s16x4 lo = *(const s16x4*)pp;
;       s16x4 hi = *(const s16x4*)(pp + 8);
;       bf16x8 a = __builtin_shufflevector(lo, hi, 0, 1, 2, 3, 4, 5, 6, 7);
;       Y = MFMA32(a, qf[ks], Y);
;     }
; #pragma unroll
;     for (int i = 0; i < 16; ++i) {
;       const int keyc = kt * 32 + (i & 3) + 8 * (i >> 2);
;       int sb = (f2sort(Y[i] * rs) & ~127) | keyc;
;       insert16(Lh, sb);
;     }
;     __builtin_amdgcn_sched_barrier(0);
	v_med3_i32 v13, v32, v13, v1
	v_med3_i32 v32, v33, v32, v1
	v_med3_i32 v33, v34, v33, v1
	v_med3_i32 v34, v0, v34, v1
	v_max_i32_e32 v35, v0, v1
	v_pk_mul_f32 v[0:1], v[14:15], s[26:27] op_sel_hi:[1,0]
	s_nop 0
	v_ashrrev_i32_e32 v14, 31, v0
	v_and_b32_e32 v14, 0x7fffff80, v14
	v_and_b32_e32 v0, 0xffffff80, v0
	v_bitop3_b32 v0, v14, s51, v0 bitop3:0xde
	v_med3_i32 v14, v33, v32, v0
	v_med3_i32 v15, v34, v33, v0
	v_ashrrev_i32_e32 v33, 31, v1
	v_and_b32_e32 v33, 0x7fffff80, v33
	v_and_b32_e32 v1, 0xffffff80, v1
	v_med3_i32 v2, v3, v2, v0
	v_med3_i32 v3, v4, v3, v0
	v_med3_i32 v4, v5, v4, v0
	v_med3_i32 v5, v6, v5, v0
	v_med3_i32 v6, v7, v6, v0
	v_med3_i32 v7, v8, v7, v0
	v_med3_i32 v8, v9, v8, v0
	v_med3_i32 v9, v10, v9, v0
	v_med3_i32 v10, v11, v10, v0
	v_med3_i32 v11, v12, v11, v0
	v_med3_i32 v12, v13, v12, v0
	v_med3_i32 v13, v32, v13, v0
	v_med3_i32 v32, v35, v34, v0
	v_max_i32_e32 v0, v35, v0
	v_bitop3_b32 v1, v33, s52, v1 bitop3:0xde
	v_med3_i32 v36, v3, v2, v1
	v_med3_i32 v37, v4, v3, v1
	v_med3_i32 v38, v5, v4, v1
	v_med3_i32 v39, v6, v5, v1
	v_med3_i32 v40, v7, v6, v1
	v_med3_i32 v41, v8, v7, v1
	v_med3_i32 v42, v9, v8, v1
	v_med3_i32 v43, v10, v9, v1
	v_med3_i32 v44, v11, v10, v1
	v_med3_i32 v45, v12, v11, v1
	v_med3_i32 v46, v13, v12, v1
	v_med3_i32 v47, v14, v13, v1
	v_med3_i32 v76, v15, v14, v1
	v_med3_i32 v77, v32, v15, v1
	v_med3_i32 v78, v0, v32, v1
	v_max_i32_e32 v79, v0, v1
	v_add_u32_e32 v74, 0x6000, v156
	ds_read2_b64 v[0:3], v74 offset0:96 offset1:98
	ds_read2_b64 v[32:35], v74 offset0:100 offset1:102
	s_waitcnt lgkmcnt(1)
	v_mfma_f32_32x32x16_bf16 v[0:15], v[0:3], v[128:131], 0
	s_waitcnt lgkmcnt(0)
	v_mfma_f32_32x32x16_bf16 v[0:15], v[32:35], v[88:91], v[0:15]
	ds_read2_b64 v[32:35], v74 offset0:104 offset1:106
	s_waitcnt lgkmcnt(0)
	v_mfma_f32_32x32x16_bf16 v[0:15], v[32:35], v[92:95], v[0:15]
	ds_read2_b64 v[32:35], v74 offset0:108 offset1:110
	s_waitcnt lgkmcnt(0)
	v_mfma_f32_32x32x16_bf16 v[0:15], v[32:35], v[56:59], v[0:15]
	ds_read2_b64 v[32:35], v74 offset0:112 offset1:114
	s_waitcnt lgkmcnt(0)
	v_mfma_f32_32x32x16_bf16 v[0:15], v[32:35], v[96:99], v[0:15]
	ds_read2_b64 v[32:35], v74 offset0:116 offset1:118
	s_waitcnt lgkmcnt(0)
	v_mfma_f32_32x32x16_bf16 v[0:15], v[32:35], v[60:63], v[0:15]
	ds_read2_b64 v[32:35], v74 offset0:120 offset1:122
	s_waitcnt lgkmcnt(0)
	v_mfma_f32_32x32x16_bf16 v[0:15], v[32:35], v[68:71], v[0:15]
	ds_read2_b64 v[32:35], v74 offset0:124 offset1:126
	s_waitcnt lgkmcnt(0)
	v_mfma_f32_32x32x16_bf16 v[0:15], v[32:35], v[64:67], v[0:15]
	s_nop 11
	v_pk_mul_f32 v[0:1], v[0:1], s[26:27] op_sel_hi:[1,0]
	v_pk_mul_f32 v[2:3], v[2:3], s[26:27] op_sel_hi:[1,0]
	v_ashrrev_i32_e32 v32, 31, v0
	v_and_b32_e32 v0, 0xffffff80, v0
	v_ashrrev_i32_e32 v33, 31, v1
	v_ashrrev_i32_e32 v34, 31, v2
	v_and_b32_e32 v32, 0x7fffff80, v32
	v_and_b32_e32 v1, 0xffffff80, v1
	v_and_b32_e32 v2, 0xffffff80, v2
	v_and_b32_e32 v33, 0x7fffff80, v33
	v_and_b32_e32 v34, 0x7fffff80, v34
	v_bitop3_b32 v0, v32, s53, v0 bitop3:0xde
	v_bitop3_b32 v1, v33, s56, v1 bitop3:0xde
	v_bitop3_b32 v2, v34, s57, v2 bitop3:0xde
	v_med3_i32 v32, v37, v36, v0
	v_med3_i32 v33, v38, v37, v0
	v_med3_i32 v34, v39, v38, v0
	v_med3_i32 v36, v40, v39, v0
	v_med3_i32 v37, v41, v40, v0
	v_med3_i32 v38, v42, v41, v0
	v_med3_i32 v39, v43, v42, v0
	v_med3_i32 v40, v44, v43, v0
	v_med3_i32 v41, v45, v44, v0
	v_med3_i32 v42, v46, v45, v0
	v_med3_i32 v43, v47, v46, v0
	v_med3_i32 v44, v76, v47, v0
	v_med3_i32 v45, v77, v76, v0
	v_med3_i32 v46, v78, v77, v0
	v_med3_i32 v47, v79, v78, v0
	v_max_i32_e32 v0, v79, v0
	v_ashrrev_i32_e32 v35, 31, v3
	v_med3_i32 v32, v33, v32, v1
	v_med3_i32 v33, v34, v33, v1
	v_med3_i32 v34, v36, v34, v1
	v_med3_i32 v36, v37, v36, v1
	v_med3_i32 v37, v38, v37, v1
	v_med3_i32 v38, v39, v38, v1
	v_med3_i32 v39, v40, v39, v1
	v_med3_i32 v40, v41, v40, v1
	v_med3_i32 v41, v42, v41, v1
	v_med3_i32 v42, v43, v42, v1
	v_med3_i32 v43, v44, v43, v1
	v_med3_i32 v44, v45, v44, v1
	v_med3_i32 v45, v46, v45, v1
	v_med3_i32 v46, v47, v46, v1
	v_med3_i32 v47, v0, v47, v1
	v_max_i32_e32 v0, v0, v1
	v_and_b32_e32 v35, 0x7fffff80, v35
	v_med3_i32 v1, v33, v32, v2
	v_med3_i32 v32, v34, v33, v2
	v_med3_i32 v33, v36, v34, v2
	v_med3_i32 v34, v37, v36, v2
	v_med3_i32 v36, v38, v37, v2
	v_med3_i32 v37, v39, v38, v2
	v_med3_i32 v38, v40, v39, v2
	v_med3_i32 v39, v41, v40, v2
	v_med3_i32 v40, v42, v41, v2
	v_med3_i32 v41, v43, v42, v2
	v_med3_i32 v42, v44, v43, v2
	v_med3_i32 v43, v45, v44, v2
	v_med3_i32 v44, v46, v45, v2
	v_med3_i32 v45, v47, v46, v2
	v_med3_i32 v46, v0, v47, v2
	v_max_i32_e32 v0, v0, v2
	v_and_b32_e32 v2, 0xffffff80, v3
	v_bitop3_b32 v2, v35, s58, v2 bitop3:0xde
	v_med3_i32 v3, v32, v1, v2
	v_med3_i32 v32, v33, v32, v2
	v_med3_i32 v33, v34, v33, v2
	v_med3_i32 v34, v36, v34, v2
	v_med3_i32 v35, v37, v36, v2
	v_med3_i32 v36, v38, v37, v2
	v_med3_i32 v37, v39, v38, v2
	v_med3_i32 v38, v40, v39, v2
	v_med3_i32 v39, v41, v40, v2
	v_med3_i32 v40, v42, v41, v2
	v_med3_i32 v41, v43, v42, v2
	v_med3_i32 v42, v44, v43, v2
	v_med3_i32 v43, v45, v44, v2
	v_med3_i32 v44, v46, v45, v2
	v_med3_i32 v45, v0, v46, v2
	v_max_i32_e32 v2, v0, v2
	v_pk_mul_f32 v[0:1], v[4:5], s[26:27] op_sel_hi:[1,0]
	s_nop 0
	v_ashrrev_i32_e32 v4, 31, v0
	v_and_b32_e32 v4, 0x7fffff80, v4
	v_and_b32_e32 v0, 0xffffff80, v0
	v_bitop3_b32 v0, v4, s59, v0 bitop3:0xde
	v_med3_i32 v3, v32, v3, v0
	v_med3_i32 v4, v33, v32, v0
	v_med3_i32 v5, v34, v33, v0
	v_med3_i32 v32, v35, v34, v0
	v_med3_i32 v33, v36, v35, v0
	v_med3_i32 v34, v37, v36, v0
	v_med3_i32 v35, v38, v37, v0
	v_med3_i32 v36, v39, v38, v0
	v_med3_i32 v37, v40, v39, v0
	v_med3_i32 v38, v41, v40, v0
; DI int med3i(int a, int b, int c) { int r; asm("v_med3_i32 %0, %1, %2, %3" : "=v"(r) : "v"(a), "v"(b), "v"(c)); return r; }
; DI void insert16(int (&L)[16], int x) {
; #pragma unroll
;   for (int j = 15; j >= 1; --j) L[j] = med3i(L[j - 1], L[j], x);
;   L[0] = max(L[0], x);
; }
; DI int f2sort(float f) { int b = __float_as_int(f); return b ^ ((b >> 31) & 0x7fffffff); }
; DI void p5a_half(const bf16x8 (&qf)[8], const u16* __restrict__ pk, float rs, int (&Lh)[16], u16* smem, int tid, int r, int h) {
;     ...
; #pragma unroll
;     for (int i = 0; i < 16; ++i) {
;       const int keyc = kt * 32 + (i & 3) + 8 * (i >> 2);
;       int sb = (f2sort(Y[i] * rs) & ~127) | keyc;
;       insert16(Lh, sb);
;     }
;     __builtin_amdgcn_sched_barrier(0);
	v_med3_i32 v39, v42, v41, v0
	v_med3_i32 v40, v43, v42, v0
	v_med3_i32 v41, v44, v43, v0
	v_med3_i32 v42, v45, v44, v0
	v_med3_i32 v43, v2, v45, v0
	v_max_i32_e32 v0, v2, v0
	v_ashrrev_i32_e32 v2, 31, v1
	v_and_b32_e32 v2, 0x7fffff80, v2
	v_and_b32_e32 v1, 0xffffff80, v1
	v_bitop3_b32 v1, v2, s60, v1 bitop3:0xde
	v_med3_i32 v2, v4, v3, v1
	v_med3_i32 v3, v5, v4, v1
	v_med3_i32 v4, v32, v5, v1
	v_med3_i32 v5, v33, v32, v1
	v_med3_i32 v32, v34, v33, v1
	v_med3_i32 v33, v35, v34, v1
	v_med3_i32 v34, v36, v35, v1
	v_med3_i32 v35, v37, v36, v1
	v_med3_i32 v36, v38, v37, v1
	v_med3_i32 v37, v39, v38, v1
	v_med3_i32 v38, v40, v39, v1
	v_med3_i32 v39, v41, v40, v1
	v_med3_i32 v40, v42, v41, v1
	v_med3_i32 v41, v43, v42, v1
	v_med3_i32 v42, v0, v43, v1
	v_max_i32_e32 v43, v0, v1
	v_pk_mul_f32 v[0:1], v[6:7], s[26:27] op_sel_hi:[1,0]
	s_nop 0
	v_ashrrev_i32_e32 v6, 31, v0
	v_and_b32_e32 v6, 0x7fffff80, v6
	v_and_b32_e32 v0, 0xffffff80, v0
	v_bitop3_b32 v0, v6, s61, v0 bitop3:0xde
	v_med3_i32 v2, v3, v2, v0
	v_med3_i32 v3, v4, v3, v0
	v_med3_i32 v4, v5, v4, v0
	v_med3_i32 v5, v32, v5, v0
	v_med3_i32 v6, v33, v32, v0
	v_med3_i32 v7, v34, v33, v0
	v_med3_i32 v32, v35, v34, v0
	v_med3_i32 v33, v36, v35, v0
	v_med3_i32 v34, v37, v36, v0
	v_med3_i32 v35, v38, v37, v0
	v_med3_i32 v36, v39, v38, v0
	v_med3_i32 v37, v40, v39, v0
	v_med3_i32 v38, v41, v40, v0
	v_med3_i32 v39, v42, v41, v0
	v_ashrrev_i32_e32 v41, 31, v1
	v_and_b32_e32 v41, 0x7fffff80, v41
	v_and_b32_e32 v1, 0xffffff80, v1
	v_med3_i32 v40, v43, v42, v0
	v_max_i32_e32 v0, v43, v0
	v_bitop3_b32 v1, v41, s62, v1 bitop3:0xde
	v_med3_i32 v2, v3, v2, v1
	v_med3_i32 v3, v4, v3, v1
	v_med3_i32 v4, v5, v4, v1
	v_med3_i32 v5, v6, v5, v1
	v_med3_i32 v6, v7, v6, v1
	v_med3_i32 v7, v32, v7, v1
	v_med3_i32 v32, v33, v32, v1
	v_med3_i32 v33, v34, v33, v1
	v_med3_i32 v34, v35, v34, v1
	v_med3_i32 v35, v36, v35, v1
	v_med3_i32 v36, v37, v36, v1
	v_med3_i32 v37, v38, v37, v1
	v_med3_i32 v38, v39, v38, v1
	v_med3_i32 v39, v40, v39, v1
	v_med3_i32 v40, v0, v40, v1
	v_max_i32_e32 v41, v0, v1
	v_pk_mul_f32 v[0:1], v[8:9], s[26:27] op_sel_hi:[1,0]
	s_nop 0
	v_ashrrev_i32_e32 v8, 31, v0
	v_and_b32_e32 v8, 0x7fffff80, v8
	v_and_b32_e32 v0, 0xffffff80, v0
	v_bitop3_b32 v0, v8, s63, v0 bitop3:0xde
	v_med3_i32 v2, v3, v2, v0
	v_med3_i32 v3, v4, v3, v0
	v_med3_i32 v4, v5, v4, v0
	v_med3_i32 v5, v6, v5, v0
	v_med3_i32 v6, v7, v6, v0
	v_med3_i32 v7, v32, v7, v0
	v_med3_i32 v8, v33, v32, v0
	v_med3_i32 v9, v34, v33, v0
	v_med3_i32 v32, v35, v34, v0
	v_med3_i32 v33, v36, v35, v0
	v_med3_i32 v34, v37, v36, v0
	v_med3_i32 v35, v38, v37, v0
	v_med3_i32 v36, v39, v38, v0
	v_med3_i32 v37, v40, v39, v0
	v_ashrrev_i32_e32 v39, 31, v1
	v_and_b32_e32 v39, 0x7fffff80, v39
	v_and_b32_e32 v1, 0xffffff80, v1
	v_med3_i32 v38, v41, v40, v0
	v_max_i32_e32 v0, v41, v0
	v_bitop3_b32 v1, v39, s64, v1 bitop3:0xde
	v_med3_i32 v2, v3, v2, v1
	v_med3_i32 v3, v4, v3, v1
	v_med3_i32 v4, v5, v4, v1
	v_med3_i32 v5, v6, v5, v1
	v_med3_i32 v6, v7, v6, v1
	v_med3_i32 v7, v8, v7, v1
	v_med3_i32 v8, v9, v8, v1
	v_med3_i32 v9, v32, v9, v1
	v_med3_i32 v32, v33, v32, v1
	v_med3_i32 v33, v34, v33, v1
	v_med3_i32 v34, v35, v34, v1
	v_med3_i32 v35, v36, v35, v1
	v_med3_i32 v36, v37, v36, v1
	v_med3_i32 v37, v38, v37, v1
	v_med3_i32 v38, v0, v38, v1
	v_max_i32_e32 v39, v0, v1
	v_pk_mul_f32 v[0:1], v[10:11], s[26:27] op_sel_hi:[1,0]
	s_nop 0
	v_ashrrev_i32_e32 v10, 31, v0
	v_and_b32_e32 v10, 0x7fffff80, v10
	v_and_b32_e32 v0, 0xffffff80, v0
	v_bitop3_b32 v0, v10, s65, v0 bitop3:0xde
	v_med3_i32 v2, v3, v2, v0
	v_med3_i32 v3, v4, v3, v0
	v_med3_i32 v4, v5, v4, v0
	v_med3_i32 v5, v6, v5, v0
	v_med3_i32 v6, v7, v6, v0
	v_med3_i32 v7, v8, v7, v0
	v_med3_i32 v8, v9, v8, v0
	v_med3_i32 v9, v32, v9, v0
	v_med3_i32 v10, v33, v32, v0
	v_med3_i32 v11, v34, v33, v0
	v_med3_i32 v32, v35, v34, v0
	v_med3_i32 v33, v36, v35, v0
	v_med3_i32 v34, v37, v36, v0
	v_med3_i32 v35, v38, v37, v0
	v_ashrrev_i32_e32 v37, 31, v1
	v_and_b32_e32 v37, 0x7fffff80, v37
	v_and_b32_e32 v1, 0xffffff80, v1
	v_med3_i32 v36, v39, v38, v0
	v_max_i32_e32 v0, v39, v0
	v_bitop3_b32 v1, v37, s66, v1 bitop3:0xde
	v_med3_i32 v2, v3, v2, v1
	v_med3_i32 v3, v4, v3, v1
	v_med3_i32 v4, v5, v4, v1
	v_med3_i32 v5, v6, v5, v1
	v_med3_i32 v6, v7, v6, v1
	v_med3_i32 v7, v8, v7, v1
	v_med3_i32 v8, v9, v8, v1
	v_med3_i32 v9, v10, v9, v1
	v_med3_i32 v10, v11, v10, v1
	v_med3_i32 v11, v32, v11, v1
	v_med3_i32 v32, v33, v32, v1
	v_med3_i32 v33, v34, v33, v1
	v_med3_i32 v34, v35, v34, v1
	v_med3_i32 v35, v36, v35, v1
	v_med3_i32 v36, v0, v36, v1
	v_max_i32_e32 v37, v0, v1
	v_pk_mul_f32 v[0:1], v[12:13], s[26:27] op_sel_hi:[1,0]
	s_nop 0
	v_ashrrev_i32_e32 v12, 31, v0
	v_and_b32_e32 v12, 0x7fffff80, v12
	v_and_b32_e32 v0, 0xffffff80, v0
	v_bitop3_b32 v0, v12, s67, v0 bitop3:0xde
	v_med3_i32 v2, v3, v2, v0
	v_med3_i32 v3, v4, v3, v0
	v_med3_i32 v4, v5, v4, v0
	v_med3_i32 v5, v6, v5, v0
	v_med3_i32 v6, v7, v6, v0
	v_med3_i32 v7, v8, v7, v0
	v_med3_i32 v8, v9, v8, v0
	v_med3_i32 v9, v10, v9, v0
	v_med3_i32 v10, v11, v10, v0
	v_med3_i32 v11, v32, v11, v0
	v_med3_i32 v12, v33, v32, v0
	v_med3_i32 v13, v34, v33, v0
	v_med3_i32 v32, v35, v34, v0
	v_med3_i32 v33, v36, v35, v0
	v_ashrrev_i32_e32 v35, 31, v1
	v_and_b32_e32 v35, 0x7fffff80, v35
	v_and_b32_e32 v1, 0xffffff80, v1
	v_med3_i32 v34, v37, v36, v0
	v_max_i32_e32 v0, v37, v0
	v_bitop3_b32 v1, v35, s68, v1 bitop3:0xde
	v_med3_i32 v2, v3, v2, v1
	v_med3_i32 v3, v4, v3, v1
	v_med3_i32 v4, v5, v4, v1
	v_med3_i32 v5, v6, v5, v1
	v_med3_i32 v6, v7, v6, v1
	v_med3_i32 v7, v8, v7, v1
	v_med3_i32 v8, v9, v8, v1
	v_med3_i32 v9, v10, v9, v1
	v_med3_i32 v10, v11, v10, v1
; DI int med3i(int a, int b, int c) { int r; asm("v_med3_i32 %0, %1, %2, %3" : "=v"(r) : "v"(a), "v"(b), "v"(c)); return r; }
; DI void insert16(int (&L)[16], int x) {
; #pragma unroll
;   for (int j = 15; j >= 1; --j) L[j] = med3i(L[j - 1], L[j], x);
;   L[0] = max(L[0], x);
; }
; DI int f2sort(float f) { int b = __float_as_int(f); return b ^ ((b >> 31) & 0x7fffffff); }
; DI void p5a_half(const bf16x8 (&qf)[8], const u16* __restrict__ pk, float rs, int (&Lh)[16], u16* smem, int tid, int r, int h) {
;     ...
;     for (int i = 0; i < 16; ++i) {
;       const int keyc = kt * 32 + (i & 3) + 8 * (i >> 2);
;       int sb = (f2sort(Y[i] * rs) & ~127) | keyc;
;       insert16(Lh, sb);
;     }
;     __builtin_amdgcn_sched_barrier(0);
;   }
;   const int h4 = 4 * h;
; #pragma unroll
;   for (int j = 0; j < 16; ++j) Lh[j] |= h4;
;   int other[16];
; #pragma unroll
;   for (int j = 0; j < 16; ++j) other[j] = __shfl_xor(Lh[j], 32);
; #pragma unroll
;   for (int j = 0; j < 16; ++j) insert16(Lh, other[j]);
	v_med3_i32 v11, v12, v11, v1
	v_med3_i32 v12, v13, v12, v1
	v_med3_i32 v13, v32, v13, v1
	v_med3_i32 v32, v33, v32, v1
	v_med3_i32 v33, v34, v33, v1
	v_med3_i32 v34, v0, v34, v1
	v_max_i32_e32 v35, v0, v1
	v_pk_mul_f32 v[0:1], v[14:15], s[26:27] op_sel_hi:[1,0]
	s_nop 0
	v_ashrrev_i32_e32 v14, 31, v0
	v_and_b32_e32 v14, 0x7fffff80, v14
	v_and_b32_e32 v0, 0xffffff80, v0
	v_bitop3_b32 v0, v14, s69, v0 bitop3:0xde
	v_med3_i32 v14, v33, v32, v0
	v_med3_i32 v15, v34, v33, v0
	v_ashrrev_i32_e32 v33, 31, v1
	v_and_b32_e32 v33, 0x7fffff80, v33
	v_and_b32_e32 v1, 0xffffff80, v1
	v_med3_i32 v2, v3, v2, v0
	v_med3_i32 v3, v4, v3, v0
	v_med3_i32 v4, v5, v4, v0
	v_med3_i32 v5, v6, v5, v0
	v_med3_i32 v6, v7, v6, v0
	v_med3_i32 v7, v8, v7, v0
	v_med3_i32 v8, v9, v8, v0
	v_med3_i32 v9, v10, v9, v0
	v_med3_i32 v10, v11, v10, v0
	v_med3_i32 v11, v12, v11, v0
	v_med3_i32 v12, v13, v12, v0
	v_med3_i32 v13, v32, v13, v0
	v_med3_i32 v32, v35, v34, v0
	v_max_i32_e32 v0, v35, v0
	v_bitop3_b32 v1, v33, s70, v1 bitop3:0xde
	v_med3_i32 v2, v3, v2, v1
	v_med3_i32 v3, v4, v3, v1
	v_med3_i32 v4, v5, v4, v1
	v_med3_i32 v5, v6, v5, v1
	v_med3_i32 v6, v7, v6, v1
	v_med3_i32 v7, v8, v7, v1
	v_med3_i32 v8, v9, v8, v1
	v_med3_i32 v9, v10, v9, v1
	v_med3_i32 v10, v11, v10, v1
	v_med3_i32 v11, v12, v11, v1
	v_med3_i32 v12, v13, v12, v1
	v_med3_i32 v13, v14, v13, v1
	v_med3_i32 v14, v15, v14, v1
	v_med3_i32 v15, v32, v15, v1
	v_med3_i32 v32, v0, v32, v1
	v_max_i32_e32 v0, v0, v1
	v_and_b32_e32 v33, 64, v198
	v_or_b32_e32 v1, v32, v190
	v_xor_b32_e32 v32, 32, v198
	v_add_u32_e32 v33, 64, v33
	v_cmp_lt_i32_e32 vcc, v32, v33
	v_or_b32_e32 v0, v0, v190
	v_or_b32_e32 v15, v15, v190
	v_cndmask_b32_e32 v32, v198, v32, vcc
	v_lshlrev_b32_e32 v56, 2, v32
	ds_bpermute_b32 v32, v56, v0
	ds_bpermute_b32 v33, v56, v1
	v_or_b32_e32 v14, v14, v190
	ds_bpermute_b32 v34, v56, v15
	v_or_b32_e32 v13, v13, v190
	ds_bpermute_b32 v35, v56, v14
	v_or_b32_e32 v12, v12, v190
	v_or_b32_e32 v11, v11, v190
	v_or_b32_e32 v10, v10, v190
	v_or_b32_e32 v9, v9, v190
	v_or_b32_e32 v8, v8, v190
	v_or_b32_e32 v7, v7, v190
	v_or_b32_e32 v6, v6, v190
	v_or_b32_e32 v5, v5, v190
	v_or_b32_e32 v4, v4, v190
	v_or_b32_e32 v3, v3, v190
	v_or_b32_e32 v2, v2, v190
	ds_bpermute_b32 v36, v56, v13
	ds_bpermute_b32 v37, v56, v12
	ds_bpermute_b32 v38, v56, v11
	ds_bpermute_b32 v39, v56, v10
	ds_bpermute_b32 v40, v56, v9
	ds_bpermute_b32 v41, v56, v8
	ds_bpermute_b32 v42, v56, v7
	ds_bpermute_b32 v43, v56, v6
	ds_bpermute_b32 v44, v56, v5
	ds_bpermute_b32 v45, v56, v4
	ds_bpermute_b32 v46, v56, v3
	ds_bpermute_b32 v57, v56, v2
	s_waitcnt lgkmcnt(14)
	v_med3_i32 v2, v3, v2, v32
	v_med3_i32 v3, v4, v3, v32
	v_med3_i32 v4, v5, v4, v32
	v_med3_i32 v5, v6, v5, v32
	v_med3_i32 v6, v7, v6, v32
	v_med3_i32 v7, v8, v7, v32
	v_med3_i32 v8, v9, v8, v32
	v_med3_i32 v9, v10, v9, v32
	v_med3_i32 v10, v11, v10, v32
	v_med3_i32 v11, v12, v11, v32
	v_med3_i32 v12, v13, v12, v32
	v_med3_i32 v13, v14, v13, v32
	v_med3_i32 v14, v15, v14, v32
	v_med3_i32 v15, v1, v15, v32
	v_med3_i32 v1, v0, v1, v32
	v_max_i32_e32 v0, v0, v32
	v_med3_i32 v2, v3, v2, v33
	v_med3_i32 v3, v4, v3, v33
	v_med3_i32 v4, v5, v4, v33
	v_med3_i32 v5, v6, v5, v33
	v_med3_i32 v6, v7, v6, v33
	v_med3_i32 v7, v8, v7, v33
	v_med3_i32 v8, v9, v8, v33
	v_med3_i32 v9, v10, v9, v33
	v_med3_i32 v10, v11, v10, v33
	v_med3_i32 v11, v12, v11, v33
	v_med3_i32 v12, v13, v12, v33
	v_med3_i32 v13, v14, v13, v33
	v_med3_i32 v14, v15, v14, v33
	v_med3_i32 v15, v1, v15, v33
	v_med3_i32 v1, v0, v1, v33
	v_max_i32_e32 v0, v0, v33
	s_waitcnt lgkmcnt(13)
	v_med3_i32 v2, v3, v2, v34
	v_med3_i32 v3, v4, v3, v34
	v_med3_i32 v4, v5, v4, v34
	v_med3_i32 v5, v6, v5, v34
	v_med3_i32 v6, v7, v6, v34
	v_med3_i32 v7, v8, v7, v34
	v_med3_i32 v8, v9, v8, v34
	v_med3_i32 v9, v10, v9, v34
	v_med3_i32 v10, v11, v10, v34
	v_med3_i32 v11, v12, v11, v34
	v_med3_i32 v12, v13, v12, v34
	v_med3_i32 v13, v14, v13, v34
	v_med3_i32 v14, v15, v14, v34
	v_med3_i32 v15, v1, v15, v34
	v_med3_i32 v1, v0, v1, v34
	v_max_i32_e32 v0, v0, v34
	s_waitcnt lgkmcnt(12)
	v_med3_i32 v2, v3, v2, v35
	v_med3_i32 v3, v4, v3, v35
	v_med3_i32 v4, v5, v4, v35
	v_med3_i32 v5, v6, v5, v35
	v_med3_i32 v6, v7, v6, v35
	v_med3_i32 v7, v8, v7, v35
	v_med3_i32 v8, v9, v8, v35
	v_med3_i32 v9, v10, v9, v35
	v_med3_i32 v10, v11, v10, v35
	v_med3_i32 v11, v12, v11, v35
	v_med3_i32 v12, v13, v12, v35
	v_med3_i32 v13, v14, v13, v35
	v_med3_i32 v14, v15, v14, v35
	v_med3_i32 v15, v1, v15, v35
	v_med3_i32 v1, v0, v1, v35
	v_max_i32_e32 v0, v0, v35
	s_waitcnt lgkmcnt(11)
	v_med3_i32 v2, v3, v2, v36
	v_med3_i32 v3, v4, v3, v36
	v_med3_i32 v4, v5, v4, v36
	v_med3_i32 v5, v6, v5, v36
	v_med3_i32 v6, v7, v6, v36
	v_med3_i32 v7, v8, v7, v36
	v_med3_i32 v8, v9, v8, v36
	v_med3_i32 v9, v10, v9, v36
	v_med3_i32 v10, v11, v10, v36
	v_med3_i32 v11, v12, v11, v36
	v_med3_i32 v12, v13, v12, v36
	v_med3_i32 v13, v14, v13, v36
	v_med3_i32 v14, v15, v14, v36
	v_med3_i32 v15, v1, v15, v36
	v_med3_i32 v1, v0, v1, v36
	v_max_i32_e32 v0, v0, v36
	s_waitcnt lgkmcnt(10)
	v_med3_i32 v2, v3, v2, v37
	v_med3_i32 v3, v4, v3, v37
	v_med3_i32 v4, v5, v4, v37
	v_med3_i32 v5, v6, v5, v37
	v_med3_i32 v6, v7, v6, v37
	v_med3_i32 v7, v8, v7, v37
	v_med3_i32 v8, v9, v8, v37
	v_med3_i32 v9, v10, v9, v37
	v_med3_i32 v10, v11, v10, v37
	v_med3_i32 v11, v12, v11, v37
	v_med3_i32 v12, v13, v12, v37
	v_med3_i32 v13, v14, v13, v37
	v_med3_i32 v14, v15, v14, v37
	v_med3_i32 v15, v1, v15, v37
	v_med3_i32 v1, v0, v1, v37
	v_max_i32_e32 v0, v0, v37
	s_waitcnt lgkmcnt(9)
; DI void p5a_half(const bf16x8 (&qf)[8], const u16* __restrict__ pk, float rs, int (&Lh)[16], u16* smem, int tid, int r, int h) {
;     ...
;   for (int i = 0; i < 8; ++i) {
;     int pidx = tid + 256 * i; int row = pidx >> 4, ch = pidx & 15;
;     uint4 v = *(const uint4*)(pk + row * 128 + ch * 8);
;     uint2* d = (uint2*)(smem + row * LPK + ch * 8);
;     d[0] = make_uint2(v.x, v.y); d[1] = make_uint2(v.z, v.w);
;   }
;   __syncthreads();
;     ...
;   for (int j = 0; j < 16; ++j) other[j] = __shfl_xor(Lh[j], 32);
; #pragma unroll
;   for (int j = 0; j < 16; ++j) insert16(Lh, other[j]);
;   __syncthreads();
	v_med3_i32 v2, v3, v2, v38
	v_med3_i32 v3, v4, v3, v38
	v_med3_i32 v4, v5, v4, v38
	v_med3_i32 v5, v6, v5, v38
	v_med3_i32 v6, v7, v6, v38
	v_med3_i32 v7, v8, v7, v38
	v_med3_i32 v8, v9, v8, v38
	v_med3_i32 v9, v10, v9, v38
	v_med3_i32 v10, v11, v10, v38
	v_med3_i32 v11, v12, v11, v38
	v_med3_i32 v12, v13, v12, v38
	v_med3_i32 v13, v14, v13, v38
	v_med3_i32 v14, v15, v14, v38
	v_med3_i32 v15, v1, v15, v38
	v_med3_i32 v1, v0, v1, v38
	v_max_i32_e32 v0, v0, v38
	s_waitcnt lgkmcnt(8)
	v_med3_i32 v2, v3, v2, v39
	v_med3_i32 v3, v4, v3, v39
	v_med3_i32 v4, v5, v4, v39
	v_med3_i32 v5, v6, v5, v39
	v_med3_i32 v6, v7, v6, v39
	v_med3_i32 v7, v8, v7, v39
	v_med3_i32 v8, v9, v8, v39
	v_med3_i32 v9, v10, v9, v39
	v_med3_i32 v10, v11, v10, v39
	v_med3_i32 v11, v12, v11, v39
	v_med3_i32 v12, v13, v12, v39
	v_med3_i32 v13, v14, v13, v39
	v_med3_i32 v14, v15, v14, v39
	v_med3_i32 v15, v1, v15, v39
	v_med3_i32 v1, v0, v1, v39
	v_max_i32_e32 v0, v0, v39
	s_waitcnt lgkmcnt(7)
	v_med3_i32 v2, v3, v2, v40
	v_med3_i32 v3, v4, v3, v40
	v_med3_i32 v4, v5, v4, v40
	v_med3_i32 v5, v6, v5, v40
	v_med3_i32 v6, v7, v6, v40
	v_med3_i32 v7, v8, v7, v40
	v_med3_i32 v8, v9, v8, v40
	v_med3_i32 v9, v10, v9, v40
	v_med3_i32 v10, v11, v10, v40
	v_med3_i32 v11, v12, v11, v40
	v_med3_i32 v12, v13, v12, v40
	v_med3_i32 v13, v14, v13, v40
	v_med3_i32 v14, v15, v14, v40
	v_med3_i32 v15, v1, v15, v40
	v_med3_i32 v1, v0, v1, v40
	v_max_i32_e32 v0, v0, v40
	s_waitcnt lgkmcnt(6)
	v_med3_i32 v2, v3, v2, v41
	v_med3_i32 v3, v4, v3, v41
	v_med3_i32 v4, v5, v4, v41
	v_med3_i32 v5, v6, v5, v41
	v_med3_i32 v6, v7, v6, v41
	v_med3_i32 v7, v8, v7, v41
	v_med3_i32 v8, v9, v8, v41
	v_med3_i32 v9, v10, v9, v41
	v_med3_i32 v10, v11, v10, v41
	v_med3_i32 v11, v12, v11, v41
	v_med3_i32 v12, v13, v12, v41
	v_med3_i32 v13, v14, v13, v41
	v_med3_i32 v14, v15, v14, v41
	v_med3_i32 v15, v1, v15, v41
	v_med3_i32 v1, v0, v1, v41
	v_max_i32_e32 v0, v0, v41
	s_waitcnt lgkmcnt(5)
	v_med3_i32 v2, v3, v2, v42
	v_med3_i32 v3, v4, v3, v42
	v_med3_i32 v4, v5, v4, v42
	v_med3_i32 v5, v6, v5, v42
	v_med3_i32 v6, v7, v6, v42
	v_med3_i32 v7, v8, v7, v42
	v_med3_i32 v8, v9, v8, v42
	v_med3_i32 v9, v10, v9, v42
	v_med3_i32 v10, v11, v10, v42
	v_med3_i32 v11, v12, v11, v42
	v_med3_i32 v12, v13, v12, v42
	v_med3_i32 v13, v14, v13, v42
	v_med3_i32 v14, v15, v14, v42
	v_med3_i32 v15, v1, v15, v42
	v_med3_i32 v1, v0, v1, v42
	v_max_i32_e32 v0, v0, v42
	s_waitcnt lgkmcnt(4)
	v_med3_i32 v2, v3, v2, v43
	v_med3_i32 v3, v4, v3, v43
	v_med3_i32 v4, v5, v4, v43
	v_med3_i32 v5, v6, v5, v43
	v_med3_i32 v6, v7, v6, v43
	v_med3_i32 v7, v8, v7, v43
	v_med3_i32 v8, v9, v8, v43
	v_med3_i32 v9, v10, v9, v43
	v_med3_i32 v10, v11, v10, v43
	v_med3_i32 v11, v12, v11, v43
	v_med3_i32 v12, v13, v12, v43
	v_med3_i32 v13, v14, v13, v43
	v_med3_i32 v14, v15, v14, v43
	v_med3_i32 v15, v1, v15, v43
	v_med3_i32 v1, v0, v1, v43
	v_max_i32_e32 v0, v0, v43
	s_waitcnt lgkmcnt(3)
	v_med3_i32 v2, v3, v2, v44
	v_med3_i32 v3, v4, v3, v44
	v_med3_i32 v4, v5, v4, v44
	v_med3_i32 v5, v6, v5, v44
	v_med3_i32 v6, v7, v6, v44
	v_med3_i32 v7, v8, v7, v44
	v_med3_i32 v8, v9, v8, v44
	v_med3_i32 v9, v10, v9, v44
	v_med3_i32 v10, v11, v10, v44
	v_med3_i32 v11, v12, v11, v44
	v_med3_i32 v12, v13, v12, v44
	v_med3_i32 v13, v14, v13, v44
	v_med3_i32 v14, v15, v14, v44
	v_med3_i32 v15, v1, v15, v44
	v_med3_i32 v1, v0, v1, v44
	v_max_i32_e32 v0, v0, v44
	s_waitcnt lgkmcnt(2)
	v_med3_i32 v2, v3, v2, v45
	v_med3_i32 v3, v4, v3, v45
	v_med3_i32 v4, v5, v4, v45
	v_med3_i32 v5, v6, v5, v45
	v_med3_i32 v6, v7, v6, v45
	v_med3_i32 v7, v8, v7, v45
	v_med3_i32 v8, v9, v8, v45
	v_med3_i32 v9, v10, v9, v45
	v_med3_i32 v10, v11, v10, v45
	v_med3_i32 v11, v12, v11, v45
	v_med3_i32 v12, v13, v12, v45
	v_med3_i32 v13, v14, v13, v45
	v_med3_i32 v14, v15, v14, v45
	v_med3_i32 v15, v1, v15, v45
	v_med3_i32 v1, v0, v1, v45
	v_max_i32_e32 v0, v0, v45
	s_waitcnt lgkmcnt(1)
	v_med3_i32 v2, v3, v2, v46
	v_med3_i32 v3, v4, v3, v46
	v_med3_i32 v4, v5, v4, v46
	v_med3_i32 v5, v6, v5, v46
	v_med3_i32 v6, v7, v6, v46
	v_med3_i32 v7, v8, v7, v46
	v_med3_i32 v8, v9, v8, v46
	v_med3_i32 v9, v10, v9, v46
	v_med3_i32 v10, v11, v10, v46
	v_med3_i32 v11, v12, v11, v46
	v_med3_i32 v12, v13, v12, v46
	v_med3_i32 v13, v14, v13, v46
	v_med3_i32 v14, v15, v14, v46
	v_med3_i32 v15, v1, v15, v46
	v_med3_i32 v1, v0, v1, v46
	v_max_i32_e32 v0, v0, v46
	s_waitcnt lgkmcnt(0)
	v_med3_i32 v32, v3, v2, v57
	v_med3_i32 v33, v4, v3, v57
	v_med3_i32 v36, v5, v4, v57
	v_med3_i32 v37, v6, v5, v57
	v_med3_i32 v35, v7, v6, v57
	v_med3_i32 v34, v8, v7, v57
	v_med3_i32 v38, v9, v8, v57
	v_med3_i32 v39, v10, v9, v57
	v_med3_i32 v43, v11, v10, v57
	v_med3_i32 v40, v12, v11, v57
	v_med3_i32 v44, v13, v12, v57
	v_med3_i32 v45, v14, v13, v57
	v_med3_i32 v41, v15, v14, v57
	v_med3_i32 v47, v1, v15, v57
	v_med3_i32 v46, v0, v1, v57
	v_max_i32_e32 v42, v0, v57
	s_barrier
	v_lshl_add_u64 v[66:67], v[136:137], 0, s[10:11]
	v_lshl_add_u64 v[0:1], v[66:67], 0, v[138:139]
	v_lshl_add_u64 v[4:5], v[66:67], 0, v[140:141]
	v_lshl_add_u64 v[8:9], v[66:67], 0, v[142:143]
	v_lshl_add_u64 v[12:13], v[66:67], 0, v[144:145]
	v_lshl_add_u64 v[58:59], v[66:67], 0, v[146:147]
	v_lshl_add_u64 v[62:63], v[66:67], 0, v[148:149]
	v_lshl_add_u64 v[68:69], v[66:67], 0, v[150:151]
	global_load_dwordx4 v[0:3], v[0:1], off
	s_nop 0
	global_load_dwordx4 v[4:7], v[4:5], off
	s_nop 0
	global_load_dwordx4 v[8:11], v[8:9], off
	s_nop 0
	global_load_dwordx4 v[12:15], v[12:13], off
	s_nop 0
	global_load_dwordx4 v[58:61], v[58:59], off
	s_nop 0
	global_load_dwordx4 v[62:65], v[62:63], off
	v_lshl_add_u64 v[70:71], v[66:67], 0, v[152:153]
	global_load_dwordx4 v[66:69], v[68:69], off
	s_nop 0
	global_load_dwordx4 v[76:79], v[70:71], off
	s_waitcnt vmcnt(7)
	ds_write2_b64 v163, v[0:1], v[2:3] offset1:1
	s_waitcnt vmcnt(6)
	ds_write2_b64 v164, v[4:5], v[6:7] offset1:1
	s_waitcnt vmcnt(5)
	ds_write2_b64 v165, v[8:9], v[10:11] offset1:1
	s_waitcnt vmcnt(4)
	ds_write2_b64 v166, v[12:13], v[14:15] offset1:1
	s_waitcnt vmcnt(3)
	ds_write2_b64 v75, v[58:59], v[60:61] offset1:1
	s_waitcnt vmcnt(2)
	ds_write2_b64 v167, v[62:63], v[64:65] offset1:1
	s_waitcnt vmcnt(1)
	ds_write2_b64 v168, v[66:67], v[68:69] offset1:1
	s_waitcnt vmcnt(0)
	ds_write2_b64 v169, v[76:77], v[78:79] offset1:1
	s_waitcnt lgkmcnt(0)
	s_barrier
; #define MFMA32(a, b, c) __builtin_amdgcn_mfma_f32_32x32x16_bf16((a), (b), (c), 0, 0, 0)
; DI int med3i(int a, int b, int c) { int r; asm("v_med3_i32 %0, %1, %2, %3" : "=v"(r) : "v"(a), "v"(b), "v"(c)); return r; }
; DI void insert16(int (&L)[16], int x) {
; #pragma unroll
;   for (int j = 15; j >= 1; --j) L[j] = med3i(L[j - 1], L[j], x);
;   L[0] = max(L[0], x);
; }
; DI int f2sort(float f) { int b = __float_as_int(f); return b ^ ((b >> 31) & 0x7fffffff); }
; DI void p5a_half(const bf16x8 (&qf)[8], const u16* __restrict__ pk, float rs, int (&Lh)[16], u16* smem, int tid, int r, int h) {
;     ...
; #pragma unroll
;   for (int j = 0; j < 16; ++j) Lh[j] = (int)0x80000000;
; #pragma unroll
;   for (int kt = 0; kt < 4; ++kt) {
;     f32x16 Y = zero16();
; #pragma unroll
;     for (int ks = 0; ks < 8; ++ks) {
;       const int m = ks >> 1, s = ks & 1;
;       const u16* pp = smem + (kt * 32 + r) * LPK + 32 * m + 16 * s + 4 * h;
;       s16x4 lo = *(const s16x4*)pp;
;       s16x4 hi = *(const s16x4*)(pp + 8);
;       bf16x8 a = __builtin_shufflevector(lo, hi, 0, 1, 2, 3, 4, 5, 6, 7);
;       Y = MFMA32(a, qf[ks], Y);
;     }
; #pragma unroll
;     for (int i = 0; i < 16; ++i) {
;       const int keyc = kt * 32 + (i & 3) + 8 * (i >> 2);
;       int sb = (f2sort(Y[i] * rs) & ~127) | keyc;
;       insert16(Lh, sb);
;     }
	ds_read2_b64 v[0:3], v156 offset1:2
	ds_read2_b64 v[58:61], v156 offset0:4 offset1:6
	s_waitcnt lgkmcnt(1)
	v_mfma_f32_32x32x16_bf16 v[0:15], v[0:3], v[80:83], 0
	s_waitcnt lgkmcnt(0)
	v_mfma_f32_32x32x16_bf16 v[0:15], v[58:61], v[84:87], v[0:15]
	ds_read2_b64 v[58:61], v156 offset0:8 offset1:10
	s_waitcnt lgkmcnt(0)
	v_mfma_f32_32x32x16_bf16 v[0:15], v[58:61], v[52:55], v[0:15]
	ds_read2_b64 v[58:61], v156 offset0:12 offset1:14
	s_waitcnt lgkmcnt(0)
	v_mfma_f32_32x32x16_bf16 v[0:15], v[58:61], v[48:51], v[0:15]
	ds_read2_b64 v[58:61], v156 offset0:16 offset1:18
	s_waitcnt lgkmcnt(0)
	v_mfma_f32_32x32x16_bf16 v[0:15], v[58:61], v[20:23], v[0:15]
	ds_read2_b64 v[58:61], v156 offset0:20 offset1:22
	s_waitcnt lgkmcnt(0)
	v_mfma_f32_32x32x16_bf16 v[0:15], v[58:61], v[16:19], v[0:15]
	ds_read2_b64 v[58:61], v156 offset0:24 offset1:26
	s_waitcnt lgkmcnt(0)
	v_mfma_f32_32x32x16_bf16 v[0:15], v[58:61], v[28:31], v[0:15]
	ds_read2_b64 v[58:61], v156 offset0:28 offset1:30
	s_waitcnt lgkmcnt(0)
	v_mfma_f32_32x32x16_bf16 v[0:15], v[58:61], v[24:27], v[0:15]
	s_nop 11
	v_pk_mul_f32 v[0:1], v[0:1], s[26:27] op_sel_hi:[1,0]
	v_pk_mul_f32 v[2:3], v[2:3], s[26:27] op_sel_hi:[1,0]
	v_ashrrev_i32_e32 v57, 31, v0
	v_and_b32_e32 v0, 0xffffff80, v0
	v_ashrrev_i32_e32 v58, 31, v1
	v_pk_mul_f32 v[4:5], v[4:5], s[26:27] op_sel_hi:[1,0]
	v_pk_mul_f32 v[6:7], v[6:7], s[26:27] op_sel_hi:[1,0]
	v_pk_mul_f32 v[8:9], v[8:9], s[26:27] op_sel_hi:[1,0]
	v_pk_mul_f32 v[10:11], v[10:11], s[26:27] op_sel_hi:[1,0]
	v_and_b32_e32 v1, 0xffffff80, v1
	v_ashrrev_i32_e32 v59, 31, v2
	v_bitop3_b32 v0, v57, v0, s37 bitop3:0x6c
	v_and_b32_e32 v57, 0x7fffff80, v58
	v_and_b32_e32 v2, 0xffffff80, v2
	v_ashrrev_i32_e32 v60, 31, v3
	v_ashrrev_i32_e32 v61, 31, v4
	v_ashrrev_i32_e32 v62, 31, v5
	v_ashrrev_i32_e32 v63, 31, v6
	v_ashrrev_i32_e32 v64, 31, v7
	v_ashrrev_i32_e32 v65, 31, v8
	v_ashrrev_i32_e32 v66, 31, v9
	v_ashrrev_i32_e32 v67, 31, v10
	v_and_b32_e32 v58, 0x7fffff80, v59
	v_bitop3_b32 v1, v57, 1, v1 bitop3:0xde
	v_and_b32_e32 v3, 0xffffff80, v3
	v_and_b32_e32 v59, 0x7fffff80, v60
	v_and_b32_e32 v60, 0x7fffff80, v61
	v_and_b32_e32 v61, 0x7fffff80, v62
	v_and_b32_e32 v62, 0x7fffff80, v63
	v_and_b32_e32 v63, 0x7fffff80, v64
	v_and_b32_e32 v64, 0x7fffff80, v65
	v_and_b32_e32 v65, 0x7fffff80, v66
	v_and_b32_e32 v66, 0x7fffff80, v67
	v_med3_i32 v67, v170, v170, v0
	v_bitop3_b32 v2, v58, 2, v2 bitop3:0xde
	v_med3_i32 v57, v67, v67, v1
	v_med3_i32 v58, v0, v67, v1
	v_max_i32_e32 v0, v0, v1
	v_and_b32_e32 v4, 0xffffff80, v4
	v_bitop3_b32 v3, v59, 3, v3 bitop3:0xde
	v_med3_i32 v1, v57, v57, v2
	v_med3_i32 v57, v58, v57, v2
	v_med3_i32 v58, v0, v58, v2
	v_max_i32_e32 v0, v0, v2
	v_and_b32_e32 v5, 0xffffff80, v5
	v_bitop3_b32 v4, v60, 8, v4 bitop3:0xde
	v_med3_i32 v2, v1, v1, v3
	v_med3_i32 v1, v57, v1, v3
	v_med3_i32 v57, v58, v57, v3
	v_med3_i32 v58, v0, v58, v3
	v_max_i32_e32 v0, v0, v3
	v_and_b32_e32 v6, 0xffffff80, v6
	v_bitop3_b32 v5, v61, 9, v5 bitop3:0xde
	v_med3_i32 v3, v2, v2, v4
	v_med3_i32 v2, v1, v2, v4
	v_med3_i32 v1, v57, v1, v4
	v_med3_i32 v57, v58, v57, v4
	v_med3_i32 v58, v0, v58, v4
	v_max_i32_e32 v0, v0, v4
	v_and_b32_e32 v7, 0xffffff80, v7
	v_bitop3_b32 v6, v62, 10, v6 bitop3:0xde
	v_med3_i32 v4, v3, v3, v5
	v_med3_i32 v3, v2, v3, v5
	v_med3_i32 v2, v1, v2, v5
	v_med3_i32 v1, v57, v1, v5
	v_med3_i32 v57, v58, v57, v5
	v_med3_i32 v58, v0, v58, v5
	v_max_i32_e32 v0, v0, v5
	v_and_b32_e32 v8, 0xffffff80, v8
	v_bitop3_b32 v7, v63, 11, v7 bitop3:0xde
	v_med3_i32 v5, v4, v4, v6
	v_med3_i32 v4, v3, v4, v6
	v_med3_i32 v3, v2, v3, v6
	v_med3_i32 v2, v1, v2, v6
	v_med3_i32 v1, v57, v1, v6
	v_med3_i32 v57, v58, v57, v6
	v_med3_i32 v58, v0, v58, v6
	v_max_i32_e32 v0, v0, v6
	v_and_b32_e32 v9, 0xffffff80, v9
	v_bitop3_b32 v8, v64, 16, v8 bitop3:0xde
	v_med3_i32 v6, v5, v5, v7
	v_med3_i32 v5, v4, v5, v7
	v_med3_i32 v4, v3, v4, v7
	v_med3_i32 v3, v2, v3, v7
	v_med3_i32 v2, v1, v2, v7
	v_med3_i32 v1, v57, v1, v7
	v_med3_i32 v57, v58, v57, v7
	v_med3_i32 v58, v0, v58, v7
	v_max_i32_e32 v0, v0, v7
	v_and_b32_e32 v10, 0xffffff80, v10
	v_bitop3_b32 v9, v65, 17, v9 bitop3:0xde
	v_med3_i32 v7, v6, v6, v8
	v_med3_i32 v6, v5, v6, v8
	v_med3_i32 v5, v4, v5, v8
	v_med3_i32 v4, v3, v4, v8
	v_med3_i32 v3, v2, v3, v8
	v_med3_i32 v2, v1, v2, v8
	v_med3_i32 v1, v57, v1, v8
	v_med3_i32 v57, v58, v57, v8
	v_med3_i32 v58, v0, v58, v8
	v_max_i32_e32 v0, v0, v8
	v_bitop3_b32 v10, v66, 18, v10 bitop3:0xde
	v_med3_i32 v8, v7, v7, v9
	v_med3_i32 v7, v6, v7, v9
	v_med3_i32 v6, v5, v6, v9
	v_med3_i32 v5, v4, v5, v9
	v_med3_i32 v4, v3, v4, v9
	v_med3_i32 v3, v2, v3, v9
	v_med3_i32 v2, v1, v2, v9
	v_med3_i32 v1, v57, v1, v9
	v_med3_i32 v57, v58, v57, v9
	v_med3_i32 v58, v0, v58, v9
	v_max_i32_e32 v0, v0, v9
	v_med3_i32 v9, v8, v8, v10
	v_med3_i32 v8, v7, v8, v10
	v_med3_i32 v7, v6, v7, v10
	v_med3_i32 v6, v5, v6, v10
	v_med3_i32 v5, v4, v5, v10
	v_med3_i32 v4, v3, v4, v10
	v_med3_i32 v3, v2, v3, v10
	v_med3_i32 v2, v1, v2, v10
	v_med3_i32 v1, v57, v1, v10
	v_med3_i32 v57, v58, v57, v10
	v_med3_i32 v58, v0, v58, v10
	v_max_i32_e32 v0, v0, v10
	v_ashrrev_i32_e32 v10, 31, v11
	v_and_b32_e32 v10, 0x7fffff80, v10
	v_and_b32_e32 v11, 0xffffff80, v11
	v_bitop3_b32 v10, v10, 19, v11 bitop3:0xde
	v_med3_i32 v11, v9, v9, v10
	v_med3_i32 v9, v8, v9, v10
	v_med3_i32 v8, v7, v8, v10
	v_med3_i32 v7, v6, v7, v10
	v_med3_i32 v6, v5, v6, v10
	v_med3_i32 v5, v4, v5, v10
	v_med3_i32 v4, v3, v4, v10
	v_med3_i32 v3, v2, v3, v10
	v_med3_i32 v2, v1, v2, v10
	v_med3_i32 v59, v57, v1, v10
	v_med3_i32 v57, v58, v57, v10
	v_med3_i32 v58, v0, v58, v10
	v_max_i32_e32 v10, v0, v10
	v_pk_mul_f32 v[0:1], v[12:13], s[26:27] op_sel_hi:[1,0]
; #define MFMA32(a, b, c) __builtin_amdgcn_mfma_f32_32x32x16_bf16((a), (b), (c), 0, 0, 0)
; DI int med3i(int a, int b, int c) { int r; asm("v_med3_i32 %0, %1, %2, %3" : "=v"(r) : "v"(a), "v"(b), "v"(c)); return r; }
; DI void insert16(int (&L)[16], int x) {
; #pragma unroll
;   for (int j = 15; j >= 1; --j) L[j] = med3i(L[j - 1], L[j], x);
;   L[0] = max(L[0], x);
; }
; DI int f2sort(float f) { int b = __float_as_int(f); return b ^ ((b >> 31) & 0x7fffffff); }
; DI void p5a_half(const bf16x8 (&qf)[8], const u16* __restrict__ pk, float rs, int (&Lh)[16], u16* smem, int tid, int r, int h) {
;     ...
;   for (int kt = 0; kt < 4; ++kt) {
;     f32x16 Y = zero16();
; #pragma unroll
;     for (int ks = 0; ks < 8; ++ks) {
;       const int m = ks >> 1, s = ks & 1;
;       const u16* pp = smem + (kt * 32 + r) * LPK + 32 * m + 16 * s + 4 * h;
;       s16x4 lo = *(const s16x4*)pp;
;       s16x4 hi = *(const s16x4*)(pp + 8);
;       bf16x8 a = __builtin_shufflevector(lo, hi, 0, 1, 2, 3, 4, 5, 6, 7);
;       Y = MFMA32(a, qf[ks], Y);
;     }
; #pragma unroll
;     for (int i = 0; i < 16; ++i) {
;       const int keyc = kt * 32 + (i & 3) + 8 * (i >> 2);
;       int sb = (f2sort(Y[i] * rs) & ~127) | keyc;
;       insert16(Lh, sb);
;     }
;     __builtin_amdgcn_sched_barrier(0);
	s_nop 0
	v_ashrrev_i32_e32 v12, 31, v0
	v_and_b32_e32 v12, 0x7fffff80, v12
	v_and_b32_e32 v0, 0xffffff80, v0
	v_bitop3_b32 v0, v12, 24, v0 bitop3:0xde
	v_med3_i32 v12, v11, v11, v0
	v_med3_i32 v11, v9, v11, v0
	v_med3_i32 v9, v8, v9, v0
	v_med3_i32 v8, v7, v8, v0
	v_med3_i32 v7, v6, v7, v0
	v_med3_i32 v6, v5, v6, v0
	v_med3_i32 v5, v4, v5, v0
	v_med3_i32 v4, v3, v4, v0
	v_med3_i32 v3, v2, v3, v0
	v_med3_i32 v2, v59, v2, v0
	v_med3_i32 v13, v57, v59, v0
	v_med3_i32 v57, v58, v57, v0
	v_med3_i32 v58, v10, v58, v0
	v_max_i32_e32 v0, v10, v0
	v_ashrrev_i32_e32 v10, 31, v1
	v_and_b32_e32 v10, 0x7fffff80, v10
	v_and_b32_e32 v1, 0xffffff80, v1
	v_bitop3_b32 v1, v10, 25, v1 bitop3:0xde
	v_med3_i32 v10, v12, v12, v1
	v_med3_i32 v12, v11, v12, v1
	v_med3_i32 v11, v9, v11, v1
	v_med3_i32 v9, v8, v9, v1
	v_med3_i32 v8, v7, v8, v1
	v_med3_i32 v7, v6, v7, v1
	v_med3_i32 v6, v5, v6, v1
	v_med3_i32 v5, v4, v5, v1
	v_med3_i32 v4, v3, v4, v1
	v_med3_i32 v3, v2, v3, v1
	v_med3_i32 v2, v13, v2, v1
	v_med3_i32 v13, v57, v13, v1
	v_med3_i32 v57, v58, v57, v1
	v_med3_i32 v58, v0, v58, v1
	v_max_i32_e32 v59, v0, v1
	v_pk_mul_f32 v[0:1], v[14:15], s[26:27] op_sel_hi:[1,0]
	s_nop 0
	v_ashrrev_i32_e32 v14, 31, v0
	v_and_b32_e32 v14, 0x7fffff80, v14
	v_and_b32_e32 v0, 0xffffff80, v0
	v_bitop3_b32 v0, v14, 26, v0 bitop3:0xde
	v_med3_i32 v14, v10, v10, v0
	v_med3_i32 v10, v12, v10, v0
	v_med3_i32 v12, v11, v12, v0
	v_med3_i32 v11, v9, v11, v0
	v_med3_i32 v9, v8, v9, v0
	v_med3_i32 v8, v7, v8, v0
	v_med3_i32 v7, v6, v7, v0
	v_med3_i32 v6, v5, v6, v0
	v_med3_i32 v5, v4, v5, v0
	v_med3_i32 v4, v3, v4, v0
	v_med3_i32 v3, v2, v3, v0
	v_med3_i32 v2, v13, v2, v0
	v_med3_i32 v13, v57, v13, v0
	v_med3_i32 v15, v58, v57, v0
	v_med3_i32 v57, v59, v58, v0
	v_ashrrev_i32_e32 v58, 31, v1
	v_and_b32_e32 v58, 0x7fffff80, v58
	v_and_b32_e32 v1, 0xffffff80, v1
	v_max_i32_e32 v0, v59, v0
	v_bitop3_b32 v1, v58, 27, v1 bitop3:0xde
	v_med3_i32 v62, v10, v14, v1
	v_med3_i32 v63, v12, v10, v1
	v_med3_i32 v64, v11, v12, v1
	v_med3_i32 v65, v9, v11, v1
	v_med3_i32 v66, v8, v9, v1
	v_med3_i32 v67, v7, v8, v1
	v_med3_i32 v68, v6, v7, v1
	v_med3_i32 v69, v5, v6, v1
	v_med3_i32 v70, v4, v5, v1
	v_med3_i32 v71, v3, v4, v1
	v_med3_i32 v75, v2, v3, v1
	v_med3_i32 v76, v13, v2, v1
	v_med3_i32 v77, v15, v13, v1
	v_med3_i32 v78, v57, v15, v1
	v_med3_i32 v57, v0, v57, v1
	v_max_i32_e32 v79, v0, v1
	ds_read2_b64 v[0:3], v72 offset0:32 offset1:34
	ds_read2_b64 v[58:61], v72 offset0:36 offset1:38
	s_waitcnt lgkmcnt(1)
	v_mfma_f32_32x32x16_bf16 v[0:15], v[0:3], v[80:83], 0
	s_waitcnt lgkmcnt(0)
	v_mfma_f32_32x32x16_bf16 v[0:15], v[58:61], v[84:87], v[0:15]
	ds_read2_b64 v[58:61], v72 offset0:40 offset1:42
	s_waitcnt lgkmcnt(0)
	v_mfma_f32_32x32x16_bf16 v[0:15], v[58:61], v[52:55], v[0:15]
	ds_read2_b64 v[58:61], v72 offset0:44 offset1:46
	s_waitcnt lgkmcnt(0)
	v_mfma_f32_32x32x16_bf16 v[0:15], v[58:61], v[48:51], v[0:15]
	ds_read2_b64 v[58:61], v72 offset0:48 offset1:50
	s_waitcnt lgkmcnt(0)
	v_mfma_f32_32x32x16_bf16 v[0:15], v[58:61], v[20:23], v[0:15]
	ds_read2_b64 v[58:61], v72 offset0:52 offset1:54
	s_waitcnt lgkmcnt(0)
	v_mfma_f32_32x32x16_bf16 v[0:15], v[58:61], v[16:19], v[0:15]
	ds_read2_b64 v[58:61], v72 offset0:56 offset1:58
	s_waitcnt lgkmcnt(0)
	v_mfma_f32_32x32x16_bf16 v[0:15], v[58:61], v[28:31], v[0:15]
	ds_read2_b64 v[58:61], v72 offset0:60 offset1:62
	s_waitcnt lgkmcnt(0)
	v_mfma_f32_32x32x16_bf16 v[0:15], v[58:61], v[24:27], v[0:15]
	s_nop 11
	v_pk_mul_f32 v[0:1], v[0:1], s[26:27] op_sel_hi:[1,0]
	v_pk_mul_f32 v[2:3], v[2:3], s[26:27] op_sel_hi:[1,0]
	v_ashrrev_i32_e32 v58, 31, v0
	v_and_b32_e32 v0, 0xffffff80, v0
	v_ashrrev_i32_e32 v59, 31, v1
	v_ashrrev_i32_e32 v60, 31, v2
	v_and_b32_e32 v58, 0x7fffff80, v58
	v_and_b32_e32 v1, 0xffffff80, v1
	v_and_b32_e32 v2, 0xffffff80, v2
	v_and_b32_e32 v59, 0x7fffff80, v59
	v_and_b32_e32 v60, 0x7fffff80, v60
	v_bitop3_b32 v0, v58, 32, v0 bitop3:0xde
	v_bitop3_b32 v1, v59, 33, v1 bitop3:0xde
	v_bitop3_b32 v2, v60, 34, v2 bitop3:0xde
	v_med3_i32 v58, v63, v62, v0
	v_med3_i32 v59, v64, v63, v0
	v_med3_i32 v60, v65, v64, v0
	v_med3_i32 v62, v66, v65, v0
	v_med3_i32 v63, v67, v66, v0
	v_med3_i32 v64, v68, v67, v0
	v_med3_i32 v65, v69, v68, v0
	v_med3_i32 v66, v70, v69, v0
	v_med3_i32 v67, v71, v70, v0
	v_med3_i32 v68, v75, v71, v0
	v_med3_i32 v69, v76, v75, v0
	v_med3_i32 v70, v77, v76, v0
	v_med3_i32 v71, v78, v77, v0
	v_med3_i32 v72, v57, v78, v0
	v_med3_i32 v57, v79, v57, v0
	v_max_i32_e32 v0, v79, v0
	v_ashrrev_i32_e32 v61, 31, v3
	v_med3_i32 v58, v59, v58, v1
	v_med3_i32 v59, v60, v59, v1
	v_med3_i32 v60, v62, v60, v1
	v_med3_i32 v62, v63, v62, v1
	v_med3_i32 v63, v64, v63, v1
	v_med3_i32 v64, v65, v64, v1
	v_med3_i32 v65, v66, v65, v1
	v_med3_i32 v66, v67, v66, v1
	v_med3_i32 v67, v68, v67, v1
	v_med3_i32 v68, v69, v68, v1
	v_med3_i32 v69, v70, v69, v1
	v_med3_i32 v70, v71, v70, v1
	v_med3_i32 v71, v72, v71, v1
	v_med3_i32 v72, v57, v72, v1
	v_med3_i32 v57, v0, v57, v1
	v_max_i32_e32 v0, v0, v1
	v_and_b32_e32 v61, 0x7fffff80, v61
	v_med3_i32 v1, v59, v58, v2
	v_med3_i32 v58, v60, v59, v2
	v_med3_i32 v59, v62, v60, v2
	v_med3_i32 v60, v63, v62, v2
	v_med3_i32 v62, v64, v63, v2
	v_med3_i32 v63, v65, v64, v2
	v_med3_i32 v64, v66, v65, v2
	v_med3_i32 v65, v67, v66, v2
	v_med3_i32 v66, v68, v67, v2
	v_med3_i32 v67, v69, v68, v2
	v_med3_i32 v68, v70, v69, v2
	v_med3_i32 v69, v71, v70, v2
	v_med3_i32 v70, v72, v71, v2
	v_med3_i32 v71, v57, v72, v2
	v_med3_i32 v57, v0, v57, v2
	v_max_i32_e32 v0, v0, v2
	v_and_b32_e32 v2, 0xffffff80, v3
	v_bitop3_b32 v2, v61, 35, v2 bitop3:0xde
	v_med3_i32 v3, v58, v1, v2
	v_med3_i32 v58, v59, v58, v2
	v_med3_i32 v59, v60, v59, v2
; DI int med3i(int a, int b, int c) { int r; asm("v_med3_i32 %0, %1, %2, %3" : "=v"(r) : "v"(a), "v"(b), "v"(c)); return r; }
; DI void insert16(int (&L)[16], int x) {
; #pragma unroll
;   for (int j = 15; j >= 1; --j) L[j] = med3i(L[j - 1], L[j], x);
;   L[0] = max(L[0], x);
; }
; DI int f2sort(float f) { int b = __float_as_int(f); return b ^ ((b >> 31) & 0x7fffffff); }
; DI void p5a_half(const bf16x8 (&qf)[8], const u16* __restrict__ pk, float rs, int (&Lh)[16], u16* smem, int tid, int r, int h) {
;     ...
; #pragma unroll
;     for (int i = 0; i < 16; ++i) {
;       const int keyc = kt * 32 + (i & 3) + 8 * (i >> 2);
;       int sb = (f2sort(Y[i] * rs) & ~127) | keyc;
;       insert16(Lh, sb);
;     }
;     __builtin_amdgcn_sched_barrier(0);
	v_med3_i32 v60, v62, v60, v2
	v_med3_i32 v61, v63, v62, v2
	v_med3_i32 v62, v64, v63, v2
	v_med3_i32 v63, v65, v64, v2
	v_med3_i32 v64, v66, v65, v2
	v_med3_i32 v65, v67, v66, v2
	v_med3_i32 v66, v68, v67, v2
	v_med3_i32 v67, v69, v68, v2
	v_med3_i32 v68, v70, v69, v2
	v_med3_i32 v69, v71, v70, v2
	v_med3_i32 v70, v57, v71, v2
	v_med3_i32 v57, v0, v57, v2
	v_max_i32_e32 v2, v0, v2
	v_pk_mul_f32 v[0:1], v[4:5], s[26:27] op_sel_hi:[1,0]
	s_nop 0
	v_ashrrev_i32_e32 v4, 31, v0
	v_and_b32_e32 v4, 0x7fffff80, v4
	v_and_b32_e32 v0, 0xffffff80, v0
	v_bitop3_b32 v0, v4, 40, v0 bitop3:0xde
	v_med3_i32 v3, v58, v3, v0
	v_med3_i32 v4, v59, v58, v0
	v_med3_i32 v5, v60, v59, v0
	v_med3_i32 v58, v61, v60, v0
	v_med3_i32 v59, v62, v61, v0
	v_med3_i32 v60, v63, v62, v0
	v_med3_i32 v61, v64, v63, v0
	v_med3_i32 v62, v65, v64, v0
	v_med3_i32 v63, v66, v65, v0
	v_med3_i32 v64, v67, v66, v0
	v_med3_i32 v65, v68, v67, v0
	v_med3_i32 v66, v69, v68, v0
	v_med3_i32 v67, v70, v69, v0
	v_med3_i32 v68, v57, v70, v0
	v_med3_i32 v57, v2, v57, v0
	v_max_i32_e32 v0, v2, v0
	v_ashrrev_i32_e32 v2, 31, v1
	v_and_b32_e32 v2, 0x7fffff80, v2
	v_and_b32_e32 v1, 0xffffff80, v1
	v_bitop3_b32 v1, v2, 41, v1 bitop3:0xde
	v_med3_i32 v2, v4, v3, v1
	v_med3_i32 v3, v5, v4, v1
	v_med3_i32 v4, v58, v5, v1
	v_med3_i32 v5, v59, v58, v1
	v_med3_i32 v58, v60, v59, v1
	v_med3_i32 v59, v61, v60, v1
	v_med3_i32 v60, v62, v61, v1
	v_med3_i32 v61, v63, v62, v1
	v_med3_i32 v62, v64, v63, v1
	v_med3_i32 v63, v65, v64, v1
	v_med3_i32 v64, v66, v65, v1
	v_med3_i32 v65, v67, v66, v1
	v_med3_i32 v66, v68, v67, v1
	v_med3_i32 v67, v57, v68, v1
	v_med3_i32 v57, v0, v57, v1
	v_max_i32_e32 v68, v0, v1
	v_pk_mul_f32 v[0:1], v[6:7], s[26:27] op_sel_hi:[1,0]
	s_nop 0
	v_ashrrev_i32_e32 v6, 31, v0
	v_and_b32_e32 v6, 0x7fffff80, v6
	v_and_b32_e32 v0, 0xffffff80, v0
	v_bitop3_b32 v0, v6, 42, v0 bitop3:0xde
	v_med3_i32 v2, v3, v2, v0
	v_med3_i32 v3, v4, v3, v0
	v_med3_i32 v4, v5, v4, v0
	v_med3_i32 v5, v58, v5, v0
	v_med3_i32 v6, v59, v58, v0
	v_med3_i32 v7, v60, v59, v0
	v_med3_i32 v58, v61, v60, v0
	v_med3_i32 v59, v62, v61, v0
	v_med3_i32 v60, v63, v62, v0
	v_med3_i32 v61, v64, v63, v0
	v_med3_i32 v62, v65, v64, v0
	v_med3_i32 v63, v66, v65, v0
	v_med3_i32 v64, v67, v66, v0
	v_ashrrev_i32_e32 v66, 31, v1
	v_and_b32_e32 v66, 0x7fffff80, v66
	v_and_b32_e32 v1, 0xffffff80, v1
	v_med3_i32 v65, v57, v67, v0
	v_med3_i32 v57, v68, v57, v0
	v_max_i32_e32 v0, v68, v0
	v_bitop3_b32 v1, v66, 43, v1 bitop3:0xde
	v_med3_i32 v2, v3, v2, v1
	v_med3_i32 v3, v4, v3, v1
	v_med3_i32 v4, v5, v4, v1
	v_med3_i32 v5, v6, v5, v1
	v_med3_i32 v6, v7, v6, v1
	v_med3_i32 v7, v58, v7, v1
	v_med3_i32 v58, v59, v58, v1
	v_med3_i32 v59, v60, v59, v1
	v_med3_i32 v60, v61, v60, v1
	v_med3_i32 v61, v62, v61, v1
	v_med3_i32 v62, v63, v62, v1
	v_med3_i32 v63, v64, v63, v1
	v_med3_i32 v64, v65, v64, v1
	v_med3_i32 v65, v57, v65, v1
	v_med3_i32 v57, v0, v57, v1
	v_max_i32_e32 v66, v0, v1
	v_pk_mul_f32 v[0:1], v[8:9], s[26:27] op_sel_hi:[1,0]
	s_nop 0
	v_ashrrev_i32_e32 v8, 31, v0
	v_and_b32_e32 v8, 0x7fffff80, v8
	v_and_b32_e32 v0, 0xffffff80, v0
	v_bitop3_b32 v0, v8, 48, v0 bitop3:0xde
	v_med3_i32 v2, v3, v2, v0
	v_med3_i32 v3, v4, v3, v0
	v_med3_i32 v4, v5, v4, v0
	v_med3_i32 v5, v6, v5, v0
	v_med3_i32 v6, v7, v6, v0
	v_med3_i32 v7, v58, v7, v0
	v_med3_i32 v8, v59, v58, v0
	v_med3_i32 v9, v60, v59, v0
	v_med3_i32 v58, v61, v60, v0
	v_med3_i32 v59, v62, v61, v0
	v_med3_i32 v60, v63, v62, v0
	v_med3_i32 v61, v64, v63, v0
	v_med3_i32 v62, v65, v64, v0
	v_ashrrev_i32_e32 v64, 31, v1
	v_and_b32_e32 v64, 0x7fffff80, v64
	v_and_b32_e32 v1, 0xffffff80, v1
	v_med3_i32 v63, v57, v65, v0
	v_med3_i32 v57, v66, v57, v0
	v_max_i32_e32 v0, v66, v0
	v_bitop3_b32 v1, v64, 49, v1 bitop3:0xde
	v_med3_i32 v2, v3, v2, v1
	v_med3_i32 v3, v4, v3, v1
	v_med3_i32 v4, v5, v4, v1
	v_med3_i32 v5, v6, v5, v1
	v_med3_i32 v6, v7, v6, v1
	v_med3_i32 v7, v8, v7, v1
	v_med3_i32 v8, v9, v8, v1
	v_med3_i32 v9, v58, v9, v1
	v_med3_i32 v58, v59, v58, v1
	v_med3_i32 v59, v60, v59, v1
	v_med3_i32 v60, v61, v60, v1
	v_med3_i32 v61, v62, v61, v1
	v_med3_i32 v62, v63, v62, v1
	v_med3_i32 v63, v57, v63, v1
	v_med3_i32 v57, v0, v57, v1
	v_max_i32_e32 v64, v0, v1
	v_pk_mul_f32 v[0:1], v[10:11], s[26:27] op_sel_hi:[1,0]
	s_nop 0
	v_ashrrev_i32_e32 v10, 31, v0
	v_and_b32_e32 v10, 0x7fffff80, v10
	v_and_b32_e32 v0, 0xffffff80, v0
	v_bitop3_b32 v0, v10, 50, v0 bitop3:0xde
	v_med3_i32 v2, v3, v2, v0
	v_med3_i32 v3, v4, v3, v0
	v_med3_i32 v4, v5, v4, v0
	v_med3_i32 v5, v6, v5, v0
	v_med3_i32 v6, v7, v6, v0
	v_med3_i32 v7, v8, v7, v0
	v_med3_i32 v8, v9, v8, v0
	v_med3_i32 v9, v58, v9, v0
	v_med3_i32 v10, v59, v58, v0
	v_med3_i32 v11, v60, v59, v0
	v_med3_i32 v58, v61, v60, v0
	v_med3_i32 v59, v62, v61, v0
	v_med3_i32 v60, v63, v62, v0
	v_ashrrev_i32_e32 v62, 31, v1
	v_and_b32_e32 v62, 0x7fffff80, v62
	v_and_b32_e32 v1, 0xffffff80, v1
	v_med3_i32 v61, v57, v63, v0
	v_med3_i32 v57, v64, v57, v0
	v_max_i32_e32 v0, v64, v0
	v_bitop3_b32 v1, v62, 51, v1 bitop3:0xde
	v_med3_i32 v2, v3, v2, v1
	v_med3_i32 v3, v4, v3, v1
	v_med3_i32 v4, v5, v4, v1
	v_med3_i32 v5, v6, v5, v1
	v_med3_i32 v6, v7, v6, v1
	v_med3_i32 v7, v8, v7, v1
	v_med3_i32 v8, v9, v8, v1
	v_med3_i32 v9, v10, v9, v1
	v_med3_i32 v10, v11, v10, v1
	v_med3_i32 v11, v58, v11, v1
	v_med3_i32 v58, v59, v58, v1
	v_med3_i32 v59, v60, v59, v1
	v_med3_i32 v60, v61, v60, v1
	v_med3_i32 v61, v57, v61, v1
	v_med3_i32 v57, v0, v57, v1
	v_max_i32_e32 v62, v0, v1
	v_pk_mul_f32 v[0:1], v[12:13], s[26:27] op_sel_hi:[1,0]
	s_nop 0
	v_ashrrev_i32_e32 v12, 31, v0
	v_and_b32_e32 v12, 0x7fffff80, v12
	v_and_b32_e32 v0, 0xffffff80, v0
	v_bitop3_b32 v0, v12, 56, v0 bitop3:0xde
; #define MFMA32(a, b, c) __builtin_amdgcn_mfma_f32_32x32x16_bf16((a), (b), (c), 0, 0, 0)
; DI int med3i(int a, int b, int c) { int r; asm("v_med3_i32 %0, %1, %2, %3" : "=v"(r) : "v"(a), "v"(b), "v"(c)); return r; }
; DI void insert16(int (&L)[16], int x) {
; #pragma unroll
;   for (int j = 15; j >= 1; --j) L[j] = med3i(L[j - 1], L[j], x);
;   L[0] = max(L[0], x);
; }
; DI int f2sort(float f) { int b = __float_as_int(f); return b ^ ((b >> 31) & 0x7fffffff); }
; DI void p5a_half(const bf16x8 (&qf)[8], const u16* __restrict__ pk, float rs, int (&Lh)[16], u16* smem, int tid, int r, int h) {
;     ...
;   for (int kt = 0; kt < 4; ++kt) {
;     f32x16 Y = zero16();
; #pragma unroll
;     for (int ks = 0; ks < 8; ++ks) {
;       const int m = ks >> 1, s = ks & 1;
;       const u16* pp = smem + (kt * 32 + r) * LPK + 32 * m + 16 * s + 4 * h;
;       s16x4 lo = *(const s16x4*)pp;
;       s16x4 hi = *(const s16x4*)(pp + 8);
;       bf16x8 a = __builtin_shufflevector(lo, hi, 0, 1, 2, 3, 4, 5, 6, 7);
;       Y = MFMA32(a, qf[ks], Y);
;     }
; #pragma unroll
;     for (int i = 0; i < 16; ++i) {
;       const int keyc = kt * 32 + (i & 3) + 8 * (i >> 2);
;       int sb = (f2sort(Y[i] * rs) & ~127) | keyc;
;       insert16(Lh, sb);
;     }
;     __builtin_amdgcn_sched_barrier(0);
	v_med3_i32 v2, v3, v2, v0
	v_med3_i32 v3, v4, v3, v0
	v_med3_i32 v4, v5, v4, v0
	v_med3_i32 v5, v6, v5, v0
	v_med3_i32 v6, v7, v6, v0
	v_med3_i32 v7, v8, v7, v0
	v_med3_i32 v8, v9, v8, v0
	v_med3_i32 v9, v10, v9, v0
	v_med3_i32 v10, v11, v10, v0
	v_med3_i32 v11, v58, v11, v0
	v_med3_i32 v12, v59, v58, v0
	v_med3_i32 v13, v60, v59, v0
	v_med3_i32 v58, v61, v60, v0
	v_ashrrev_i32_e32 v60, 31, v1
	v_and_b32_e32 v60, 0x7fffff80, v60
	v_and_b32_e32 v1, 0xffffff80, v1
	v_med3_i32 v59, v57, v61, v0
	v_med3_i32 v57, v62, v57, v0
	v_max_i32_e32 v0, v62, v0
	v_bitop3_b32 v1, v60, 57, v1 bitop3:0xde
	v_med3_i32 v2, v3, v2, v1
	v_med3_i32 v3, v4, v3, v1
	v_med3_i32 v4, v5, v4, v1
	v_med3_i32 v5, v6, v5, v1
	v_med3_i32 v6, v7, v6, v1
	v_med3_i32 v7, v8, v7, v1
	v_med3_i32 v8, v9, v8, v1
	v_med3_i32 v9, v10, v9, v1
	v_med3_i32 v10, v11, v10, v1
	v_med3_i32 v11, v12, v11, v1
	v_med3_i32 v12, v13, v12, v1
	v_med3_i32 v13, v58, v13, v1
	v_med3_i32 v58, v59, v58, v1
	v_med3_i32 v59, v57, v59, v1
	v_med3_i32 v57, v0, v57, v1
	v_max_i32_e32 v60, v0, v1
	v_pk_mul_f32 v[0:1], v[14:15], s[26:27] op_sel_hi:[1,0]
	s_nop 0
	v_ashrrev_i32_e32 v14, 31, v0
	v_and_b32_e32 v14, 0x7fffff80, v14
	v_and_b32_e32 v0, 0xffffff80, v0
	v_bitop3_b32 v0, v14, 58, v0 bitop3:0xde
	v_med3_i32 v2, v3, v2, v0
	v_med3_i32 v3, v4, v3, v0
	v_med3_i32 v4, v5, v4, v0
	v_med3_i32 v5, v6, v5, v0
	v_med3_i32 v6, v7, v6, v0
	v_med3_i32 v7, v8, v7, v0
	v_med3_i32 v8, v9, v8, v0
	v_med3_i32 v9, v10, v9, v0
	v_med3_i32 v10, v11, v10, v0
	v_med3_i32 v11, v12, v11, v0
	v_med3_i32 v12, v13, v12, v0
	v_med3_i32 v13, v58, v13, v0
	v_med3_i32 v14, v59, v58, v0
	v_ashrrev_i32_e32 v58, 31, v1
	v_and_b32_e32 v58, 0x7fffff80, v58
	v_and_b32_e32 v1, 0xffffff80, v1
	v_med3_i32 v15, v57, v59, v0
	v_med3_i32 v57, v60, v57, v0
	v_max_i32_e32 v0, v60, v0
	v_bitop3_b32 v1, v58, 59, v1 bitop3:0xde
	v_med3_i32 v62, v3, v2, v1
	v_med3_i32 v63, v4, v3, v1
	v_med3_i32 v64, v5, v4, v1
	v_med3_i32 v65, v6, v5, v1
	v_med3_i32 v66, v7, v6, v1
	v_med3_i32 v67, v8, v7, v1
	v_med3_i32 v68, v9, v8, v1
	v_med3_i32 v69, v10, v9, v1
	v_med3_i32 v70, v11, v10, v1
	v_med3_i32 v71, v12, v11, v1
	v_med3_i32 v72, v13, v12, v1
	v_med3_i32 v75, v14, v13, v1
	v_med3_i32 v76, v15, v14, v1
	v_med3_i32 v77, v57, v15, v1
	v_med3_i32 v57, v0, v57, v1
	v_max_i32_e32 v78, v0, v1
	ds_read2_b64 v[0:3], v73 offset0:64 offset1:66
	ds_read2_b64 v[58:61], v73 offset0:68 offset1:70
	s_waitcnt lgkmcnt(1)
	v_mfma_f32_32x32x16_bf16 v[0:15], v[0:3], v[80:83], 0
	s_waitcnt lgkmcnt(0)
	v_mfma_f32_32x32x16_bf16 v[0:15], v[58:61], v[84:87], v[0:15]
	ds_read2_b64 v[58:61], v73 offset0:72 offset1:74
	s_waitcnt lgkmcnt(0)
	v_mfma_f32_32x32x16_bf16 v[0:15], v[58:61], v[52:55], v[0:15]
	ds_read2_b64 v[58:61], v73 offset0:76 offset1:78
	s_waitcnt lgkmcnt(0)
	v_mfma_f32_32x32x16_bf16 v[0:15], v[58:61], v[48:51], v[0:15]
	ds_read2_b64 v[58:61], v73 offset0:80 offset1:82
	s_waitcnt lgkmcnt(0)
	v_mfma_f32_32x32x16_bf16 v[0:15], v[58:61], v[20:23], v[0:15]
	ds_read2_b64 v[58:61], v73 offset0:84 offset1:86
	s_waitcnt lgkmcnt(0)
	v_mfma_f32_32x32x16_bf16 v[0:15], v[58:61], v[16:19], v[0:15]
	ds_read2_b64 v[58:61], v73 offset0:88 offset1:90
	s_waitcnt lgkmcnt(0)
	v_mfma_f32_32x32x16_bf16 v[0:15], v[58:61], v[28:31], v[0:15]
	ds_read2_b64 v[58:61], v73 offset0:92 offset1:94
	s_waitcnt lgkmcnt(0)
	v_mfma_f32_32x32x16_bf16 v[0:15], v[58:61], v[24:27], v[0:15]
	s_nop 11
	v_pk_mul_f32 v[0:1], v[0:1], s[26:27] op_sel_hi:[1,0]
	v_pk_mul_f32 v[2:3], v[2:3], s[26:27] op_sel_hi:[1,0]
	v_ashrrev_i32_e32 v58, 31, v0
	v_and_b32_e32 v0, 0xffffff80, v0
	v_ashrrev_i32_e32 v59, 31, v1
	v_ashrrev_i32_e32 v60, 31, v2
	v_and_b32_e32 v58, 0x7fffff80, v58
	v_and_b32_e32 v1, 0xffffff80, v1
	v_and_b32_e32 v2, 0xffffff80, v2
	v_and_b32_e32 v59, 0x7fffff80, v59
	v_and_b32_e32 v60, 0x7fffff80, v60
	v_bitop3_b32 v0, v58, 64, v0 bitop3:0xde
	v_bitop3_b32 v1, v59, s38, v1 bitop3:0xde
	v_bitop3_b32 v2, v60, s39, v2 bitop3:0xde
	v_med3_i32 v58, v63, v62, v0
	v_med3_i32 v59, v64, v63, v0
	v_med3_i32 v60, v65, v64, v0
	v_med3_i32 v62, v66, v65, v0
	v_med3_i32 v63, v67, v66, v0
	v_med3_i32 v64, v68, v67, v0
	v_med3_i32 v65, v69, v68, v0
	v_med3_i32 v66, v70, v69, v0
	v_med3_i32 v67, v71, v70, v0
	v_med3_i32 v68, v72, v71, v0
	v_med3_i32 v69, v75, v72, v0
	v_med3_i32 v70, v76, v75, v0
	v_med3_i32 v71, v77, v76, v0
	v_med3_i32 v72, v57, v77, v0
	v_med3_i32 v57, v78, v57, v0
	v_max_i32_e32 v0, v78, v0
	v_ashrrev_i32_e32 v61, 31, v3
	v_med3_i32 v58, v59, v58, v1
	v_med3_i32 v59, v60, v59, v1
	v_med3_i32 v60, v62, v60, v1
	v_med3_i32 v62, v63, v62, v1
	v_med3_i32 v63, v64, v63, v1
	v_med3_i32 v64, v65, v64, v1
	v_med3_i32 v65, v66, v65, v1
	v_med3_i32 v66, v67, v66, v1
	v_med3_i32 v67, v68, v67, v1
	v_med3_i32 v68, v69, v68, v1
	v_med3_i32 v69, v70, v69, v1
	v_med3_i32 v70, v71, v70, v1
	v_med3_i32 v71, v72, v71, v1
	v_med3_i32 v72, v57, v72, v1
	v_med3_i32 v57, v0, v57, v1
	v_max_i32_e32 v0, v0, v1
	v_and_b32_e32 v61, 0x7fffff80, v61
	v_med3_i32 v1, v59, v58, v2
	v_med3_i32 v58, v60, v59, v2
	v_med3_i32 v59, v62, v60, v2
	v_med3_i32 v60, v63, v62, v2
	v_med3_i32 v62, v64, v63, v2
	v_med3_i32 v63, v65, v64, v2
	v_med3_i32 v64, v66, v65, v2
	v_med3_i32 v65, v67, v66, v2
	v_med3_i32 v66, v68, v67, v2
	v_med3_i32 v67, v69, v68, v2
	v_med3_i32 v68, v70, v69, v2
	v_med3_i32 v69, v71, v70, v2
	v_med3_i32 v70, v72, v71, v2
	v_med3_i32 v71, v57, v72, v2
	v_med3_i32 v57, v0, v57, v2
	v_max_i32_e32 v0, v0, v2
	v_and_b32_e32 v2, 0xffffff80, v3
	v_bitop3_b32 v2, v61, s40, v2 bitop3:0xde
	v_med3_i32 v3, v58, v1, v2
	v_med3_i32 v58, v59, v58, v2
	v_med3_i32 v59, v60, v59, v2
	v_med3_i32 v60, v62, v60, v2
; DI int med3i(int a, int b, int c) { int r; asm("v_med3_i32 %0, %1, %2, %3" : "=v"(r) : "v"(a), "v"(b), "v"(c)); return r; }
; DI void insert16(int (&L)[16], int x) {
; #pragma unroll
;   for (int j = 15; j >= 1; --j) L[j] = med3i(L[j - 1], L[j], x);
;   L[0] = max(L[0], x);
; }
; DI int f2sort(float f) { int b = __float_as_int(f); return b ^ ((b >> 31) & 0x7fffffff); }
; DI void p5a_half(const bf16x8 (&qf)[8], const u16* __restrict__ pk, float rs, int (&Lh)[16], u16* smem, int tid, int r, int h) {
;     ...
; #pragma unroll
;     for (int i = 0; i < 16; ++i) {
;       const int keyc = kt * 32 + (i & 3) + 8 * (i >> 2);
;       int sb = (f2sort(Y[i] * rs) & ~127) | keyc;
;       insert16(Lh, sb);
;     }
;     __builtin_amdgcn_sched_barrier(0);
	v_med3_i32 v61, v63, v62, v2
	v_med3_i32 v62, v64, v63, v2
	v_med3_i32 v63, v65, v64, v2
	v_med3_i32 v64, v66, v65, v2
	v_med3_i32 v65, v67, v66, v2
	v_med3_i32 v66, v68, v67, v2
	v_med3_i32 v67, v69, v68, v2
	v_med3_i32 v68, v70, v69, v2
	v_med3_i32 v69, v71, v70, v2
	v_med3_i32 v70, v57, v71, v2
	v_med3_i32 v57, v0, v57, v2
	v_max_i32_e32 v2, v0, v2
	v_pk_mul_f32 v[0:1], v[4:5], s[26:27] op_sel_hi:[1,0]
	s_nop 0
	v_ashrrev_i32_e32 v4, 31, v0
	v_and_b32_e32 v4, 0x7fffff80, v4
	v_and_b32_e32 v0, 0xffffff80, v0
	v_bitop3_b32 v0, v4, s41, v0 bitop3:0xde
	v_med3_i32 v3, v58, v3, v0
	v_med3_i32 v4, v59, v58, v0
	v_med3_i32 v5, v60, v59, v0
	v_med3_i32 v58, v61, v60, v0
	v_med3_i32 v59, v62, v61, v0
	v_med3_i32 v60, v63, v62, v0
	v_med3_i32 v61, v64, v63, v0
	v_med3_i32 v62, v65, v64, v0
	v_med3_i32 v63, v66, v65, v0
	v_med3_i32 v64, v67, v66, v0
	v_med3_i32 v65, v68, v67, v0
	v_med3_i32 v66, v69, v68, v0
	v_med3_i32 v67, v70, v69, v0
	v_med3_i32 v68, v57, v70, v0
	v_med3_i32 v57, v2, v57, v0
	v_max_i32_e32 v0, v2, v0
	v_ashrrev_i32_e32 v2, 31, v1
	v_and_b32_e32 v2, 0x7fffff80, v2
	v_and_b32_e32 v1, 0xffffff80, v1
	v_bitop3_b32 v1, v2, s42, v1 bitop3:0xde
	v_med3_i32 v2, v4, v3, v1
	v_med3_i32 v3, v5, v4, v1
	v_med3_i32 v4, v58, v5, v1
	v_med3_i32 v5, v59, v58, v1
	v_med3_i32 v58, v60, v59, v1
	v_med3_i32 v59, v61, v60, v1
	v_med3_i32 v60, v62, v61, v1
	v_med3_i32 v61, v63, v62, v1
	v_med3_i32 v62, v64, v63, v1
	v_med3_i32 v63, v65, v64, v1
	v_med3_i32 v64, v66, v65, v1
	v_med3_i32 v65, v67, v66, v1
	v_med3_i32 v66, v68, v67, v1
	v_med3_i32 v67, v57, v68, v1
	v_med3_i32 v57, v0, v57, v1
	v_max_i32_e32 v68, v0, v1
	v_pk_mul_f32 v[0:1], v[6:7], s[26:27] op_sel_hi:[1,0]
	s_nop 0
	v_ashrrev_i32_e32 v6, 31, v0
	v_and_b32_e32 v6, 0x7fffff80, v6
	v_and_b32_e32 v0, 0xffffff80, v0
	v_bitop3_b32 v0, v6, s43, v0 bitop3:0xde
	v_med3_i32 v2, v3, v2, v0
	v_med3_i32 v3, v4, v3, v0
	v_med3_i32 v4, v5, v4, v0
	v_med3_i32 v5, v58, v5, v0
	v_med3_i32 v6, v59, v58, v0
	v_med3_i32 v7, v60, v59, v0
	v_med3_i32 v58, v61, v60, v0
	v_med3_i32 v59, v62, v61, v0
	v_med3_i32 v60, v63, v62, v0
	v_med3_i32 v61, v64, v63, v0
	v_med3_i32 v62, v65, v64, v0
	v_med3_i32 v63, v66, v65, v0
	v_med3_i32 v64, v67, v66, v0
	v_ashrrev_i32_e32 v66, 31, v1
	v_and_b32_e32 v66, 0x7fffff80, v66
	v_and_b32_e32 v1, 0xffffff80, v1
	v_med3_i32 v65, v57, v67, v0
	v_med3_i32 v57, v68, v57, v0
	v_max_i32_e32 v0, v68, v0
	v_bitop3_b32 v1, v66, s44, v1 bitop3:0xde
	v_med3_i32 v2, v3, v2, v1
	v_med3_i32 v3, v4, v3, v1
	v_med3_i32 v4, v5, v4, v1
	v_med3_i32 v5, v6, v5, v1
	v_med3_i32 v6, v7, v6, v1
	v_med3_i32 v7, v58, v7, v1
	v_med3_i32 v58, v59, v58, v1
	v_med3_i32 v59, v60, v59, v1
	v_med3_i32 v60, v61, v60, v1
	v_med3_i32 v61, v62, v61, v1
	v_med3_i32 v62, v63, v62, v1
	v_med3_i32 v63, v64, v63, v1
	v_med3_i32 v64, v65, v64, v1
	v_med3_i32 v65, v57, v65, v1
	v_med3_i32 v57, v0, v57, v1
	v_max_i32_e32 v66, v0, v1
	v_pk_mul_f32 v[0:1], v[8:9], s[26:27] op_sel_hi:[1,0]
	s_nop 0
	v_ashrrev_i32_e32 v8, 31, v0
	v_and_b32_e32 v8, 0x7fffff80, v8
	v_and_b32_e32 v0, 0xffffff80, v0
	v_bitop3_b32 v0, v8, s45, v0 bitop3:0xde
	v_med3_i32 v2, v3, v2, v0
	v_med3_i32 v3, v4, v3, v0
	v_med3_i32 v4, v5, v4, v0
	v_med3_i32 v5, v6, v5, v0
	v_med3_i32 v6, v7, v6, v0
	v_med3_i32 v7, v58, v7, v0
	v_med3_i32 v8, v59, v58, v0
	v_med3_i32 v9, v60, v59, v0
	v_med3_i32 v58, v61, v60, v0
	v_med3_i32 v59, v62, v61, v0
	v_med3_i32 v60, v63, v62, v0
	v_med3_i32 v61, v64, v63, v0
	v_med3_i32 v62, v65, v64, v0
	v_ashrrev_i32_e32 v64, 31, v1
	v_and_b32_e32 v64, 0x7fffff80, v64
	v_and_b32_e32 v1, 0xffffff80, v1
	v_med3_i32 v63, v57, v65, v0
	v_med3_i32 v57, v66, v57, v0
	v_max_i32_e32 v0, v66, v0
	v_bitop3_b32 v1, v64, s46, v1 bitop3:0xde
	v_med3_i32 v2, v3, v2, v1
	v_med3_i32 v3, v4, v3, v1
	v_med3_i32 v4, v5, v4, v1
	v_med3_i32 v5, v6, v5, v1
	v_med3_i32 v6, v7, v6, v1
	v_med3_i32 v7, v8, v7, v1
	v_med3_i32 v8, v9, v8, v1
	v_med3_i32 v9, v58, v9, v1
	v_med3_i32 v58, v59, v58, v1
	v_med3_i32 v59, v60, v59, v1
	v_med3_i32 v60, v61, v60, v1
	v_med3_i32 v61, v62, v61, v1
	v_med3_i32 v62, v63, v62, v1
	v_med3_i32 v63, v57, v63, v1
	v_med3_i32 v57, v0, v57, v1
	v_max_i32_e32 v64, v0, v1
	v_pk_mul_f32 v[0:1], v[10:11], s[26:27] op_sel_hi:[1,0]
	s_nop 0
	v_ashrrev_i32_e32 v10, 31, v0
	v_and_b32_e32 v10, 0x7fffff80, v10
	v_and_b32_e32 v0, 0xffffff80, v0
	v_bitop3_b32 v0, v10, s47, v0 bitop3:0xde
	v_med3_i32 v2, v3, v2, v0
	v_med3_i32 v3, v4, v3, v0
	v_med3_i32 v4, v5, v4, v0
	v_med3_i32 v5, v6, v5, v0
	v_med3_i32 v6, v7, v6, v0
	v_med3_i32 v7, v8, v7, v0
	v_med3_i32 v8, v9, v8, v0
	v_med3_i32 v9, v58, v9, v0
	v_med3_i32 v10, v59, v58, v0
	v_med3_i32 v11, v60, v59, v0
	v_med3_i32 v58, v61, v60, v0
	v_med3_i32 v59, v62, v61, v0
	v_med3_i32 v60, v63, v62, v0
	v_ashrrev_i32_e32 v62, 31, v1
	v_and_b32_e32 v62, 0x7fffff80, v62
	v_and_b32_e32 v1, 0xffffff80, v1
	v_med3_i32 v61, v57, v63, v0
	v_med3_i32 v57, v64, v57, v0
	v_max_i32_e32 v0, v64, v0
	v_bitop3_b32 v1, v62, s48, v1 bitop3:0xde
	v_med3_i32 v2, v3, v2, v1
	v_med3_i32 v3, v4, v3, v1
	v_med3_i32 v4, v5, v4, v1
	v_med3_i32 v5, v6, v5, v1
	v_med3_i32 v6, v7, v6, v1
	v_med3_i32 v7, v8, v7, v1
	v_med3_i32 v8, v9, v8, v1
	v_med3_i32 v9, v10, v9, v1
	v_med3_i32 v10, v11, v10, v1
	v_med3_i32 v11, v58, v11, v1
	v_med3_i32 v58, v59, v58, v1
	v_med3_i32 v59, v60, v59, v1
	v_med3_i32 v60, v61, v60, v1
	v_med3_i32 v61, v57, v61, v1
	v_med3_i32 v57, v0, v57, v1
	v_max_i32_e32 v62, v0, v1
	v_pk_mul_f32 v[0:1], v[12:13], s[26:27] op_sel_hi:[1,0]
	s_nop 0
	v_ashrrev_i32_e32 v12, 31, v0
	v_and_b32_e32 v12, 0x7fffff80, v12
	v_and_b32_e32 v0, 0xffffff80, v0
	v_bitop3_b32 v0, v12, s49, v0 bitop3:0xde
; #define MFMA32(a, b, c) __builtin_amdgcn_mfma_f32_32x32x16_bf16((a), (b), (c), 0, 0, 0)
; DI int med3i(int a, int b, int c) { int r; asm("v_med3_i32 %0, %1, %2, %3" : "=v"(r) : "v"(a), "v"(b), "v"(c)); return r; }
; DI void insert16(int (&L)[16], int x) {
; #pragma unroll
;   for (int j = 15; j >= 1; --j) L[j] = med3i(L[j - 1], L[j], x);
;   L[0] = max(L[0], x);
; }
; DI int f2sort(float f) { int b = __float_as_int(f); return b ^ ((b >> 31) & 0x7fffffff); }
; DI void p5a_half(const bf16x8 (&qf)[8], const u16* __restrict__ pk, float rs, int (&Lh)[16], u16* smem, int tid, int r, int h) {
;     ...
;   for (int kt = 0; kt < 4; ++kt) {
;     f32x16 Y = zero16();
; #pragma unroll
;     for (int ks = 0; ks < 8; ++ks) {
;       const int m = ks >> 1, s = ks & 1;
;       const u16* pp = smem + (kt * 32 + r) * LPK + 32 * m + 16 * s + 4 * h;
;       s16x4 lo = *(const s16x4*)pp;
;       s16x4 hi = *(const s16x4*)(pp + 8);
;       bf16x8 a = __builtin_shufflevector(lo, hi, 0, 1, 2, 3, 4, 5, 6, 7);
;       Y = MFMA32(a, qf[ks], Y);
;     }
; #pragma unroll
;     for (int i = 0; i < 16; ++i) {
;       const int keyc = kt * 32 + (i & 3) + 8 * (i >> 2);
;       int sb = (f2sort(Y[i] * rs) & ~127) | keyc;
;       insert16(Lh, sb);
;     }
;     __builtin_amdgcn_sched_barrier(0);
	v_med3_i32 v2, v3, v2, v0
	v_med3_i32 v3, v4, v3, v0
	v_med3_i32 v4, v5, v4, v0
	v_med3_i32 v5, v6, v5, v0
	v_med3_i32 v6, v7, v6, v0
	v_med3_i32 v7, v8, v7, v0
	v_med3_i32 v8, v9, v8, v0
	v_med3_i32 v9, v10, v9, v0
	v_med3_i32 v10, v11, v10, v0
	v_med3_i32 v11, v58, v11, v0
	v_med3_i32 v12, v59, v58, v0
	v_med3_i32 v13, v60, v59, v0
	v_med3_i32 v58, v61, v60, v0
	v_ashrrev_i32_e32 v60, 31, v1
	v_and_b32_e32 v60, 0x7fffff80, v60
	v_and_b32_e32 v1, 0xffffff80, v1
	v_med3_i32 v59, v57, v61, v0
	v_med3_i32 v57, v62, v57, v0
	v_max_i32_e32 v0, v62, v0
	v_bitop3_b32 v1, v60, s50, v1 bitop3:0xde
	v_med3_i32 v2, v3, v2, v1
	v_med3_i32 v3, v4, v3, v1
	v_med3_i32 v4, v5, v4, v1
	v_med3_i32 v5, v6, v5, v1
	v_med3_i32 v6, v7, v6, v1
	v_med3_i32 v7, v8, v7, v1
	v_med3_i32 v8, v9, v8, v1
	v_med3_i32 v9, v10, v9, v1
	v_med3_i32 v10, v11, v10, v1
	v_med3_i32 v11, v12, v11, v1
	v_med3_i32 v12, v13, v12, v1
	v_med3_i32 v13, v58, v13, v1
	v_med3_i32 v58, v59, v58, v1
	v_med3_i32 v59, v57, v59, v1
	v_med3_i32 v57, v0, v57, v1
	v_max_i32_e32 v60, v0, v1
	v_pk_mul_f32 v[0:1], v[14:15], s[26:27] op_sel_hi:[1,0]
	s_nop 0
	v_ashrrev_i32_e32 v14, 31, v0
	v_and_b32_e32 v14, 0x7fffff80, v14
	v_and_b32_e32 v0, 0xffffff80, v0
	v_bitop3_b32 v0, v14, s51, v0 bitop3:0xde
	v_med3_i32 v2, v3, v2, v0
	v_med3_i32 v3, v4, v3, v0
	v_med3_i32 v4, v5, v4, v0
	v_med3_i32 v5, v6, v5, v0
	v_med3_i32 v6, v7, v6, v0
	v_med3_i32 v7, v8, v7, v0
	v_med3_i32 v8, v9, v8, v0
	v_med3_i32 v9, v10, v9, v0
	v_med3_i32 v10, v11, v10, v0
	v_med3_i32 v11, v12, v11, v0
	v_med3_i32 v12, v13, v12, v0
	v_med3_i32 v13, v58, v13, v0
	v_med3_i32 v14, v59, v58, v0
	v_ashrrev_i32_e32 v58, 31, v1
	v_and_b32_e32 v58, 0x7fffff80, v58
	v_and_b32_e32 v1, 0xffffff80, v1
	v_med3_i32 v15, v57, v59, v0
	v_med3_i32 v57, v60, v57, v0
	v_max_i32_e32 v0, v60, v0
	v_bitop3_b32 v1, v58, s52, v1 bitop3:0xde
	v_med3_i32 v62, v3, v2, v1
	v_med3_i32 v63, v4, v3, v1
	v_med3_i32 v64, v5, v4, v1
	v_med3_i32 v65, v6, v5, v1
	v_med3_i32 v66, v7, v6, v1
	v_med3_i32 v67, v8, v7, v1
	v_med3_i32 v68, v9, v8, v1
	v_med3_i32 v69, v10, v9, v1
	v_med3_i32 v70, v11, v10, v1
	v_med3_i32 v71, v12, v11, v1
	v_med3_i32 v72, v13, v12, v1
	v_med3_i32 v73, v14, v13, v1
	v_med3_i32 v75, v15, v14, v1
	v_med3_i32 v76, v57, v15, v1
	v_med3_i32 v57, v0, v57, v1
	v_max_i32_e32 v77, v0, v1
	ds_read2_b64 v[0:3], v74 offset0:96 offset1:98
	ds_read2_b64 v[58:61], v74 offset0:100 offset1:102
	s_waitcnt lgkmcnt(1)
	v_mfma_f32_32x32x16_bf16 v[0:15], v[0:3], v[80:83], 0
	s_waitcnt lgkmcnt(0)
	v_mfma_f32_32x32x16_bf16 v[0:15], v[58:61], v[84:87], v[0:15]
	ds_read2_b64 v[58:61], v74 offset0:104 offset1:106
	s_waitcnt lgkmcnt(0)
	v_mfma_f32_32x32x16_bf16 v[0:15], v[58:61], v[52:55], v[0:15]
	ds_read2_b64 v[52:55], v74 offset0:108 offset1:110
	s_waitcnt lgkmcnt(0)
	v_mfma_f32_32x32x16_bf16 v[0:15], v[52:55], v[48:51], v[0:15]
	ds_read2_b64 v[48:51], v74 offset0:112 offset1:114
	s_waitcnt lgkmcnt(0)
	v_mfma_f32_32x32x16_bf16 v[0:15], v[48:51], v[20:23], v[0:15]
	ds_read2_b64 v[20:23], v74 offset0:116 offset1:118
	s_waitcnt lgkmcnt(0)
	v_mfma_f32_32x32x16_bf16 v[0:15], v[20:23], v[16:19], v[0:15]
	ds_read2_b64 v[16:19], v74 offset0:120 offset1:122
	s_waitcnt lgkmcnt(0)
	v_mfma_f32_32x32x16_bf16 v[0:15], v[16:19], v[28:31], v[0:15]
	ds_read2_b64 v[16:19], v74 offset0:124 offset1:126
	s_waitcnt lgkmcnt(0)
	v_mfma_f32_32x32x16_bf16 v[0:15], v[16:19], v[24:27], v[0:15]
	s_nop 11
	v_pk_mul_f32 v[0:1], v[0:1], s[26:27] op_sel_hi:[1,0]
	v_pk_mul_f32 v[2:3], v[2:3], s[26:27] op_sel_hi:[1,0]
	v_ashrrev_i32_e32 v16, 31, v0
	v_and_b32_e32 v0, 0xffffff80, v0
	v_ashrrev_i32_e32 v17, 31, v1
	v_ashrrev_i32_e32 v18, 31, v2
	v_and_b32_e32 v16, 0x7fffff80, v16
	v_and_b32_e32 v1, 0xffffff80, v1
	v_and_b32_e32 v2, 0xffffff80, v2
	v_and_b32_e32 v17, 0x7fffff80, v17
	v_and_b32_e32 v18, 0x7fffff80, v18
	v_bitop3_b32 v0, v16, s53, v0 bitop3:0xde
	v_bitop3_b32 v1, v17, s56, v1 bitop3:0xde
	v_bitop3_b32 v2, v18, s57, v2 bitop3:0xde
	v_med3_i32 v16, v63, v62, v0
	v_med3_i32 v17, v64, v63, v0
	v_med3_i32 v18, v65, v64, v0
	v_med3_i32 v20, v66, v65, v0
	v_med3_i32 v21, v67, v66, v0
	v_med3_i32 v22, v68, v67, v0
	v_med3_i32 v23, v69, v68, v0
	v_med3_i32 v24, v70, v69, v0
	v_med3_i32 v25, v71, v70, v0
	v_med3_i32 v26, v72, v71, v0
	v_med3_i32 v27, v73, v72, v0
	v_med3_i32 v28, v75, v73, v0
	v_med3_i32 v29, v76, v75, v0
	v_med3_i32 v30, v57, v76, v0
	v_med3_i32 v31, v77, v57, v0
	v_max_i32_e32 v0, v77, v0
	v_ashrrev_i32_e32 v19, 31, v3
	v_med3_i32 v16, v17, v16, v1
	v_med3_i32 v17, v18, v17, v1
	v_med3_i32 v18, v20, v18, v1
	v_med3_i32 v20, v21, v20, v1
	v_med3_i32 v21, v22, v21, v1
	v_med3_i32 v22, v23, v22, v1
	v_med3_i32 v23, v24, v23, v1
	v_med3_i32 v24, v25, v24, v1
	v_med3_i32 v25, v26, v25, v1
	v_med3_i32 v26, v27, v26, v1
	v_med3_i32 v27, v28, v27, v1
	v_med3_i32 v28, v29, v28, v1
	v_med3_i32 v29, v30, v29, v1
	v_med3_i32 v30, v31, v30, v1
	v_med3_i32 v31, v0, v31, v1
	v_max_i32_e32 v0, v0, v1
	v_and_b32_e32 v19, 0x7fffff80, v19
	v_med3_i32 v1, v17, v16, v2
	v_med3_i32 v16, v18, v17, v2
	v_med3_i32 v17, v20, v18, v2
	v_med3_i32 v18, v21, v20, v2
	v_med3_i32 v20, v22, v21, v2
	v_med3_i32 v21, v23, v22, v2
	v_med3_i32 v22, v24, v23, v2
	v_med3_i32 v23, v25, v24, v2
	v_med3_i32 v24, v26, v25, v2
	v_med3_i32 v25, v27, v26, v2
	v_med3_i32 v26, v28, v27, v2
	v_med3_i32 v27, v29, v28, v2
	v_med3_i32 v28, v30, v29, v2
	v_med3_i32 v29, v31, v30, v2
	v_med3_i32 v30, v0, v31, v2
	v_max_i32_e32 v0, v0, v2
	v_and_b32_e32 v2, 0xffffff80, v3
	v_bitop3_b32 v2, v19, s58, v2 bitop3:0xde
	v_med3_i32 v3, v16, v1, v2
	v_med3_i32 v16, v17, v16, v2
	v_med3_i32 v17, v18, v17, v2
	v_med3_i32 v18, v20, v18, v2
; DI int med3i(int a, int b, int c) { int r; asm("v_med3_i32 %0, %1, %2, %3" : "=v"(r) : "v"(a), "v"(b), "v"(c)); return r; }
; DI void insert16(int (&L)[16], int x) {
; #pragma unroll
;   for (int j = 15; j >= 1; --j) L[j] = med3i(L[j - 1], L[j], x);
;   L[0] = max(L[0], x);
; }
; DI int f2sort(float f) { int b = __float_as_int(f); return b ^ ((b >> 31) & 0x7fffffff); }
; DI void p5a_half(const bf16x8 (&qf)[8], const u16* __restrict__ pk, float rs, int (&Lh)[16], u16* smem, int tid, int r, int h) {
;     ...
; #pragma unroll
;     for (int i = 0; i < 16; ++i) {
;       const int keyc = kt * 32 + (i & 3) + 8 * (i >> 2);
;       int sb = (f2sort(Y[i] * rs) & ~127) | keyc;
;       insert16(Lh, sb);
;     }
;     __builtin_amdgcn_sched_barrier(0);
	v_med3_i32 v19, v21, v20, v2
	v_med3_i32 v20, v22, v21, v2
	v_med3_i32 v21, v23, v22, v2
	v_med3_i32 v22, v24, v23, v2
	v_med3_i32 v23, v25, v24, v2
	v_med3_i32 v24, v26, v25, v2
	v_med3_i32 v25, v27, v26, v2
	v_med3_i32 v26, v28, v27, v2
	v_med3_i32 v27, v29, v28, v2
	v_med3_i32 v28, v30, v29, v2
	v_med3_i32 v29, v0, v30, v2
	v_max_i32_e32 v2, v0, v2
	v_pk_mul_f32 v[0:1], v[4:5], s[26:27] op_sel_hi:[1,0]
	s_nop 0
	v_ashrrev_i32_e32 v4, 31, v0
	v_and_b32_e32 v4, 0x7fffff80, v4
	v_and_b32_e32 v0, 0xffffff80, v0
	v_bitop3_b32 v0, v4, s59, v0 bitop3:0xde
	v_med3_i32 v3, v16, v3, v0
	v_med3_i32 v4, v17, v16, v0
	v_med3_i32 v5, v18, v17, v0
	v_med3_i32 v16, v19, v18, v0
	v_med3_i32 v17, v20, v19, v0
	v_med3_i32 v18, v21, v20, v0
	v_med3_i32 v19, v22, v21, v0
	v_med3_i32 v20, v23, v22, v0
	v_med3_i32 v21, v24, v23, v0
	v_med3_i32 v22, v25, v24, v0
	v_med3_i32 v23, v26, v25, v0
	v_med3_i32 v24, v27, v26, v0
	v_med3_i32 v25, v28, v27, v0
	v_med3_i32 v26, v29, v28, v0
	v_med3_i32 v27, v2, v29, v0
	v_max_i32_e32 v0, v2, v0
	v_ashrrev_i32_e32 v2, 31, v1
	v_and_b32_e32 v2, 0x7fffff80, v2
	v_and_b32_e32 v1, 0xffffff80, v1
	v_bitop3_b32 v1, v2, s60, v1 bitop3:0xde
	v_med3_i32 v2, v4, v3, v1
	v_med3_i32 v3, v5, v4, v1
	v_med3_i32 v4, v16, v5, v1
	v_med3_i32 v5, v17, v16, v1
	v_med3_i32 v16, v18, v17, v1
	v_med3_i32 v17, v19, v18, v1
	v_med3_i32 v18, v20, v19, v1
	v_med3_i32 v19, v21, v20, v1
	v_med3_i32 v20, v22, v21, v1
	v_med3_i32 v21, v23, v22, v1
	v_med3_i32 v22, v24, v23, v1
	v_med3_i32 v23, v25, v24, v1
	v_med3_i32 v24, v26, v25, v1
	v_med3_i32 v25, v27, v26, v1
	v_med3_i32 v26, v0, v27, v1
	v_max_i32_e32 v27, v0, v1
	v_pk_mul_f32 v[0:1], v[6:7], s[26:27] op_sel_hi:[1,0]
	s_nop 0
	v_ashrrev_i32_e32 v6, 31, v0
	v_and_b32_e32 v6, 0x7fffff80, v6
	v_and_b32_e32 v0, 0xffffff80, v0
	v_bitop3_b32 v0, v6, s61, v0 bitop3:0xde
	v_med3_i32 v2, v3, v2, v0
	v_med3_i32 v3, v4, v3, v0
	v_med3_i32 v4, v5, v4, v0
	v_med3_i32 v5, v16, v5, v0
	v_med3_i32 v6, v17, v16, v0
	v_med3_i32 v7, v18, v17, v0
	v_med3_i32 v16, v19, v18, v0
	v_med3_i32 v17, v20, v19, v0
	v_med3_i32 v18, v21, v20, v0
	v_med3_i32 v19, v22, v21, v0
	v_med3_i32 v20, v23, v22, v0
	v_med3_i32 v21, v24, v23, v0
	v_med3_i32 v22, v25, v24, v0
	v_med3_i32 v23, v26, v25, v0
	v_ashrrev_i32_e32 v25, 31, v1
	v_and_b32_e32 v25, 0x7fffff80, v25
	v_and_b32_e32 v1, 0xffffff80, v1
	v_med3_i32 v24, v27, v26, v0
	v_max_i32_e32 v0, v27, v0
	v_bitop3_b32 v1, v25, s62, v1 bitop3:0xde
	v_med3_i32 v2, v3, v2, v1
	v_med3_i32 v3, v4, v3, v1
	v_med3_i32 v4, v5, v4, v1
	v_med3_i32 v5, v6, v5, v1
	v_med3_i32 v6, v7, v6, v1
	v_med3_i32 v7, v16, v7, v1
	v_med3_i32 v16, v17, v16, v1
	v_med3_i32 v17, v18, v17, v1
	v_med3_i32 v18, v19, v18, v1
	v_med3_i32 v19, v20, v19, v1
	v_med3_i32 v20, v21, v20, v1
	v_med3_i32 v21, v22, v21, v1
	v_med3_i32 v22, v23, v22, v1
	v_med3_i32 v23, v24, v23, v1
	v_med3_i32 v24, v0, v24, v1
	v_max_i32_e32 v25, v0, v1
	v_pk_mul_f32 v[0:1], v[8:9], s[26:27] op_sel_hi:[1,0]
	s_nop 0
	v_ashrrev_i32_e32 v8, 31, v0
	v_and_b32_e32 v8, 0x7fffff80, v8
	v_and_b32_e32 v0, 0xffffff80, v0
	v_bitop3_b32 v0, v8, s63, v0 bitop3:0xde
	v_med3_i32 v2, v3, v2, v0
	v_med3_i32 v3, v4, v3, v0
	v_med3_i32 v4, v5, v4, v0
	v_med3_i32 v5, v6, v5, v0
	v_med3_i32 v6, v7, v6, v0
	v_med3_i32 v7, v16, v7, v0
	v_med3_i32 v8, v17, v16, v0
	v_med3_i32 v9, v18, v17, v0
	v_med3_i32 v16, v19, v18, v0
	v_med3_i32 v17, v20, v19, v0
	v_med3_i32 v18, v21, v20, v0
	v_med3_i32 v19, v22, v21, v0
	v_med3_i32 v20, v23, v22, v0
	v_med3_i32 v21, v24, v23, v0
	v_ashrrev_i32_e32 v23, 31, v1
	v_and_b32_e32 v23, 0x7fffff80, v23
	v_and_b32_e32 v1, 0xffffff80, v1
	v_med3_i32 v22, v25, v24, v0
	v_max_i32_e32 v0, v25, v0
	v_bitop3_b32 v1, v23, s64, v1 bitop3:0xde
	v_med3_i32 v2, v3, v2, v1
	v_med3_i32 v3, v4, v3, v1
	v_med3_i32 v4, v5, v4, v1
	v_med3_i32 v5, v6, v5, v1
	v_med3_i32 v6, v7, v6, v1
	v_med3_i32 v7, v8, v7, v1
	v_med3_i32 v8, v9, v8, v1
	v_med3_i32 v9, v16, v9, v1
	v_med3_i32 v16, v17, v16, v1
	v_med3_i32 v17, v18, v17, v1
	v_med3_i32 v18, v19, v18, v1
	v_med3_i32 v19, v20, v19, v1
	v_med3_i32 v20, v21, v20, v1
	v_med3_i32 v21, v22, v21, v1
	v_med3_i32 v22, v0, v22, v1
	v_max_i32_e32 v23, v0, v1
	v_pk_mul_f32 v[0:1], v[10:11], s[26:27] op_sel_hi:[1,0]
	s_nop 0
	v_ashrrev_i32_e32 v10, 31, v0
	v_and_b32_e32 v10, 0x7fffff80, v10
	v_and_b32_e32 v0, 0xffffff80, v0
	v_bitop3_b32 v0, v10, s65, v0 bitop3:0xde
	v_med3_i32 v2, v3, v2, v0
	v_med3_i32 v3, v4, v3, v0
	v_med3_i32 v4, v5, v4, v0
	v_med3_i32 v5, v6, v5, v0
	v_med3_i32 v6, v7, v6, v0
	v_med3_i32 v7, v8, v7, v0
	v_med3_i32 v8, v9, v8, v0
	v_med3_i32 v9, v16, v9, v0
	v_med3_i32 v10, v17, v16, v0
	v_med3_i32 v11, v18, v17, v0
	v_med3_i32 v16, v19, v18, v0
	v_med3_i32 v17, v20, v19, v0
	v_med3_i32 v18, v21, v20, v0
	v_med3_i32 v19, v22, v21, v0
	v_ashrrev_i32_e32 v21, 31, v1
	v_and_b32_e32 v21, 0x7fffff80, v21
	v_and_b32_e32 v1, 0xffffff80, v1
	v_med3_i32 v20, v23, v22, v0
	v_max_i32_e32 v0, v23, v0
	v_bitop3_b32 v1, v21, s66, v1 bitop3:0xde
	v_med3_i32 v2, v3, v2, v1
	v_med3_i32 v3, v4, v3, v1
	v_med3_i32 v4, v5, v4, v1
	v_med3_i32 v5, v6, v5, v1
	v_med3_i32 v6, v7, v6, v1
	v_med3_i32 v7, v8, v7, v1
	v_med3_i32 v8, v9, v8, v1
	v_med3_i32 v9, v10, v9, v1
	v_med3_i32 v10, v11, v10, v1
	v_med3_i32 v11, v16, v11, v1
	v_med3_i32 v16, v17, v16, v1
	v_med3_i32 v17, v18, v17, v1
	v_med3_i32 v18, v19, v18, v1
	v_med3_i32 v19, v20, v19, v1
	v_med3_i32 v20, v0, v20, v1
	v_max_i32_e32 v21, v0, v1
	v_pk_mul_f32 v[0:1], v[12:13], s[26:27] op_sel_hi:[1,0]
	s_nop 0
	v_ashrrev_i32_e32 v12, 31, v0
	v_and_b32_e32 v12, 0x7fffff80, v12
	v_and_b32_e32 v0, 0xffffff80, v0
	v_bitop3_b32 v0, v12, s67, v0 bitop3:0xde
; DI int med3i(int a, int b, int c) { int r; asm("v_med3_i32 %0, %1, %2, %3" : "=v"(r) : "v"(a), "v"(b), "v"(c)); return r; }
; DI void insert16(int (&L)[16], int x) {
; #pragma unroll
;   for (int j = 15; j >= 1; --j) L[j] = med3i(L[j - 1], L[j], x);
;   L[0] = max(L[0], x);
; }
; DI int f2sort(float f) { int b = __float_as_int(f); return b ^ ((b >> 31) & 0x7fffffff); }
; DI void p5a_half(const bf16x8 (&qf)[8], const u16* __restrict__ pk, float rs, int (&Lh)[16], u16* smem, int tid, int r, int h) {
;     ...
;     for (int i = 0; i < 16; ++i) {
;       const int keyc = kt * 32 + (i & 3) + 8 * (i >> 2);
;       int sb = (f2sort(Y[i] * rs) & ~127) | keyc;
;       insert16(Lh, sb);
;     }
;     __builtin_amdgcn_sched_barrier(0);
;   }
;   const int h4 = 4 * h;
; #pragma unroll
;   for (int j = 0; j < 16; ++j) Lh[j] |= h4;
;   int other[16];
; #pragma unroll
;   for (int j = 0; j < 16; ++j) other[j] = __shfl_xor(Lh[j], 32);
; #pragma unroll
;   for (int j = 0; j < 16; ++j) insert16(Lh, other[j]);
	v_med3_i32 v2, v3, v2, v0
	v_med3_i32 v3, v4, v3, v0
	v_med3_i32 v4, v5, v4, v0
	v_med3_i32 v5, v6, v5, v0
	v_med3_i32 v6, v7, v6, v0
	v_med3_i32 v7, v8, v7, v0
	v_med3_i32 v8, v9, v8, v0
	v_med3_i32 v9, v10, v9, v0
	v_med3_i32 v10, v11, v10, v0
	v_med3_i32 v11, v16, v11, v0
	v_med3_i32 v12, v17, v16, v0
	v_med3_i32 v13, v18, v17, v0
	v_med3_i32 v16, v19, v18, v0
	v_med3_i32 v17, v20, v19, v0
	v_ashrrev_i32_e32 v19, 31, v1
	v_and_b32_e32 v19, 0x7fffff80, v19
	v_and_b32_e32 v1, 0xffffff80, v1
	v_med3_i32 v18, v21, v20, v0
	v_max_i32_e32 v0, v21, v0
	v_bitop3_b32 v1, v19, s68, v1 bitop3:0xde
	v_med3_i32 v2, v3, v2, v1
	v_med3_i32 v3, v4, v3, v1
	v_med3_i32 v4, v5, v4, v1
	v_med3_i32 v5, v6, v5, v1
	v_med3_i32 v6, v7, v6, v1
	v_med3_i32 v7, v8, v7, v1
	v_med3_i32 v8, v9, v8, v1
	v_med3_i32 v9, v10, v9, v1
	v_med3_i32 v10, v11, v10, v1
	v_med3_i32 v11, v12, v11, v1
	v_med3_i32 v12, v13, v12, v1
	v_med3_i32 v13, v16, v13, v1
	v_med3_i32 v16, v17, v16, v1
	v_med3_i32 v17, v18, v17, v1
	v_med3_i32 v18, v0, v18, v1
	v_max_i32_e32 v19, v0, v1
	v_pk_mul_f32 v[0:1], v[14:15], s[26:27] op_sel_hi:[1,0]
	s_nop 0
	v_ashrrev_i32_e32 v14, 31, v0
	v_and_b32_e32 v14, 0x7fffff80, v14
	v_and_b32_e32 v0, 0xffffff80, v0
	v_bitop3_b32 v0, v14, s69, v0 bitop3:0xde
	v_med3_i32 v14, v17, v16, v0
	v_med3_i32 v15, v18, v17, v0
	v_ashrrev_i32_e32 v17, 31, v1
	v_and_b32_e32 v17, 0x7fffff80, v17
	v_and_b32_e32 v1, 0xffffff80, v1
	v_med3_i32 v2, v3, v2, v0
	v_med3_i32 v3, v4, v3, v0
	v_med3_i32 v4, v5, v4, v0
	v_med3_i32 v5, v6, v5, v0
	v_med3_i32 v6, v7, v6, v0
	v_med3_i32 v7, v8, v7, v0
	v_med3_i32 v8, v9, v8, v0
	v_med3_i32 v9, v10, v9, v0
	v_med3_i32 v10, v11, v10, v0
	v_med3_i32 v11, v12, v11, v0
	v_med3_i32 v12, v13, v12, v0
	v_med3_i32 v13, v16, v13, v0
	v_med3_i32 v16, v19, v18, v0
	v_max_i32_e32 v0, v19, v0
	v_bitop3_b32 v1, v17, s70, v1 bitop3:0xde
	v_med3_i32 v2, v3, v2, v1
	v_med3_i32 v3, v4, v3, v1
	v_med3_i32 v4, v5, v4, v1
	v_med3_i32 v5, v6, v5, v1
	v_med3_i32 v6, v7, v6, v1
	v_med3_i32 v7, v8, v7, v1
	v_med3_i32 v8, v9, v8, v1
	v_med3_i32 v9, v10, v9, v1
	v_med3_i32 v10, v11, v10, v1
	v_med3_i32 v11, v12, v11, v1
	v_med3_i32 v12, v13, v12, v1
	v_med3_i32 v13, v14, v13, v1
	v_med3_i32 v14, v15, v14, v1
	v_med3_i32 v15, v16, v15, v1
	v_med3_i32 v16, v0, v16, v1
	v_max_i32_e32 v0, v0, v1
	v_or_b32_e32 v0, v0, v190
	v_or_b32_e32 v1, v16, v190
	ds_bpermute_b32 v16, v56, v0
	v_or_b32_e32 v15, v15, v190
	ds_bpermute_b32 v17, v56, v1
	v_or_b32_e32 v14, v14, v190
	ds_bpermute_b32 v18, v56, v15
	v_or_b32_e32 v13, v13, v190
	ds_bpermute_b32 v19, v56, v14
	v_or_b32_e32 v12, v12, v190
	v_or_b32_e32 v11, v11, v190
	v_or_b32_e32 v10, v10, v190
	v_or_b32_e32 v9, v9, v190
	v_or_b32_e32 v8, v8, v190
	v_or_b32_e32 v7, v7, v190
	v_or_b32_e32 v6, v6, v190
	v_or_b32_e32 v5, v5, v190
	v_or_b32_e32 v4, v4, v190
	v_or_b32_e32 v3, v3, v190
	v_or_b32_e32 v2, v2, v190
	ds_bpermute_b32 v20, v56, v13
	ds_bpermute_b32 v21, v56, v12
	ds_bpermute_b32 v22, v56, v11
	ds_bpermute_b32 v23, v56, v10
	ds_bpermute_b32 v24, v56, v9
	ds_bpermute_b32 v25, v56, v8
	ds_bpermute_b32 v26, v56, v7
	ds_bpermute_b32 v27, v56, v6
	ds_bpermute_b32 v28, v56, v5
	ds_bpermute_b32 v29, v56, v4
	ds_bpermute_b32 v30, v56, v3
	ds_bpermute_b32 v53, v56, v2
	s_waitcnt lgkmcnt(14)
	v_med3_i32 v2, v3, v2, v16
	v_med3_i32 v3, v4, v3, v16
	v_med3_i32 v4, v5, v4, v16
	v_med3_i32 v5, v6, v5, v16
	v_med3_i32 v6, v7, v6, v16
	v_med3_i32 v7, v8, v7, v16
	v_med3_i32 v8, v9, v8, v16
	v_med3_i32 v9, v10, v9, v16
	v_med3_i32 v10, v11, v10, v16
	v_med3_i32 v11, v12, v11, v16
	v_med3_i32 v12, v13, v12, v16
	v_med3_i32 v13, v14, v13, v16
	v_med3_i32 v14, v15, v14, v16
	v_med3_i32 v15, v1, v15, v16
	v_med3_i32 v1, v0, v1, v16
	v_max_i32_e32 v0, v0, v16
	v_med3_i32 v2, v3, v2, v17
	v_med3_i32 v3, v4, v3, v17
	v_med3_i32 v4, v5, v4, v17
	v_med3_i32 v5, v6, v5, v17
	v_med3_i32 v6, v7, v6, v17
	v_med3_i32 v7, v8, v7, v17
	v_med3_i32 v8, v9, v8, v17
	v_med3_i32 v9, v10, v9, v17
	v_med3_i32 v10, v11, v10, v17
	v_med3_i32 v11, v12, v11, v17
	v_med3_i32 v12, v13, v12, v17
	v_med3_i32 v13, v14, v13, v17
	v_med3_i32 v14, v15, v14, v17
	v_med3_i32 v15, v1, v15, v17
	v_med3_i32 v1, v0, v1, v17
	v_max_i32_e32 v0, v0, v17
	s_waitcnt lgkmcnt(13)
	v_med3_i32 v2, v3, v2, v18
	v_med3_i32 v3, v4, v3, v18
	v_med3_i32 v4, v5, v4, v18
	v_med3_i32 v5, v6, v5, v18
	v_med3_i32 v6, v7, v6, v18
	v_med3_i32 v7, v8, v7, v18
	v_med3_i32 v8, v9, v8, v18
	v_med3_i32 v9, v10, v9, v18
	v_med3_i32 v10, v11, v10, v18
	v_med3_i32 v11, v12, v11, v18
	v_med3_i32 v12, v13, v12, v18
	v_med3_i32 v13, v14, v13, v18
	v_med3_i32 v14, v15, v14, v18
	v_med3_i32 v15, v1, v15, v18
	v_med3_i32 v1, v0, v1, v18
	v_max_i32_e32 v0, v0, v18
	s_waitcnt lgkmcnt(12)
	v_med3_i32 v2, v3, v2, v19
	v_med3_i32 v3, v4, v3, v19
	v_med3_i32 v4, v5, v4, v19
	v_med3_i32 v5, v6, v5, v19
	v_med3_i32 v6, v7, v6, v19
	v_med3_i32 v7, v8, v7, v19
	v_med3_i32 v8, v9, v8, v19
	v_med3_i32 v9, v10, v9, v19
	v_med3_i32 v10, v11, v10, v19
	v_med3_i32 v11, v12, v11, v19
	v_med3_i32 v12, v13, v12, v19
	v_med3_i32 v13, v14, v13, v19
	v_med3_i32 v14, v15, v14, v19
	v_med3_i32 v15, v1, v15, v19
	v_med3_i32 v1, v0, v1, v19
	v_max_i32_e32 v0, v0, v19
	s_waitcnt lgkmcnt(11)
	v_med3_i32 v2, v3, v2, v20
	v_med3_i32 v3, v4, v3, v20
	v_med3_i32 v4, v5, v4, v20
	v_med3_i32 v5, v6, v5, v20
	v_med3_i32 v6, v7, v6, v20
	v_med3_i32 v7, v8, v7, v20
	v_med3_i32 v8, v9, v8, v20
	v_med3_i32 v9, v10, v9, v20
	v_med3_i32 v10, v11, v10, v20
	v_med3_i32 v11, v12, v11, v20
	v_med3_i32 v12, v13, v12, v20
	v_med3_i32 v13, v14, v13, v20
	v_med3_i32 v14, v15, v14, v20
	v_med3_i32 v15, v1, v15, v20
	v_med3_i32 v1, v0, v1, v20
	v_max_i32_e32 v0, v0, v20
	s_waitcnt lgkmcnt(10)
; DI void p5a_half(const bf16x8 (&qf)[8], const u16* __restrict__ pk, float rs, int (&Lh)[16], u16* smem, int tid, int r, int h) {
;     ...
;   for (int j = 0; j < 16; ++j) other[j] = __shfl_xor(Lh[j], 32);
; #pragma unroll
;   for (int j = 0; j < 16; ++j) insert16(Lh, other[j]);
;   __syncthreads();
	v_med3_i32 v2, v3, v2, v21
	v_med3_i32 v3, v4, v3, v21
	v_med3_i32 v4, v5, v4, v21
	v_med3_i32 v5, v6, v5, v21
	v_med3_i32 v6, v7, v6, v21
	v_med3_i32 v7, v8, v7, v21
	v_med3_i32 v8, v9, v8, v21
	v_med3_i32 v9, v10, v9, v21
	v_med3_i32 v10, v11, v10, v21
	v_med3_i32 v11, v12, v11, v21
	v_med3_i32 v12, v13, v12, v21
	v_med3_i32 v13, v14, v13, v21
	v_med3_i32 v14, v15, v14, v21
	v_med3_i32 v15, v1, v15, v21
	v_med3_i32 v1, v0, v1, v21
	v_max_i32_e32 v0, v0, v21
	s_waitcnt lgkmcnt(9)
	v_med3_i32 v2, v3, v2, v22
	v_med3_i32 v3, v4, v3, v22
	v_med3_i32 v4, v5, v4, v22
	v_med3_i32 v5, v6, v5, v22
	v_med3_i32 v6, v7, v6, v22
	v_med3_i32 v7, v8, v7, v22
	v_med3_i32 v8, v9, v8, v22
	v_med3_i32 v9, v10, v9, v22
	v_med3_i32 v10, v11, v10, v22
	v_med3_i32 v11, v12, v11, v22
	v_med3_i32 v12, v13, v12, v22
	v_med3_i32 v13, v14, v13, v22
	v_med3_i32 v14, v15, v14, v22
	v_med3_i32 v15, v1, v15, v22
	v_med3_i32 v1, v0, v1, v22
	v_max_i32_e32 v0, v0, v22
	s_waitcnt lgkmcnt(8)
	v_med3_i32 v2, v3, v2, v23
	v_med3_i32 v3, v4, v3, v23
	v_med3_i32 v4, v5, v4, v23
	v_med3_i32 v5, v6, v5, v23
	v_med3_i32 v6, v7, v6, v23
	v_med3_i32 v7, v8, v7, v23
	v_med3_i32 v8, v9, v8, v23
	v_med3_i32 v9, v10, v9, v23
	v_med3_i32 v10, v11, v10, v23
	v_med3_i32 v11, v12, v11, v23
	v_med3_i32 v12, v13, v12, v23
	v_med3_i32 v13, v14, v13, v23
	v_med3_i32 v14, v15, v14, v23
	v_med3_i32 v15, v1, v15, v23
	v_med3_i32 v1, v0, v1, v23
	v_max_i32_e32 v0, v0, v23
	s_waitcnt lgkmcnt(7)
	v_med3_i32 v2, v3, v2, v24
	v_med3_i32 v3, v4, v3, v24
	v_med3_i32 v4, v5, v4, v24
	v_med3_i32 v5, v6, v5, v24
	v_med3_i32 v6, v7, v6, v24
	v_med3_i32 v7, v8, v7, v24
	v_med3_i32 v8, v9, v8, v24
	v_med3_i32 v9, v10, v9, v24
	v_med3_i32 v10, v11, v10, v24
	v_med3_i32 v11, v12, v11, v24
	v_med3_i32 v12, v13, v12, v24
	v_med3_i32 v13, v14, v13, v24
	v_med3_i32 v14, v15, v14, v24
	v_med3_i32 v15, v1, v15, v24
	v_med3_i32 v1, v0, v1, v24
	v_max_i32_e32 v0, v0, v24
	s_waitcnt lgkmcnt(6)
	v_med3_i32 v2, v3, v2, v25
	v_med3_i32 v3, v4, v3, v25
	v_med3_i32 v4, v5, v4, v25
	v_med3_i32 v5, v6, v5, v25
	v_med3_i32 v6, v7, v6, v25
	v_med3_i32 v7, v8, v7, v25
	v_med3_i32 v8, v9, v8, v25
	v_med3_i32 v9, v10, v9, v25
	v_med3_i32 v10, v11, v10, v25
	v_med3_i32 v11, v12, v11, v25
	v_med3_i32 v12, v13, v12, v25
	v_med3_i32 v13, v14, v13, v25
	v_med3_i32 v14, v15, v14, v25
	v_med3_i32 v15, v1, v15, v25
	v_med3_i32 v1, v0, v1, v25
	v_max_i32_e32 v0, v0, v25
	s_waitcnt lgkmcnt(5)
	v_med3_i32 v2, v3, v2, v26
	v_med3_i32 v3, v4, v3, v26
	v_med3_i32 v4, v5, v4, v26
	v_med3_i32 v5, v6, v5, v26
	v_med3_i32 v6, v7, v6, v26
	v_med3_i32 v7, v8, v7, v26
	v_med3_i32 v8, v9, v8, v26
	v_med3_i32 v9, v10, v9, v26
	v_med3_i32 v10, v11, v10, v26
	v_med3_i32 v11, v12, v11, v26
	v_med3_i32 v12, v13, v12, v26
	v_med3_i32 v13, v14, v13, v26
	v_med3_i32 v14, v15, v14, v26
	v_med3_i32 v15, v1, v15, v26
	v_med3_i32 v1, v0, v1, v26
	v_max_i32_e32 v0, v0, v26
	s_waitcnt lgkmcnt(4)
	v_med3_i32 v2, v3, v2, v27
	v_med3_i32 v3, v4, v3, v27
	v_med3_i32 v4, v5, v4, v27
	v_med3_i32 v5, v6, v5, v27
	v_med3_i32 v6, v7, v6, v27
	v_med3_i32 v7, v8, v7, v27
	v_med3_i32 v8, v9, v8, v27
	v_med3_i32 v9, v10, v9, v27
	v_med3_i32 v10, v11, v10, v27
	v_med3_i32 v11, v12, v11, v27
	v_med3_i32 v12, v13, v12, v27
	v_med3_i32 v13, v14, v13, v27
	v_med3_i32 v14, v15, v14, v27
	v_med3_i32 v15, v1, v15, v27
	v_med3_i32 v1, v0, v1, v27
	v_max_i32_e32 v0, v0, v27
	s_waitcnt lgkmcnt(3)
	v_med3_i32 v2, v3, v2, v28
	v_med3_i32 v3, v4, v3, v28
	v_med3_i32 v4, v5, v4, v28
	v_med3_i32 v5, v6, v5, v28
	v_med3_i32 v6, v7, v6, v28
	v_med3_i32 v7, v8, v7, v28
	v_med3_i32 v8, v9, v8, v28
	v_med3_i32 v9, v10, v9, v28
	v_med3_i32 v10, v11, v10, v28
	v_med3_i32 v11, v12, v11, v28
	v_med3_i32 v12, v13, v12, v28
	v_med3_i32 v13, v14, v13, v28
	v_med3_i32 v14, v15, v14, v28
	v_med3_i32 v15, v1, v15, v28
	v_med3_i32 v1, v0, v1, v28
	v_max_i32_e32 v0, v0, v28
	s_waitcnt lgkmcnt(2)
	v_med3_i32 v2, v3, v2, v29
	v_med3_i32 v3, v4, v3, v29
	v_med3_i32 v4, v5, v4, v29
	v_med3_i32 v5, v6, v5, v29
	v_med3_i32 v6, v7, v6, v29
	v_med3_i32 v7, v8, v7, v29
	v_med3_i32 v8, v9, v8, v29
	v_med3_i32 v9, v10, v9, v29
	v_med3_i32 v10, v11, v10, v29
	v_med3_i32 v11, v12, v11, v29
	v_med3_i32 v12, v13, v12, v29
	v_med3_i32 v13, v14, v13, v29
	v_med3_i32 v14, v15, v14, v29
	v_med3_i32 v15, v1, v15, v29
	v_med3_i32 v1, v0, v1, v29
	v_max_i32_e32 v0, v0, v29
	s_waitcnt lgkmcnt(1)
	v_med3_i32 v16, v10, v9, v30
	v_med3_i32 v10, v11, v10, v30
	v_med3_i32 v11, v12, v11, v30
	v_med3_i32 v12, v13, v12, v30
	v_med3_i32 v13, v14, v13, v30
	v_med3_i32 v14, v15, v14, v30
	v_med3_i32 v15, v1, v15, v30
	v_med3_i32 v1, v0, v1, v30
	v_max_i32_e32 v0, v0, v30
	v_med3_i32 v2, v3, v2, v30
	v_med3_i32 v3, v4, v3, v30
	v_med3_i32 v4, v5, v4, v30
	v_med3_i32 v5, v6, v5, v30
	v_med3_i32 v6, v7, v6, v30
	v_med3_i32 v7, v8, v7, v30
	v_med3_i32 v8, v9, v8, v30
	s_waitcnt lgkmcnt(0)
	v_med3_i32 v9, v3, v2, v53
	v_med3_i32 v28, v4, v3, v53
	v_med3_i32 v31, v5, v4, v53
	v_med3_i32 v48, v6, v5, v53
	v_med3_i32 v30, v7, v6, v53
	v_med3_i32 v29, v8, v7, v53
	v_med3_i32 v49, v16, v8, v53
	v_med3_i32 v50, v10, v16, v53
	v_med3_i32 v57, v11, v10, v53
	v_med3_i32 v51, v12, v11, v53
	v_med3_i32 v54, v13, v12, v53
	v_med3_i32 v55, v14, v13, v53
	v_med3_i32 v52, v15, v14, v53
	v_med3_i32 v58, v1, v15, v53
	v_med3_i32 v56, v0, v1, v53
	v_max_i32_e32 v53, v0, v53
	s_barrier
; DI int f2sort(float f) { int b = __float_as_int(f); return b ^ ((b >> 31) & 0x7fffffff); }
; DI float sort2f(int b) { return __int_as_float(b ^ ((b >> 31) & 0x7fffffff)); }
; DI void phase5a(const Params& p, u16* smem) {
;     ...
;     float v1[16], v2[16];
; #pragma unroll
;     for (int j = 0; j < 16; ++j) { v1[j] = sort2f(L[0][j] & ~127); v2[j] = sort2f(L[1][j] & ~127); }
;     int Lc[16];
; #pragma unroll
;     for (int j = 0; j < 16; ++j) Lc[j] = (int)0x80000000;
; #pragma unroll
;     for (int i = 0; i < 16; ++i)
; #pragma unroll
;       for (int j = 0; j < 16; ++j)
;         if ((i + 1) * (j + 1) <= 16) {
;           int sb = (f2sort(v1[i] + v2[j]) & ~255) | (i * 16 + j);
;           insert16(Lc, sb);
;         }
	v_ashrrev_i32_e32 v2, 31, v41
	v_ashrrev_i32_e32 v3, 31, v52
	v_and_b32_e32 v0, 0xffffff80, v52
	v_and_b32_e32 v1, 0xffffff80, v41
	v_and_b32_e32 v2, 0x7fffffff, v2
	v_and_b32_e32 v3, 0x7fffffff, v3
	v_xor_b32_e32 v13, v3, v0
	v_xor_b32_e32 v12, v2, v1
	v_ashrrev_i32_e32 v2, 31, v45
	v_ashrrev_i32_e32 v3, 31, v58
	v_and_b32_e32 v0, 0xffffff80, v58
	v_and_b32_e32 v1, 0xffffff80, v45
	v_and_b32_e32 v2, 0x7fffffff, v2
	v_and_b32_e32 v3, 0x7fffffff, v3
	v_xor_b32_e32 v11, v3, v0
	v_xor_b32_e32 v10, v2, v1
	v_ashrrev_i32_e32 v2, 31, v47
	v_ashrrev_i32_e32 v3, 31, v55
	v_and_b32_e32 v0, 0xffffff80, v55
	v_and_b32_e32 v1, 0xffffff80, v47
	v_and_b32_e32 v2, 0x7fffffff, v2
	v_and_b32_e32 v3, 0x7fffffff, v3
	v_xor_b32_e32 v15, v3, v0
	v_xor_b32_e32 v14, v2, v1
	v_and_b32_e32 v0, 0xffffff80, v44
	v_ashrrev_i32_e32 v1, 31, v44
	v_bitop3_b32 v8, v1, v0, s71 bitop3:0x6c
	v_and_b32_e32 v0, 0xffffff80, v54
	v_ashrrev_i32_e32 v1, 31, v54
	v_bitop3_b32 v22, v1, v0, s71 bitop3:0x6c
	v_and_b32_e32 v0, 0xffffff80, v40
	v_ashrrev_i32_e32 v1, 31, v40
	v_bitop3_b32 v0, v1, v0, s71 bitop3:0x6c
	v_and_b32_e32 v1, 0xffffff80, v51
	v_ashrrev_i32_e32 v2, 31, v51
	v_ashrrev_i32_e32 v3, 31, v43
	v_ashrrev_i32_e32 v4, 31, v56
	v_bitop3_b32 v19, v2, v1, s71 bitop3:0x6c
	v_and_b32_e32 v1, 0xffffff80, v56
	v_and_b32_e32 v2, 0xffffff80, v43
	v_and_b32_e32 v3, 0x7fffffff, v3
	v_and_b32_e32 v4, 0x7fffffff, v4
	v_xor_b32_e32 v5, v4, v1
	v_xor_b32_e32 v4, v3, v2
	v_ashrrev_i32_e32 v3, 31, v46
	v_ashrrev_i32_e32 v6, 31, v57
	v_and_b32_e32 v1, 0xffffff80, v57
	v_and_b32_e32 v2, 0xffffff80, v46
	v_and_b32_e32 v3, 0x7fffffff, v3
	v_and_b32_e32 v6, 0x7fffffff, v6
	v_xor_b32_e32 v21, v6, v1
	v_xor_b32_e32 v20, v3, v2
	v_and_b32_e32 v1, 0xffffff80, v33
	v_ashrrev_i32_e32 v2, 31, v33
	v_bitop3_b32 v1, v2, v1, s71 bitop3:0x6c
	v_and_b32_e32 v2, 0xffffff80, v28
	v_ashrrev_i32_e32 v3, 31, v28
	v_bitop3_b32 v25, v3, v2, s71 bitop3:0x6c
	v_ashrrev_i32_e32 v3, 31, v32
	v_and_b32_e32 v7, 0x7fffffff, v3
	v_ashrrev_i32_e32 v3, 31, v53
	v_and_b32_e32 v2, 0xffffff80, v53
	v_and_b32_e32 v6, 0xffffff80, v32
	v_and_b32_e32 v3, 0x7fffffff, v3
	v_ashrrev_i32_e32 v16, 31, v9
	v_ashrrev_i32_e32 v17, 31, v42
	v_xor_b32_e32 v3, v3, v2
	v_xor_b32_e32 v2, v7, v6
	v_and_b32_e32 v6, 0xffffff80, v9
	v_and_b32_e32 v7, 0xffffff80, v42
	v_and_b32_e32 v16, 0x7fffffff, v16
	v_and_b32_e32 v17, 0x7fffffff, v17
	v_xor_b32_e32 v27, v16, v6
	v_xor_b32_e32 v26, v17, v7
	v_mov_b32_e32 v6, v5
	v_mov_b32_e32 v7, v3
	v_pk_add_f32 v[16:17], v[26:27], v[6:7] op_sel_hi:[0,1]
	v_ashrrev_i32_e32 v23, 31, v16
	v_ashrrev_i32_e32 v18, 31, v17
	v_and_b32_e32 v17, 0xffffff00, v17
	v_and_b32_e32 v23, 0x7fffff00, v23
	v_and_b32_e32 v16, 0xffffff00, v16
	v_bitop3_b32 v17, v18, v17, s72 bitop3:0x6c
	v_med3_i32 v18, v170, v170, v17
	v_bitop3_b32 v16, v23, 1, v16 bitop3:0xde
	v_med3_i32 v23, v18, v18, v16
	v_med3_i32 v18, v17, v18, v16
	v_max_i32_e32 v24, v17, v16
	v_mov_b32_e32 v16, v13
	v_mov_b32_e32 v17, v11
	v_pk_add_f32 v[60:61], v[26:27], v[16:17] op_sel_hi:[0,1]
	v_ashrrev_i32_e32 v59, 31, v61
	v_and_b32_e32 v59, 0x7fffff00, v59
	v_and_b32_e32 v61, 0xffffff00, v61
	v_bitop3_b32 v59, v59, 2, v61 bitop3:0xde
	v_med3_i32 v61, v23, v23, v59
	v_med3_i32 v23, v18, v23, v59
	v_med3_i32 v18, v24, v18, v59
	v_max_i32_e32 v24, v24, v59
	v_ashrrev_i32_e32 v59, 31, v60
	v_and_b32_e32 v59, 0x7fffff00, v59
	v_and_b32_e32 v60, 0xffffff00, v60
	v_bitop3_b32 v59, v59, 3, v60 bitop3:0xde
	v_med3_i32 v63, v23, v61, v59
	v_med3_i32 v64, v18, v23, v59
	v_mov_b32_e32 v23, v15
	v_med3_i32 v62, v61, v61, v59
	v_pk_add_f32 v[60:61], v[26:27], v[22:23] op_sel_hi:[0,1]
	v_med3_i32 v18, v24, v18, v59
	v_max_i32_e32 v24, v24, v59
	v_ashrrev_i32_e32 v59, 31, v61
	v_and_b32_e32 v59, 0x7fffff00, v59
	v_and_b32_e32 v61, 0xffffff00, v61
	v_bitop3_b32 v59, v59, 4, v61 bitop3:0xde
	v_med3_i32 v61, v62, v62, v59
	v_med3_i32 v62, v63, v62, v59
	v_med3_i32 v63, v64, v63, v59
	v_med3_i32 v64, v18, v64, v59
	v_med3_i32 v18, v24, v18, v59
	v_max_i32_e32 v24, v24, v59
	v_ashrrev_i32_e32 v59, 31, v60
	v_and_b32_e32 v59, 0x7fffff00, v59
	v_and_b32_e32 v60, 0xffffff00, v60
	v_bitop3_b32 v59, v59, 5, v60 bitop3:0xde
	v_med3_i32 v66, v62, v61, v59
	v_med3_i32 v62, v63, v62, v59
	v_med3_i32 v63, v64, v63, v59
	v_med3_i32 v64, v18, v64, v59
	v_med3_i32 v67, v24, v18, v59
	v_mov_b32_e32 v18, v21
	v_med3_i32 v65, v61, v61, v59
	v_pk_add_f32 v[60:61], v[26:27], v[18:19] op_sel_hi:[0,1]
	v_max_i32_e32 v24, v24, v59
	v_ashrrev_i32_e32 v59, 31, v61
	v_and_b32_e32 v59, 0x7fffff00, v59
	v_and_b32_e32 v61, 0xffffff00, v61
	v_bitop3_b32 v59, v59, 6, v61 bitop3:0xde
	v_med3_i32 v61, v65, v65, v59
	v_med3_i32 v65, v66, v65, v59
	v_med3_i32 v66, v62, v66, v59
	v_med3_i32 v62, v63, v62, v59
	v_med3_i32 v63, v64, v63, v59
	v_med3_i32 v64, v67, v64, v59
	v_med3_i32 v67, v24, v67, v59
	v_max_i32_e32 v24, v24, v59
	v_ashrrev_i32_e32 v59, 31, v60
	v_and_b32_e32 v59, 0x7fffff00, v59
	v_and_b32_e32 v60, 0xffffff00, v60
	v_bitop3_b32 v59, v59, 7, v60 bitop3:0xde
	v_med3_i32 v68, v61, v61, v59
	v_med3_i32 v69, v65, v61, v59
	v_ashrrev_i32_e32 v61, 31, v50
	v_ashrrev_i32_e32 v70, 31, v49
	v_med3_i32 v65, v66, v65, v59
	v_med3_i32 v66, v62, v66, v59
	v_med3_i32 v62, v63, v62, v59
	v_med3_i32 v63, v64, v63, v59
	v_med3_i32 v64, v67, v64, v59
	v_med3_i32 v67, v24, v67, v59
	v_max_i32_e32 v24, v24, v59
	v_and_b32_e32 v59, 0xffffff80, v50
	v_and_b32_e32 v60, 0xffffff80, v49
	v_and_b32_e32 v61, 0x7fffffff, v61
	v_and_b32_e32 v70, 0x7fffffff, v70
	v_xor_b32_e32 v61, v61, v59
	v_xor_b32_e32 v60, v70, v60
	v_pk_add_f32 v[60:61], v[26:27], v[60:61] op_sel_hi:[0,1]
	v_ashrrev_i32_e32 v59, 31, v61
; DI int f2sort(float f) { int b = __float_as_int(f); return b ^ ((b >> 31) & 0x7fffffff); }
; DI void phase5a(const Params& p, u16* smem) {
;     ...
;     for (int i = 0; i < 16; ++i)
; #pragma unroll
;       for (int j = 0; j < 16; ++j)
;         if ((i + 1) * (j + 1) <= 16) {
;           int sb = (f2sort(v1[i] + v2[j]) & ~255) | (i * 16 + j);
;           insert16(Lc, sb);
;         }
	v_and_b32_e32 v59, 0x7fffff00, v59
	v_and_b32_e32 v61, 0xffffff00, v61
	v_bitop3_b32 v59, v59, 8, v61 bitop3:0xde
	v_med3_i32 v61, v68, v68, v59
	v_med3_i32 v68, v69, v68, v59
	v_med3_i32 v69, v65, v69, v59
	v_med3_i32 v65, v66, v65, v59
	v_med3_i32 v66, v62, v66, v59
	v_med3_i32 v62, v63, v62, v59
	v_med3_i32 v63, v64, v63, v59
	v_med3_i32 v64, v67, v64, v59
	v_med3_i32 v67, v24, v67, v59
	v_max_i32_e32 v24, v24, v59
	v_ashrrev_i32_e32 v59, 31, v60
	v_and_b32_e32 v59, 0x7fffff00, v59
	v_and_b32_e32 v60, 0xffffff00, v60
	v_bitop3_b32 v59, v59, 9, v60 bitop3:0xde
	v_med3_i32 v70, v61, v61, v59
	v_med3_i32 v71, v68, v61, v59
	v_ashrrev_i32_e32 v61, 31, v29
	v_ashrrev_i32_e32 v72, 31, v30
	v_med3_i32 v68, v69, v68, v59
	v_med3_i32 v69, v65, v69, v59
	v_med3_i32 v65, v66, v65, v59
	v_med3_i32 v66, v62, v66, v59
	v_med3_i32 v62, v63, v62, v59
	v_med3_i32 v63, v64, v63, v59
	v_med3_i32 v64, v67, v64, v59
	v_med3_i32 v67, v24, v67, v59
	v_max_i32_e32 v24, v24, v59
	v_and_b32_e32 v59, 0xffffff80, v29
	v_and_b32_e32 v60, 0xffffff80, v30
	v_and_b32_e32 v61, 0x7fffffff, v61
	v_and_b32_e32 v72, 0x7fffffff, v72
	v_xor_b32_e32 v61, v61, v59
	v_xor_b32_e32 v60, v72, v60
	v_pk_add_f32 v[60:61], v[26:27], v[60:61] op_sel_hi:[0,1]
	v_ashrrev_i32_e32 v59, 31, v61
	v_and_b32_e32 v59, 0x7fffff00, v59
	v_and_b32_e32 v61, 0xffffff00, v61
	v_bitop3_b32 v59, v59, 10, v61 bitop3:0xde
	v_med3_i32 v61, v70, v70, v59
	v_med3_i32 v70, v71, v70, v59
	v_med3_i32 v71, v68, v71, v59
	v_med3_i32 v68, v69, v68, v59
	v_med3_i32 v69, v65, v69, v59
	v_med3_i32 v65, v66, v65, v59
	v_med3_i32 v66, v62, v66, v59
	v_med3_i32 v62, v63, v62, v59
	v_med3_i32 v63, v64, v63, v59
	v_med3_i32 v64, v67, v64, v59
	v_med3_i32 v67, v24, v67, v59
	v_max_i32_e32 v24, v24, v59
	v_ashrrev_i32_e32 v59, 31, v60
	v_and_b32_e32 v59, 0x7fffff00, v59
	v_and_b32_e32 v60, 0xffffff00, v60
	v_bitop3_b32 v59, v59, 11, v60 bitop3:0xde
	v_med3_i32 v72, v61, v61, v59
	v_med3_i32 v73, v70, v61, v59
	v_ashrrev_i32_e32 v61, 31, v48
	v_ashrrev_i32_e32 v74, 31, v31
	v_med3_i32 v70, v71, v70, v59
	v_med3_i32 v71, v68, v71, v59
	v_med3_i32 v68, v69, v68, v59
	v_med3_i32 v69, v65, v69, v59
	v_med3_i32 v65, v66, v65, v59
	v_med3_i32 v66, v62, v66, v59
	v_med3_i32 v62, v63, v62, v59
	v_med3_i32 v63, v64, v63, v59
	v_med3_i32 v64, v67, v64, v59
	v_med3_i32 v67, v24, v67, v59
	v_max_i32_e32 v24, v24, v59
	v_and_b32_e32 v59, 0xffffff80, v48
	v_and_b32_e32 v60, 0xffffff80, v31
	v_and_b32_e32 v61, 0x7fffffff, v61
	v_and_b32_e32 v74, 0x7fffffff, v74
	v_xor_b32_e32 v61, v61, v59
	v_xor_b32_e32 v60, v74, v60
	v_pk_add_f32 v[60:61], v[26:27], v[60:61] op_sel_hi:[0,1]
	v_ashrrev_i32_e32 v59, 31, v61
	v_and_b32_e32 v59, 0x7fffff00, v59
	v_and_b32_e32 v61, 0xffffff00, v61
	v_bitop3_b32 v59, v59, 12, v61 bitop3:0xde
	v_med3_i32 v61, v72, v72, v59
	v_med3_i32 v72, v73, v72, v59
	v_med3_i32 v73, v70, v73, v59
	v_med3_i32 v70, v71, v70, v59
	v_med3_i32 v71, v68, v71, v59
	v_med3_i32 v68, v69, v68, v59
	v_med3_i32 v69, v65, v69, v59
	v_med3_i32 v65, v66, v65, v59
	v_med3_i32 v66, v62, v66, v59
	v_med3_i32 v62, v63, v62, v59
	v_med3_i32 v63, v64, v63, v59
	v_med3_i32 v64, v67, v64, v59
	v_med3_i32 v67, v24, v67, v59
	v_max_i32_e32 v24, v24, v59
	v_ashrrev_i32_e32 v59, 31, v60
	v_and_b32_e32 v59, 0x7fffff00, v59
	v_and_b32_e32 v60, 0xffffff00, v60
	v_bitop3_b32 v59, v59, 13, v60 bitop3:0xde
	v_med3_i32 v60, v61, v61, v59
	v_med3_i32 v61, v72, v61, v59
	v_med3_i32 v72, v73, v72, v59
	v_med3_i32 v73, v70, v73, v59
	v_med3_i32 v70, v71, v70, v59
	v_med3_i32 v71, v68, v71, v59
	v_med3_i32 v68, v69, v68, v59
	v_med3_i32 v69, v65, v69, v59
	v_med3_i32 v65, v66, v65, v59
	v_med3_i32 v66, v62, v66, v59
	v_med3_i32 v62, v63, v62, v59
	v_med3_i32 v63, v64, v63, v59
	v_med3_i32 v64, v67, v64, v59
	v_med3_i32 v67, v24, v67, v59
	v_max_i32_e32 v59, v24, v59
	v_mov_b32_e32 v24, v27
	v_pk_add_f32 v[24:25], v[26:27], v[24:25] op_sel_hi:[0,1]
	v_ashrrev_i32_e32 v26, 31, v25
	v_and_b32_e32 v26, 0x7fffff00, v26
	v_and_b32_e32 v25, 0xffffff00, v25
	v_bitop3_b32 v25, v26, 14, v25 bitop3:0xde
	v_med3_i32 v26, v60, v60, v25
	v_med3_i32 v27, v61, v60, v25
	v_med3_i32 v60, v72, v61, v25
	v_med3_i32 v61, v73, v72, v25
	v_med3_i32 v72, v70, v73, v25
	v_med3_i32 v70, v71, v70, v25
	v_med3_i32 v71, v68, v71, v25
	v_med3_i32 v68, v69, v68, v25
	v_med3_i32 v69, v65, v69, v25
	v_med3_i32 v65, v66, v65, v25
	v_med3_i32 v66, v62, v66, v25
	v_med3_i32 v62, v63, v62, v25
	v_med3_i32 v63, v64, v63, v25
	v_med3_i32 v64, v67, v64, v25
	v_med3_i32 v67, v59, v67, v25
	v_max_i32_e32 v25, v59, v25
	v_ashrrev_i32_e32 v59, 31, v24
	v_and_b32_e32 v59, 0x7fffff00, v59
	v_and_b32_e32 v24, 0xffffff00, v24
	v_bitop3_b32 v24, v59, 15, v24 bitop3:0xde
	v_med3_i32 v26, v27, v26, v24
	v_med3_i32 v27, v60, v27, v24
	v_med3_i32 v59, v61, v60, v24
	v_med3_i32 v60, v72, v61, v24
	v_med3_i32 v61, v70, v72, v24
	v_med3_i32 v70, v71, v70, v24
	v_med3_i32 v71, v68, v71, v24
	v_med3_i32 v68, v69, v68, v24
	v_med3_i32 v69, v65, v69, v24
	v_med3_i32 v65, v66, v65, v24
	v_med3_i32 v66, v62, v66, v24
	v_med3_i32 v62, v63, v62, v24
	v_med3_i32 v63, v64, v63, v24
	v_med3_i32 v64, v67, v64, v24
	v_med3_i32 v67, v25, v67, v24
	v_max_i32_e32 v72, v25, v24
	v_pk_add_f32 v[24:25], v[20:21], v[6:7] op_sel_hi:[0,1]
	v_ashrrev_i32_e32 v73, 31, v25
	v_and_b32_e32 v73, 0x7fffff00, v73
	v_and_b32_e32 v25, 0xffffff00, v25
	v_bitop3_b32 v25, v73, 16, v25 bitop3:0xde
	v_med3_i32 v26, v27, v26, v25
	v_med3_i32 v27, v59, v27, v25
	v_med3_i32 v59, v60, v59, v25
	v_med3_i32 v60, v61, v60, v25
	v_med3_i32 v61, v70, v61, v25
	v_med3_i32 v70, v71, v70, v25
	v_med3_i32 v71, v68, v71, v25
	v_med3_i32 v68, v69, v68, v25
; DI int f2sort(float f) { int b = __float_as_int(f); return b ^ ((b >> 31) & 0x7fffffff); }
; DI void phase5a(const Params& p, u16* smem) {
;     ...
;     for (int i = 0; i < 16; ++i)
; #pragma unroll
;       for (int j = 0; j < 16; ++j)
;         if ((i + 1) * (j + 1) <= 16) {
;           int sb = (f2sort(v1[i] + v2[j]) & ~255) | (i * 16 + j);
;           insert16(Lc, sb);
;         }
	v_med3_i32 v69, v65, v69, v25
	v_med3_i32 v65, v66, v65, v25
	v_med3_i32 v66, v62, v66, v25
	v_med3_i32 v62, v63, v62, v25
	v_med3_i32 v63, v64, v63, v25
	v_med3_i32 v64, v67, v64, v25
	v_med3_i32 v67, v72, v67, v25
	v_max_i32_e32 v25, v72, v25
	v_ashrrev_i32_e32 v72, 31, v24
	v_and_b32_e32 v72, 0x7fffff00, v72
	v_and_b32_e32 v24, 0xffffff00, v24
	v_bitop3_b32 v24, v72, 17, v24 bitop3:0xde
	v_med3_i32 v26, v27, v26, v24
	v_med3_i32 v27, v59, v27, v24
	v_med3_i32 v59, v60, v59, v24
	v_med3_i32 v60, v61, v60, v24
	v_med3_i32 v61, v70, v61, v24
	v_med3_i32 v70, v71, v70, v24
	v_med3_i32 v71, v68, v71, v24
	v_med3_i32 v68, v69, v68, v24
	v_med3_i32 v69, v65, v69, v24
	v_med3_i32 v65, v66, v65, v24
	v_med3_i32 v66, v62, v66, v24
	v_med3_i32 v62, v63, v62, v24
	v_med3_i32 v63, v64, v63, v24
	v_med3_i32 v64, v67, v64, v24
	v_med3_i32 v67, v25, v67, v24
	v_max_i32_e32 v72, v25, v24
	v_pk_add_f32 v[24:25], v[20:21], v[16:17] op_sel_hi:[0,1]
	v_ashrrev_i32_e32 v73, 31, v25
	v_and_b32_e32 v73, 0x7fffff00, v73
	v_and_b32_e32 v25, 0xffffff00, v25
	v_bitop3_b32 v25, v73, 18, v25 bitop3:0xde
	v_med3_i32 v26, v27, v26, v25
	v_med3_i32 v27, v59, v27, v25
	v_med3_i32 v59, v60, v59, v25
	v_med3_i32 v60, v61, v60, v25
	v_med3_i32 v61, v70, v61, v25
	v_med3_i32 v70, v71, v70, v25
	v_med3_i32 v71, v68, v71, v25
	v_med3_i32 v68, v69, v68, v25
	v_med3_i32 v69, v65, v69, v25
	v_med3_i32 v65, v66, v65, v25
	v_med3_i32 v66, v62, v66, v25
	v_med3_i32 v62, v63, v62, v25
	v_med3_i32 v63, v64, v63, v25
	v_med3_i32 v64, v67, v64, v25
	v_med3_i32 v67, v72, v67, v25
	v_max_i32_e32 v25, v72, v25
	v_ashrrev_i32_e32 v72, 31, v24
	v_and_b32_e32 v72, 0x7fffff00, v72
	v_and_b32_e32 v24, 0xffffff00, v24
	v_bitop3_b32 v24, v72, 19, v24 bitop3:0xde
	v_pk_add_f32 v[22:23], v[20:21], v[22:23] op_sel_hi:[0,1]
	v_med3_i32 v26, v27, v26, v24
	v_med3_i32 v27, v59, v27, v24
	v_med3_i32 v59, v60, v59, v24
	v_med3_i32 v60, v61, v60, v24
	v_med3_i32 v61, v70, v61, v24
	v_med3_i32 v70, v71, v70, v24
	v_med3_i32 v71, v68, v71, v24
	v_med3_i32 v68, v69, v68, v24
	v_med3_i32 v69, v65, v69, v24
	v_med3_i32 v65, v66, v65, v24
	v_med3_i32 v66, v62, v66, v24
	v_med3_i32 v62, v63, v62, v24
	v_med3_i32 v63, v64, v63, v24
	v_med3_i32 v64, v67, v64, v24
	v_med3_i32 v67, v25, v67, v24
	v_max_i32_e32 v24, v25, v24
	v_ashrrev_i32_e32 v25, 31, v23
	v_and_b32_e32 v25, 0x7fffff00, v25
	v_and_b32_e32 v23, 0xffffff00, v23
	v_bitop3_b32 v23, v25, 20, v23 bitop3:0xde
	v_med3_i32 v25, v27, v26, v23
	v_med3_i32 v26, v59, v27, v23
	v_med3_i32 v27, v60, v59, v23
	v_med3_i32 v59, v61, v60, v23
	v_med3_i32 v60, v70, v61, v23
	v_med3_i32 v61, v71, v70, v23
	v_med3_i32 v70, v68, v71, v23
	v_med3_i32 v68, v69, v68, v23
	v_med3_i32 v69, v65, v69, v23
	v_med3_i32 v65, v66, v65, v23
	v_med3_i32 v66, v62, v66, v23
	v_med3_i32 v62, v63, v62, v23
	v_med3_i32 v63, v64, v63, v23
	v_med3_i32 v64, v67, v64, v23
	v_med3_i32 v67, v24, v67, v23
	v_max_i32_e32 v23, v24, v23
	v_ashrrev_i32_e32 v24, 31, v22
	v_pk_add_f32 v[18:19], v[20:21], v[18:19] op_sel_hi:[0,1]
	v_and_b32_e32 v24, 0x7fffff00, v24
	v_and_b32_e32 v22, 0xffffff00, v22
	v_ashrrev_i32_e32 v20, 31, v19
	v_bitop3_b32 v22, v24, 21, v22 bitop3:0xde
	v_and_b32_e32 v20, 0x7fffff00, v20
	v_and_b32_e32 v19, 0xffffff00, v19
	v_med3_i32 v24, v26, v25, v22
	v_med3_i32 v25, v27, v26, v22
	v_med3_i32 v26, v59, v27, v22
	v_med3_i32 v27, v60, v59, v22
	v_med3_i32 v59, v61, v60, v22
	v_med3_i32 v60, v70, v61, v22
	v_med3_i32 v61, v68, v70, v22
	v_med3_i32 v68, v69, v68, v22
	v_med3_i32 v69, v65, v69, v22
	v_med3_i32 v65, v66, v65, v22
	v_med3_i32 v66, v62, v66, v22
	v_med3_i32 v62, v63, v62, v22
	v_med3_i32 v63, v64, v63, v22
	v_med3_i32 v64, v67, v64, v22
	v_med3_i32 v67, v23, v67, v22
	v_max_i32_e32 v22, v23, v22
	v_bitop3_b32 v19, v20, 22, v19 bitop3:0xde
	v_med3_i32 v20, v25, v24, v19
	v_med3_i32 v21, v26, v25, v19
	v_med3_i32 v23, v27, v26, v19
	v_med3_i32 v24, v59, v27, v19
	v_med3_i32 v25, v60, v59, v19
	v_med3_i32 v26, v61, v60, v19
	v_med3_i32 v27, v68, v61, v19
	v_med3_i32 v59, v69, v68, v19
	v_med3_i32 v60, v65, v69, v19
	v_med3_i32 v61, v66, v65, v19
	v_med3_i32 v65, v62, v66, v19
	v_med3_i32 v62, v63, v62, v19
	v_med3_i32 v63, v64, v63, v19
	v_med3_i32 v64, v67, v64, v19
	v_med3_i32 v66, v22, v67, v19
	v_max_i32_e32 v19, v22, v19
	v_ashrrev_i32_e32 v22, 31, v18
	v_and_b32_e32 v22, 0x7fffff00, v22
	v_and_b32_e32 v18, 0xffffff00, v18
	v_bitop3_b32 v18, v22, 23, v18 bitop3:0xde
	v_med3_i32 v20, v21, v20, v18
	v_med3_i32 v21, v23, v21, v18
	v_med3_i32 v22, v24, v23, v18
	v_med3_i32 v23, v25, v24, v18
	v_med3_i32 v24, v26, v25, v18
	v_med3_i32 v25, v27, v26, v18
	v_med3_i32 v26, v59, v27, v18
	v_med3_i32 v27, v60, v59, v18
	v_med3_i32 v59, v61, v60, v18
	v_med3_i32 v60, v65, v61, v18
	v_med3_i32 v61, v62, v65, v18
	v_med3_i32 v62, v63, v62, v18
	v_med3_i32 v63, v64, v63, v18
	v_med3_i32 v64, v66, v64, v18
	v_med3_i32 v65, v19, v66, v18
	v_max_i32_e32 v66, v19, v18
	v_pk_add_f32 v[18:19], v[14:15], v[6:7] op_sel_hi:[0,1]
	v_ashrrev_i32_e32 v67, 31, v19
	v_and_b32_e32 v67, 0x7fffff00, v67
	v_and_b32_e32 v19, 0xffffff00, v19
	v_bitop3_b32 v19, v67, 32, v19 bitop3:0xde
	v_med3_i32 v20, v21, v20, v19
	v_med3_i32 v21, v22, v21, v19
	v_med3_i32 v22, v23, v22, v19
	v_med3_i32 v23, v24, v23, v19
	v_med3_i32 v24, v25, v24, v19
	v_med3_i32 v25, v26, v25, v19
	v_med3_i32 v26, v27, v26, v19
	v_med3_i32 v27, v59, v27, v19
	v_med3_i32 v59, v60, v59, v19
	v_med3_i32 v60, v61, v60, v19
	v_med3_i32 v61, v62, v61, v19
	v_med3_i32 v62, v63, v62, v19
	v_med3_i32 v63, v64, v63, v19
	v_med3_i32 v64, v65, v64, v19
	v_med3_i32 v65, v66, v65, v19
	v_max_i32_e32 v19, v66, v19
	v_ashrrev_i32_e32 v66, 31, v18
; DI int f2sort(float f) { int b = __float_as_int(f); return b ^ ((b >> 31) & 0x7fffffff); }
; DI void phase5a(const Params& p, u16* smem) {
;     ...
;     for (int i = 0; i < 16; ++i)
; #pragma unroll
;       for (int j = 0; j < 16; ++j)
;         if ((i + 1) * (j + 1) <= 16) {
;           int sb = (f2sort(v1[i] + v2[j]) & ~255) | (i * 16 + j);
;           insert16(Lc, sb);
;         }
;     unsigned char* my = s_idx + tid * 32;
; #pragma unroll
;     for (int j = 0; j < 4; ++j) {
;       unsigned a = (L[0][4 * j] & 127) | ((L[0][4 * j + 1] & 127) << 8) | ((L[0][4 * j + 2] & 127) << 16) | ((L[0][4 * j + 3] & 127) << 24);
	v_and_b32_e32 v66, 0x7fffff00, v66
	v_and_b32_e32 v18, 0xffffff00, v18
	v_bitop3_b32 v18, v66, 33, v18 bitop3:0xde
	v_pk_add_f32 v[16:17], v[14:15], v[16:17] op_sel_hi:[0,1]
	v_med3_i32 v20, v21, v20, v18
	v_med3_i32 v21, v22, v21, v18
	v_med3_i32 v22, v23, v22, v18
	v_med3_i32 v23, v24, v23, v18
	v_med3_i32 v24, v25, v24, v18
	v_med3_i32 v25, v26, v25, v18
	v_med3_i32 v26, v27, v26, v18
	v_med3_i32 v27, v59, v27, v18
	v_med3_i32 v59, v60, v59, v18
	v_med3_i32 v60, v61, v60, v18
	v_med3_i32 v61, v62, v61, v18
	v_med3_i32 v62, v63, v62, v18
	v_med3_i32 v63, v64, v63, v18
	v_med3_i32 v64, v65, v64, v18
	v_med3_i32 v65, v19, v65, v18
	v_max_i32_e32 v18, v19, v18
	v_ashrrev_i32_e32 v19, 31, v17
	v_and_b32_e32 v19, 0x7fffff00, v19
	v_and_b32_e32 v17, 0xffffff00, v17
	v_bitop3_b32 v17, v19, 34, v17 bitop3:0xde
	v_med3_i32 v19, v21, v20, v17
	v_med3_i32 v20, v22, v21, v17
	v_med3_i32 v21, v23, v22, v17
	v_med3_i32 v22, v24, v23, v17
	v_med3_i32 v23, v25, v24, v17
	v_med3_i32 v24, v26, v25, v17
	v_med3_i32 v25, v27, v26, v17
	v_med3_i32 v26, v59, v27, v17
	v_med3_i32 v27, v60, v59, v17
	v_med3_i32 v59, v61, v60, v17
	v_med3_i32 v60, v62, v61, v17
	v_med3_i32 v61, v63, v62, v17
	v_med3_i32 v62, v64, v63, v17
	v_med3_i32 v63, v65, v64, v17
	v_med3_i32 v64, v18, v65, v17
	v_max_i32_e32 v17, v18, v17
	v_ashrrev_i32_e32 v18, 31, v16
	v_and_b32_e32 v18, 0x7fffff00, v18
	v_and_b32_e32 v16, 0xffffff00, v16
	v_bitop3_b32 v16, v18, 35, v16 bitop3:0xde
	v_med3_i32 v18, v20, v19, v16
	v_med3_i32 v19, v21, v20, v16
	v_med3_i32 v20, v22, v21, v16
	v_med3_i32 v21, v23, v22, v16
	v_med3_i32 v22, v24, v23, v16
	v_med3_i32 v23, v25, v24, v16
	v_med3_i32 v24, v26, v25, v16
	v_med3_i32 v25, v27, v26, v16
	v_med3_i32 v26, v59, v27, v16
	v_med3_i32 v27, v60, v59, v16
	v_med3_i32 v59, v61, v60, v16
	v_med3_i32 v60, v62, v61, v16
	v_med3_i32 v61, v63, v62, v16
	v_med3_i32 v62, v64, v63, v16
	v_med3_i32 v63, v17, v64, v16
	v_max_i32_e32 v64, v17, v16
	v_mov_b32_e32 v16, v12
	v_mov_b32_e32 v17, v14
	v_mov_b32_e32 v14, v3
	v_pk_add_f32 v[14:15], v[16:17], v[14:15]
	v_lshlrev_b32_e32 v32, 24, v32
	v_ashrrev_i32_e32 v16, 31, v15
	v_and_b32_e32 v16, 0x7fffff00, v16
	v_and_b32_e32 v15, 0xffffff00, v15
	v_bitop3_b32 v15, v16, 36, v15 bitop3:0xde
	v_med3_i32 v16, v19, v18, v15
	v_med3_i32 v17, v20, v19, v15
	v_med3_i32 v18, v21, v20, v15
	v_med3_i32 v19, v22, v21, v15
	v_med3_i32 v20, v23, v22, v15
	v_med3_i32 v21, v24, v23, v15
	v_med3_i32 v22, v25, v24, v15
	v_med3_i32 v23, v26, v25, v15
	v_med3_i32 v24, v27, v26, v15
	v_med3_i32 v25, v59, v27, v15
	v_med3_i32 v26, v60, v59, v15
	v_med3_i32 v27, v61, v60, v15
	v_med3_i32 v59, v62, v61, v15
	v_med3_i32 v60, v63, v62, v15
	v_ashrrev_i32_e32 v62, 31, v14
	v_and_b32_e32 v62, 0x7fffff00, v62
	v_and_b32_e32 v14, 0xffffff00, v14
	v_med3_i32 v61, v64, v63, v15
	v_max_i32_e32 v15, v64, v15
	v_bitop3_b32 v14, v62, 48, v14 bitop3:0xde
	v_med3_i32 v62, v17, v16, v14
	v_med3_i32 v63, v18, v17, v14
	v_med3_i32 v18, v19, v18, v14
	v_med3_i32 v19, v20, v19, v14
	v_med3_i32 v20, v21, v20, v14
	v_med3_i32 v21, v22, v21, v14
	v_med3_i32 v22, v23, v22, v14
	v_med3_i32 v23, v24, v23, v14
	v_med3_i32 v24, v25, v24, v14
	v_med3_i32 v25, v26, v25, v14
	v_med3_i32 v26, v27, v26, v14
	v_med3_i32 v27, v59, v27, v14
	v_med3_i32 v59, v60, v59, v14
	v_med3_i32 v60, v61, v60, v14
	v_med3_i32 v61, v15, v61, v14
	v_max_i32_e32 v64, v15, v14
	v_mov_b32_e32 v14, v11
	v_mov_b32_e32 v15, v5
	v_pk_add_f32 v[16:17], v[12:13], v[14:15] op_sel_hi:[0,1]
	v_ashrrev_i32_e32 v65, 31, v17
	v_and_b32_e32 v65, 0x7fffff00, v65
	v_and_b32_e32 v17, 0xffffff00, v17
	v_bitop3_b32 v17, v65, 49, v17 bitop3:0xde
	v_med3_i32 v62, v63, v62, v17
	v_med3_i32 v63, v18, v63, v17
	v_med3_i32 v18, v19, v18, v17
	v_med3_i32 v19, v20, v19, v17
	v_med3_i32 v20, v21, v20, v17
	v_med3_i32 v21, v22, v21, v17
	v_med3_i32 v22, v23, v22, v17
	v_med3_i32 v23, v24, v23, v17
	v_med3_i32 v24, v25, v24, v17
	v_med3_i32 v25, v26, v25, v17
	v_med3_i32 v26, v27, v26, v17
	v_med3_i32 v27, v59, v27, v17
	v_med3_i32 v59, v60, v59, v17
	v_med3_i32 v60, v61, v60, v17
	v_med3_i32 v61, v64, v61, v17
	v_max_i32_e32 v17, v64, v17
	v_ashrrev_i32_e32 v64, 31, v16
	v_and_b32_e32 v64, 0x7fffff00, v64
	v_and_b32_e32 v16, 0xffffff00, v16
	v_bitop3_b32 v16, v64, 50, v16 bitop3:0xde
	v_med3_i32 v62, v63, v62, v16
	v_med3_i32 v63, v18, v63, v16
	v_med3_i32 v18, v19, v18, v16
	v_med3_i32 v19, v20, v19, v16
	v_med3_i32 v20, v21, v20, v16
	v_med3_i32 v21, v22, v21, v16
	v_med3_i32 v22, v23, v22, v16
	v_med3_i32 v23, v24, v23, v16
	v_med3_i32 v24, v25, v24, v16
	v_med3_i32 v25, v26, v25, v16
	v_med3_i32 v26, v27, v26, v16
	v_med3_i32 v27, v59, v27, v16
	v_med3_i32 v59, v60, v59, v16
	v_med3_i32 v60, v61, v60, v16
	v_med3_i32 v61, v17, v61, v16
	v_max_i32_e32 v64, v17, v16
	v_mov_b32_e32 v16, v10
	v_mov_b32_e32 v17, v12
	v_mov_b32_e32 v12, v3
	v_pk_add_f32 v[12:13], v[16:17], v[12:13]
	v_pk_add_f32 v[10:11], v[10:11], v[14:15] op_sel_hi:[0,1]
	v_ashrrev_i32_e32 v16, 31, v13
	v_and_b32_e32 v16, 0x7fffff00, v16
	v_and_b32_e32 v13, 0xffffff00, v13
	v_bitop3_b32 v13, v16, 51, v13 bitop3:0xde
	v_med3_i32 v16, v63, v62, v13
	v_ashrrev_i32_e32 v62, 31, v12
	v_and_b32_e32 v62, 0x7fffff00, v62
	v_and_b32_e32 v12, 0xffffff00, v12
	v_med3_i32 v17, v18, v63, v13
	v_med3_i32 v18, v19, v18, v13
	v_med3_i32 v19, v20, v19, v13
	v_med3_i32 v20, v21, v20, v13
	v_med3_i32 v21, v22, v21, v13
	v_med3_i32 v22, v23, v22, v13
	v_med3_i32 v23, v24, v23, v13
	v_med3_i32 v24, v25, v24, v13
	v_med3_i32 v25, v26, v25, v13
	v_med3_i32 v26, v27, v26, v13
	v_med3_i32 v27, v59, v27, v13
	v_med3_i32 v59, v60, v59, v13
	v_med3_i32 v60, v61, v60, v13
; DI int med3i(int a, int b, int c) { int r; asm("v_med3_i32 %0, %1, %2, %3" : "=v"(r) : "v"(a), "v"(b), "v"(c)); return r; }
; DI void insert16(int (&L)[16], int x) {
; #pragma unroll
;   for (int j = 15; j >= 1; --j) L[j] = med3i(L[j - 1], L[j], x);
;   L[0] = max(L[0], x);
; }
; DI int f2sort(float f) { int b = __float_as_int(f); return b ^ ((b >> 31) & 0x7fffffff); }
; DI float sort2f(int b) { return __int_as_float(b ^ ((b >> 31) & 0x7fffffff)); }
; DI void phase5a(const Params& p, u16* smem) {
;     ...
;     for (int i = 0; i < 16; ++i)
; #pragma unroll
;       for (int j = 0; j < 16; ++j)
;         if ((i + 1) * (j + 1) <= 16) {
;           int sb = (f2sort(v1[i] + v2[j]) & ~255) | (i * 16 + j);
;           insert16(Lc, sb);
;         }
	v_med3_i32 v61, v64, v61, v13
	v_max_i32_e32 v13, v64, v13
	v_bitop3_b32 v12, v62, 64, v12 bitop3:0xde
	v_med3_i32 v16, v17, v16, v12
	v_med3_i32 v17, v18, v17, v12
	v_med3_i32 v18, v19, v18, v12
	v_med3_i32 v19, v20, v19, v12
	v_med3_i32 v20, v21, v20, v12
	v_med3_i32 v21, v22, v21, v12
	v_med3_i32 v22, v23, v22, v12
	v_med3_i32 v23, v24, v23, v12
	v_med3_i32 v24, v25, v24, v12
	v_med3_i32 v25, v26, v25, v12
	v_med3_i32 v26, v27, v26, v12
	v_med3_i32 v27, v59, v27, v12
	v_med3_i32 v59, v60, v59, v12
	v_med3_i32 v60, v61, v60, v12
	v_med3_i32 v61, v13, v61, v12
	v_max_i32_e32 v12, v13, v12
	v_ashrrev_i32_e32 v13, 31, v11
	v_and_b32_e32 v13, 0x7fffff00, v13
	v_and_b32_e32 v11, 0xffffff00, v11
	v_bitop3_b32 v11, v13, s38, v11 bitop3:0xde
	v_med3_i32 v13, v17, v16, v11
	v_med3_i32 v14, v18, v17, v11
	v_med3_i32 v15, v19, v18, v11
	v_med3_i32 v16, v20, v19, v11
	v_med3_i32 v17, v21, v20, v11
	v_med3_i32 v18, v22, v21, v11
	v_med3_i32 v19, v23, v22, v11
	v_med3_i32 v20, v24, v23, v11
	v_med3_i32 v21, v25, v24, v11
	v_med3_i32 v22, v26, v25, v11
	v_med3_i32 v23, v27, v26, v11
	v_med3_i32 v24, v59, v27, v11
	v_med3_i32 v25, v60, v59, v11
	v_med3_i32 v26, v61, v60, v11
	v_med3_i32 v27, v12, v61, v11
	v_max_i32_e32 v11, v12, v11
	v_ashrrev_i32_e32 v12, 31, v10
	v_and_b32_e32 v12, 0x7fffff00, v12
	v_and_b32_e32 v10, 0xffffff00, v10
	v_bitop3_b32 v10, v12, s39, v10 bitop3:0xde
	v_med3_i32 v12, v14, v13, v10
	v_med3_i32 v13, v15, v14, v10
	v_med3_i32 v14, v16, v15, v10
	v_med3_i32 v15, v17, v16, v10
	v_med3_i32 v16, v18, v17, v10
	v_med3_i32 v17, v19, v18, v10
	v_med3_i32 v18, v20, v19, v10
	v_med3_i32 v19, v21, v20, v10
	v_med3_i32 v20, v22, v21, v10
	v_med3_i32 v21, v23, v22, v10
	v_med3_i32 v22, v24, v23, v10
	v_med3_i32 v23, v25, v24, v10
	v_med3_i32 v24, v26, v25, v10
	v_med3_i32 v25, v27, v26, v10
	v_med3_i32 v26, v11, v27, v10
	v_max_i32_e32 v27, v11, v10
	v_pk_add_f32 v[10:11], v[8:9], v[6:7] op_sel_hi:[0,1]
	v_ashrrev_i32_e32 v8, 31, v11
	v_and_b32_e32 v8, 0x7fffff00, v8
	v_and_b32_e32 v11, 0xffffff00, v11
	v_bitop3_b32 v8, v8, s45, v11 bitop3:0xde
	v_med3_i32 v11, v13, v12, v8
	v_med3_i32 v12, v14, v13, v8
	v_med3_i32 v13, v15, v14, v8
	v_med3_i32 v14, v16, v15, v8
	v_med3_i32 v15, v17, v16, v8
	v_med3_i32 v16, v18, v17, v8
	v_med3_i32 v17, v19, v18, v8
	v_med3_i32 v18, v20, v19, v8
	v_med3_i32 v19, v21, v20, v8
	v_med3_i32 v20, v22, v21, v8
	v_med3_i32 v21, v23, v22, v8
	v_med3_i32 v22, v24, v23, v8
	v_med3_i32 v23, v25, v24, v8
	v_med3_i32 v24, v26, v25, v8
	v_med3_i32 v25, v27, v26, v8
	v_ashrrev_i32_e32 v26, 31, v10
	v_and_b32_e32 v26, 0x7fffff00, v26
	v_and_b32_e32 v10, 0xffffff00, v10
	v_max_i32_e32 v8, v27, v8
	v_bitop3_b32 v10, v26, s46, v10 bitop3:0xde
	v_med3_i32 v26, v12, v11, v10
	v_med3_i32 v12, v13, v12, v10
	v_med3_i32 v13, v14, v13, v10
	v_med3_i32 v14, v15, v14, v10
	v_med3_i32 v15, v16, v15, v10
	v_med3_i32 v16, v17, v16, v10
	v_med3_i32 v17, v18, v17, v10
	v_med3_i32 v18, v19, v18, v10
	v_med3_i32 v19, v20, v19, v10
	v_med3_i32 v20, v21, v20, v10
	v_med3_i32 v21, v22, v21, v10
	v_med3_i32 v22, v23, v22, v10
	v_med3_i32 v23, v24, v23, v10
	v_med3_i32 v24, v25, v24, v10
	v_med3_i32 v25, v8, v25, v10
	v_max_i32_e32 v8, v8, v10
	v_pk_add_f32 v[10:11], v[0:1], v[6:7] op_sel_hi:[0,1]
	v_ashrrev_i32_e32 v0, 31, v11
	v_and_b32_e32 v0, 0x7fffff00, v0
	v_and_b32_e32 v11, 0xffffff00, v11
	v_bitop3_b32 v0, v0, s53, v11 bitop3:0xde
	v_med3_i32 v11, v12, v26, v0
	v_med3_i32 v12, v13, v12, v0
	v_med3_i32 v13, v14, v13, v0
	v_med3_i32 v14, v15, v14, v0
	v_med3_i32 v15, v16, v15, v0
	v_med3_i32 v16, v17, v16, v0
	v_med3_i32 v17, v18, v17, v0
	v_med3_i32 v18, v19, v18, v0
	v_med3_i32 v19, v20, v19, v0
	v_med3_i32 v20, v21, v20, v0
	v_med3_i32 v21, v22, v21, v0
	v_med3_i32 v22, v23, v22, v0
	v_med3_i32 v23, v24, v23, v0
	v_med3_i32 v24, v25, v24, v0
	v_med3_i32 v25, v8, v25, v0
	v_max_i32_e32 v0, v8, v0
	v_ashrrev_i32_e32 v8, 31, v10
	v_pk_add_f32 v[4:5], v[4:5], v[6:7] op_sel_hi:[0,1]
	v_and_b32_e32 v8, 0x7fffff00, v8
	v_and_b32_e32 v10, 0xffffff00, v10
	v_ashrrev_i32_e32 v6, 31, v5
	v_bitop3_b32 v8, v8, s56, v10 bitop3:0xde
	v_and_b32_e32 v6, 0x7fffff00, v6
	v_and_b32_e32 v5, 0xffffff00, v5
	v_med3_i32 v10, v12, v11, v8
	v_med3_i32 v11, v13, v12, v8
	v_med3_i32 v12, v14, v13, v8
	v_med3_i32 v13, v15, v14, v8
	v_med3_i32 v14, v16, v15, v8
	v_med3_i32 v15, v17, v16, v8
	v_med3_i32 v16, v18, v17, v8
	v_med3_i32 v17, v19, v18, v8
	v_med3_i32 v18, v20, v19, v8
	v_med3_i32 v19, v21, v20, v8
	v_med3_i32 v20, v22, v21, v8
	v_med3_i32 v21, v23, v22, v8
	v_med3_i32 v22, v24, v23, v8
	v_med3_i32 v23, v25, v24, v8
	v_med3_i32 v24, v0, v25, v8
	v_max_i32_e32 v0, v0, v8
	v_bitop3_b32 v5, v6, s63, v5 bitop3:0xde
	v_med3_i32 v6, v11, v10, v5
	v_med3_i32 v7, v12, v11, v5
	v_med3_i32 v8, v13, v12, v5
	v_med3_i32 v10, v14, v13, v5
	v_med3_i32 v11, v15, v14, v5
	v_med3_i32 v12, v16, v15, v5
	v_med3_i32 v13, v17, v16, v5
	v_med3_i32 v14, v18, v17, v5
	v_med3_i32 v15, v19, v18, v5
	v_med3_i32 v16, v20, v19, v5
	v_med3_i32 v17, v21, v20, v5
	v_med3_i32 v18, v22, v21, v5
	v_med3_i32 v19, v23, v22, v5
	v_med3_i32 v20, v24, v23, v5
	v_med3_i32 v21, v0, v24, v5
	v_max_i32_e32 v0, v0, v5
	v_ashrrev_i32_e32 v5, 31, v4
	v_and_b32_e32 v5, 0x7fffff00, v5
	v_and_b32_e32 v4, 0xffffff00, v4
	v_bitop3_b32 v4, v5, s64, v4 bitop3:0xde
	v_ashrrev_i32_e32 v5, 31, v39
	v_ashrrev_i32_e32 v23, 31, v38
	v_med3_i32 v6, v7, v6, v4
	v_med3_i32 v7, v8, v7, v4
	v_med3_i32 v8, v10, v8, v4
	v_med3_i32 v10, v11, v10, v4
	v_med3_i32 v11, v12, v11, v4
	v_med3_i32 v12, v13, v12, v4
	v_med3_i32 v13, v14, v13, v4
	v_med3_i32 v14, v15, v14, v4
	v_med3_i32 v15, v16, v15, v4
	v_med3_i32 v16, v17, v16, v4
; DI int f2sort(float f) { int b = __float_as_int(f); return b ^ ((b >> 31) & 0x7fffffff); }
; DI float sort2f(int b) { return __int_as_float(b ^ ((b >> 31) & 0x7fffffff)); }
; DI void phase5a(const Params& p, u16* smem) {
;     ...
;     for (int j = 0; j < 16; ++j) { v1[j] = sort2f(L[0][j] & ~127); v2[j] = sort2f(L[1][j] & ~127); }
;     int Lc[16];
; #pragma unroll
;     for (int j = 0; j < 16; ++j) Lc[j] = (int)0x80000000;
; #pragma unroll
;     for (int i = 0; i < 16; ++i)
; #pragma unroll
;       for (int j = 0; j < 16; ++j)
;         if ((i + 1) * (j + 1) <= 16) {
;           int sb = (f2sort(v1[i] + v2[j]) & ~255) | (i * 16 + j);
;           insert16(Lc, sb);
;         }
;     ...
;       unsigned a = (L[0][4 * j] & 127) | ((L[0][4 * j + 1] & 127) << 8) | ((L[0][4 * j + 2] & 127) << 16) | ((L[0][4 * j + 3] & 127) << 24);
;       unsigned b = (L[1][4 * j] & 127) | ((L[1][4 * j + 1] & 127) << 8) | ((L[1][4 * j + 2] & 127) << 16) | ((L[1][4 * j + 3] & 127) << 24);
	v_med3_i32 v17, v18, v17, v4
	v_med3_i32 v18, v19, v18, v4
	v_med3_i32 v19, v20, v19, v4
	v_med3_i32 v20, v21, v20, v4
	v_med3_i32 v21, v0, v21, v4
	v_max_i32_e32 v0, v0, v4
	v_and_b32_e32 v4, 0xffffff80, v39
	v_and_b32_e32 v22, 0xffffff80, v38
	v_and_b32_e32 v5, 0x7fffffff, v5
	v_and_b32_e32 v23, 0x7fffffff, v23
	v_xor_b32_e32 v5, v5, v4
	v_xor_b32_e32 v4, v23, v22
	v_pk_add_f32 v[4:5], v[2:3], v[4:5] op_sel:[1,0]
	v_ashrrev_i32_e32 v23, 31, v35
	v_ashrrev_i32_e32 v22, 31, v5
	v_and_b32_e32 v22, 0x7fffff00, v22
	v_and_b32_e32 v5, 0xffffff00, v5
	v_bitop3_b32 v5, v22, s73, v5 bitop3:0xde
	v_med3_i32 v6, v7, v6, v5
	v_med3_i32 v7, v8, v7, v5
	v_med3_i32 v8, v10, v8, v5
	v_med3_i32 v10, v11, v10, v5
	v_med3_i32 v11, v12, v11, v5
	v_med3_i32 v12, v13, v12, v5
	v_med3_i32 v13, v14, v13, v5
	v_med3_i32 v14, v15, v14, v5
	v_med3_i32 v15, v16, v15, v5
	v_med3_i32 v16, v17, v16, v5
	v_med3_i32 v17, v18, v17, v5
	v_med3_i32 v18, v19, v18, v5
	v_med3_i32 v19, v20, v19, v5
	v_med3_i32 v20, v21, v20, v5
	v_med3_i32 v21, v0, v21, v5
	v_max_i32_e32 v0, v0, v5
	v_ashrrev_i32_e32 v5, 31, v4
	v_and_b32_e32 v5, 0x7fffff00, v5
	v_and_b32_e32 v4, 0xffffff00, v4
	v_bitop3_b32 v4, v5, s74, v4 bitop3:0xde
	v_ashrrev_i32_e32 v5, 31, v34
	v_med3_i32 v6, v7, v6, v4
	v_med3_i32 v7, v8, v7, v4
	v_med3_i32 v8, v10, v8, v4
	v_med3_i32 v10, v11, v10, v4
	v_med3_i32 v11, v12, v11, v4
	v_med3_i32 v12, v13, v12, v4
	v_med3_i32 v13, v14, v13, v4
	v_med3_i32 v14, v15, v14, v4
	v_med3_i32 v15, v16, v15, v4
	v_med3_i32 v16, v17, v16, v4
	v_med3_i32 v17, v18, v17, v4
	v_med3_i32 v18, v19, v18, v4
	v_med3_i32 v19, v20, v19, v4
	v_med3_i32 v20, v21, v20, v4
	v_med3_i32 v21, v0, v21, v4
	v_max_i32_e32 v0, v0, v4
	v_and_b32_e32 v4, 0xffffff80, v34
	v_and_b32_e32 v22, 0xffffff80, v35
	v_and_b32_e32 v5, 0x7fffffff, v5
	v_and_b32_e32 v23, 0x7fffffff, v23
	v_xor_b32_e32 v5, v5, v4
	v_xor_b32_e32 v4, v23, v22
	v_pk_add_f32 v[4:5], v[2:3], v[4:5] op_sel:[1,0]
	v_ashrrev_i32_e32 v23, 31, v36
	v_ashrrev_i32_e32 v22, 31, v5
	v_and_b32_e32 v22, 0x7fffff00, v22
	v_and_b32_e32 v5, 0xffffff00, v5
	v_bitop3_b32 v5, v22, s75, v5 bitop3:0xde
	v_med3_i32 v6, v7, v6, v5
	v_med3_i32 v7, v8, v7, v5
	v_med3_i32 v8, v10, v8, v5
	v_med3_i32 v10, v11, v10, v5
	v_med3_i32 v11, v12, v11, v5
	v_med3_i32 v12, v13, v12, v5
	v_med3_i32 v13, v14, v13, v5
	v_med3_i32 v14, v15, v14, v5
	v_med3_i32 v15, v16, v15, v5
	v_med3_i32 v16, v17, v16, v5
	v_med3_i32 v17, v18, v17, v5
	v_med3_i32 v18, v19, v18, v5
	v_med3_i32 v19, v20, v19, v5
	v_med3_i32 v20, v21, v20, v5
	v_med3_i32 v21, v0, v21, v5
	v_max_i32_e32 v0, v0, v5
	v_ashrrev_i32_e32 v5, 31, v4
	v_and_b32_e32 v5, 0x7fffff00, v5
	v_and_b32_e32 v4, 0xffffff00, v4
	v_bitop3_b32 v4, v5, s76, v4 bitop3:0xde
	v_ashrrev_i32_e32 v5, 31, v37
	v_med3_i32 v6, v7, v6, v4
	v_med3_i32 v7, v8, v7, v4
	v_med3_i32 v8, v10, v8, v4
	v_med3_i32 v10, v11, v10, v4
	v_med3_i32 v11, v12, v11, v4
	v_med3_i32 v12, v13, v12, v4
	v_med3_i32 v13, v14, v13, v4
	v_med3_i32 v14, v15, v14, v4
	v_med3_i32 v15, v16, v15, v4
	v_med3_i32 v16, v17, v16, v4
	v_med3_i32 v17, v18, v17, v4
	v_med3_i32 v18, v19, v18, v4
	v_med3_i32 v19, v20, v19, v4
	v_med3_i32 v20, v21, v20, v4
	v_med3_i32 v21, v0, v21, v4
	v_max_i32_e32 v0, v0, v4
	v_and_b32_e32 v4, 0xffffff80, v37
	v_and_b32_e32 v22, 0xffffff80, v36
	v_and_b32_e32 v5, 0x7fffffff, v5
	v_and_b32_e32 v23, 0x7fffffff, v23
	v_xor_b32_e32 v5, v5, v4
	v_xor_b32_e32 v4, v23, v22
	v_pk_add_f32 v[4:5], v[2:3], v[4:5] op_sel:[1,0]
	v_and_b32_e32 v32, 0x7f000000, v32
	v_ashrrev_i32_e32 v22, 31, v5
	v_and_b32_e32 v22, 0x7fffff00, v22
	v_and_b32_e32 v5, 0xffffff00, v5
	v_bitop3_b32 v5, v22, s77, v5 bitop3:0xde
	v_med3_i32 v6, v7, v6, v5
	v_med3_i32 v7, v8, v7, v5
	v_med3_i32 v8, v10, v8, v5
	v_med3_i32 v10, v11, v10, v5
	v_med3_i32 v11, v12, v11, v5
	v_med3_i32 v12, v13, v12, v5
	v_med3_i32 v13, v14, v13, v5
	v_med3_i32 v14, v15, v14, v5
	v_med3_i32 v15, v16, v15, v5
	v_med3_i32 v16, v17, v16, v5
	v_med3_i32 v17, v18, v17, v5
	v_med3_i32 v18, v19, v18, v5
	v_med3_i32 v19, v20, v19, v5
	v_med3_i32 v20, v21, v20, v5
	v_med3_i32 v21, v0, v21, v5
	v_max_i32_e32 v0, v0, v5
	v_ashrrev_i32_e32 v5, 31, v4
	v_and_b32_e32 v5, 0x7fffff00, v5
	v_and_b32_e32 v4, 0xffffff00, v4
	v_bitop3_b32 v4, v5, s78, v4 bitop3:0xde
	v_med3_i32 v5, v7, v6, v4
	v_med3_i32 v6, v8, v7, v4
	v_med3_i32 v7, v10, v8, v4
	v_med3_i32 v8, v11, v10, v4
	v_med3_i32 v10, v12, v11, v4
	v_med3_i32 v11, v13, v12, v4
	v_med3_i32 v12, v14, v13, v4
	v_med3_i32 v13, v15, v14, v4
	v_med3_i32 v14, v16, v15, v4
	v_med3_i32 v15, v17, v16, v4
	v_med3_i32 v16, v18, v17, v4
	v_med3_i32 v17, v19, v18, v4
	v_med3_i32 v18, v20, v19, v4
	v_med3_i32 v19, v21, v20, v4
	v_med3_i32 v20, v0, v21, v4
	v_max_i32_e32 v4, v0, v4
	v_mov_b32_e32 v0, v2
	v_pk_add_f32 v[2:3], v[2:3], v[0:1] op_sel:[1,0]
	v_lshlrev_b32_e32 v9, 24, v9
	v_ashrrev_i32_e32 v0, 31, v3
	v_and_b32_e32 v0, 0x7fffff00, v0
	v_and_b32_e32 v1, 0xffffff00, v3
	v_bitop3_b32 v0, v0, s79, v1 bitop3:0xde
	v_ashrrev_i32_e32 v1, 31, v2
	v_med3_i32 v3, v6, v5, v0
	v_med3_i32 v5, v7, v6, v0
	v_med3_i32 v6, v8, v7, v0
	v_med3_i32 v7, v10, v8, v0
	v_med3_i32 v8, v11, v10, v0
	v_med3_i32 v10, v12, v11, v0
	v_med3_i32 v25, v19, v18, v0
	v_med3_i32 v26, v20, v19, v0
	v_and_b32_e32 v1, 0x7fffff00, v1
	v_and_b32_e32 v2, 0xffffff00, v2
	v_med3_i32 v11, v13, v12, v0
	v_med3_i32 v22, v16, v15, v0
	v_med3_i32 v23, v17, v16, v0
	v_med3_i32 v24, v18, v17, v0
	v_med3_i32 v27, v4, v20, v0
	v_bitop3_b32 v1, v1, s36, v2 bitop3:0xde
	v_med3_i32 v21, v5, v3, v1
	v_med3_i32 v19, v7, v6, v1
	v_med3_i32 v18, v8, v7, v1
	v_med3_i32 v17, v10, v8, v1
	v_med3_i32 v16, v11, v10, v1
; DI float sort2f(int b) { return __int_as_float(b ^ ((b >> 31) & 0x7fffffff)); }
; DI void phase5a(const Params& p, u16* smem) {
;     ...
;     unsigned char* my = s_idx + tid * 32;
; #pragma unroll
;     for (int j = 0; j < 4; ++j) {
;       unsigned a = (L[0][4 * j] & 127) | ((L[0][4 * j + 1] & 127) << 8) | ((L[0][4 * j + 2] & 127) << 16) | ((L[0][4 * j + 3] & 127) << 24);
;       unsigned b = (L[1][4 * j] & 127) | ((L[1][4 * j + 1] & 127) << 8) | ((L[1][4 * j + 2] & 127) << 16) | ((L[1][4 * j + 3] & 127) << 24);
;       ((unsigned*)my)[j] = a; ((unsigned*)my)[4 + j] = b;
;     }
;     __syncthreads();
;     float sc[16]; int ee[16];
; #pragma unroll
;     for (int n = 0; n < 16; ++n) {
;       int id = Lc[n] & 255;
;       sc[n] = sort2f(Lc[n] & ~255);
;       int i1 = my[id >> 4], i2 = my[16 + (id & 15)];
;       ee[n] = i1 * 128 + i2;
;     }
;     float den = 0.f;
;     {
;       const float mxv = sc[0];
; #pragma unroll
;       for (int n = 0; n < 16; ++n) { sc[n] = __expf(sc[n] - mxv); den += sc[n]; }
	v_med3_i32 v10, v25, v24, v1
	v_med3_i32 v8, v26, v25, v1
	v_med3_i32 v7, v27, v26, v1
	v_lshlrev_b32_e32 v3, 24, v43
	v_lshlrev_b32_e32 v25, 16, v40
	v_lshlrev_b32_e32 v26, 24, v41
	v_med3_i32 v12, v14, v13, v0
	v_med3_i32 v13, v15, v14, v0
	v_max_i32_e32 v0, v4, v0
	v_med3_i32 v20, v6, v5, v1
	v_med3_i32 v6, v0, v27, v1
	v_lshlrev_b32_e32 v2, 16, v47
	v_and_b32_e32 v25, 0x7f0000, v25
	v_and_b32_e32 v26, 0x7f000000, v26
	v_and_b32_e32 v3, 0x7f000000, v3
	v_and_b32_e32 v27, 0x7f, v42
	v_and_b32_e32 v2, 0x7f0000, v2
	v_or_b32_e32 v3, v25, v3
	v_or_b32_e32 v25, v26, v27
	v_med3_i32 v15, v12, v11, v1
	v_med3_i32 v14, v13, v12, v1
	v_med3_i32 v13, v22, v13, v1
	v_med3_i32 v12, v23, v22, v1
	v_med3_i32 v11, v24, v23, v1
	v_lshlrev_b32_e32 v5, 24, v57
	v_and_b32_e32 v22, 0x7f, v45
	v_lshlrev_b32_e32 v23, 8, v44
	v_lshlrev_b32_e32 v24, 8, v46
	v_or_b32_e32 v2, v25, v2
	v_lshlrev_b32_e32 v25, 16, v51
	v_lshlrev_b32_e32 v26, 24, v52
	v_lshlrev_b32_e32 v4, 16, v58
	v_and_b32_e32 v23, 0x7f00, v23
	v_and_b32_e32 v24, 0x7f00, v24
	v_or_b32_e32 v3, v3, v22
	v_and_b32_e32 v25, 0x7f0000, v25
	v_and_b32_e32 v26, 0x7f000000, v26
	v_and_b32_e32 v5, 0x7f000000, v5
	v_and_b32_e32 v27, 0x7f, v53
	v_or_b32_e32 v3, v3, v23
	v_or_b32_e32 v2, v2, v24
	v_and_b32_e32 v22, 0x7f, v55
	v_and_b32_e32 v4, 0x7f0000, v4
	v_lshlrev_b32_e32 v23, 8, v54
	v_lshlrev_b32_e32 v24, 8, v56
	v_or_b32_e32 v5, v25, v5
	v_or_b32_e32 v25, v26, v27
	v_lshlrev_b32_e32 v26, 16, v33
	v_lshlrev_b32_e32 v27, 24, v35
	v_lshlrev_b32_e32 v33, 16, v34
	v_and_b32_e32 v23, 0x7f00, v23
	v_and_b32_e32 v24, 0x7f00, v24
	v_or_b32_e32 v5, v5, v22
	v_or_b32_e32 v4, v25, v4
	v_and_b32_e32 v26, 0x7f0000, v26
	v_and_b32_e32 v27, 0x7f000000, v27
	v_and_b32_e32 v33, 0x7f0000, v33
	v_or_b32_e32 v23, v5, v23
	v_or_b32_e32 v22, v4, v24
	v_and_b32_e32 v4, 0x7f, v37
	v_and_b32_e32 v5, 0x7f, v39
	v_lshlrev_b32_e32 v24, 8, v36
	v_lshlrev_b32_e32 v25, 8, v38
	v_or_b32_e32 v26, v26, v32
	v_or_b32_e32 v27, v27, v33
	v_and_b32_e32 v24, 0x7f00, v24
	v_and_b32_e32 v25, 0x7f00, v25
	v_or_b32_e32 v4, v26, v4
	v_or_b32_e32 v26, v27, v5
	v_or_b32_e32 v5, v4, v24
	v_or_b32_e32 v4, v26, v25
	v_lshlrev_b32_e32 v24, 16, v28
	v_lshlrev_b32_e32 v25, 24, v30
	v_lshlrev_b32_e32 v26, 16, v29
	v_and_b32_e32 v24, 0x7f0000, v24
	v_and_b32_e32 v25, 0x7f000000, v25
	v_and_b32_e32 v9, 0x7f000000, v9
	v_and_b32_e32 v26, 0x7f0000, v26
	ds_write_b128 v199, v[2:5] offset:33792
	v_and_b32_e32 v2, 0x7f, v48
	v_and_b32_e32 v3, 0x7f, v50
	v_lshlrev_b32_e32 v4, 8, v31
	v_lshlrev_b32_e32 v5, 8, v49
	v_or_b32_e32 v9, v24, v9
	v_or_b32_e32 v24, v25, v26
	v_and_b32_e32 v4, 0x7f00, v4
	v_and_b32_e32 v5, 0x7f00, v5
	v_or_b32_e32 v2, v9, v2
	v_or_b32_e32 v3, v24, v3
	v_or_b32_e32 v25, v2, v4
	v_or_b32_e32 v24, v3, v5
	ds_write_b128 v199, v[22:25] offset:33808
	s_waitcnt lgkmcnt(0)
	s_barrier
	s_and_saveexec_b64 s[28:29], s[8:9]
	s_cbranch_execz .LBB0_358
	v_max_i32_e32 v9, v0, v1
	v_ashrrev_i32_e32 v0, 31, v6
	v_and_b32_e32 v1, 0xffffff00, v6
	v_bitop3_b32 v0, v0, v1, s71 bitop3:0x6c
	v_ashrrev_i32_e32 v1, 31, v7
	v_and_b32_e32 v2, 0xffffff00, v7
	v_bitop3_b32 v1, v1, v2, s71 bitop3:0x6c
	v_ashrrev_i32_e32 v2, 31, v8
	v_and_b32_e32 v3, 0xffffff00, v8
	v_bitop3_b32 v2, v2, v3, s71 bitop3:0x6c
	v_ashrrev_i32_e32 v3, 31, v10
	v_and_b32_e32 v4, 0xffffff00, v10
	v_bitop3_b32 v3, v3, v4, s71 bitop3:0x6c
	v_ashrrev_i32_e32 v4, 31, v11
	v_and_b32_e32 v5, 0xffffff00, v11
	v_bitop3_b32 v24, v4, v5, s71 bitop3:0x6c
	v_ashrrev_i32_e32 v4, 31, v12
	v_and_b32_e32 v5, 0xffffff00, v12
	v_bitop3_b32 v25, v4, v5, s71 bitop3:0x6c
	v_ashrrev_i32_e32 v4, 31, v13
	v_and_b32_e32 v5, 0xffffff00, v13
	v_bitop3_b32 v26, v4, v5, s71 bitop3:0x6c
	v_ashrrev_i32_e32 v4, 31, v14
	v_and_b32_e32 v5, 0xffffff00, v14
	v_bitop3_b32 v27, v4, v5, s71 bitop3:0x6c
	v_ashrrev_i32_e32 v4, 31, v15
	v_and_b32_e32 v5, 0xffffff00, v15
	v_bitop3_b32 v28, v4, v5, s71 bitop3:0x6c
	v_ashrrev_i32_e32 v4, 31, v16
	v_and_b32_e32 v5, 0xffffff00, v16
	v_bitop3_b32 v29, v4, v5, s71 bitop3:0x6c
	v_ashrrev_i32_e32 v4, 31, v17
	v_and_b32_e32 v5, 0xffffff00, v17
	v_bitop3_b32 v30, v4, v5, s71 bitop3:0x6c
	v_ashrrev_i32_e32 v4, 31, v18
	v_and_b32_e32 v5, 0xffffff00, v18
	v_bitop3_b32 v31, v4, v5, s71 bitop3:0x6c
	v_ashrrev_i32_e32 v4, 31, v19
	v_and_b32_e32 v5, 0xffffff00, v19
	v_bitop3_b32 v32, v4, v5, s71 bitop3:0x6c
	v_ashrrev_i32_e32 v4, 31, v20
	v_and_b32_e32 v5, 0xffffff00, v20
	v_bitop3_b32 v33, v4, v5, s71 bitop3:0x6c
	v_ashrrev_i32_e32 v5, 31, v9
	v_and_b32_e32 v5, 0x7fffffff, v5
	v_and_b32_e32 v22, 0xffffff00, v9
	v_xor_b32_e32 v34, v5, v22
	v_sub_f32_e32 v0, v0, v34
	v_mul_f32_e32 v0, 0x3fb8aa3b, v0
	v_exp_f32_e32 v5, v0
	v_sub_f32_e32 v0, v1, v34
	v_sub_f32_e32 v1, v3, v34
	v_ashrrev_i32_e32 v4, 31, v21
	v_mul_f32_e32 v0, 0x3fb8aa3b, v0
	v_mul_f32_e32 v1, 0x3fb8aa3b, v1
	v_and_b32_e32 v4, 0x7fffffff, v4
	v_and_b32_e32 v23, 0xffffff00, v21
	v_exp_f32_e32 v22, v0
	v_sub_f32_e32 v0, v2, v34
	v_exp_f32_e32 v2, v1
	v_sub_f32_e32 v1, v24, v34
	v_xor_b32_e32 v35, v4, v23
	v_sub_f32_e32 v4, v34, v34
	v_mul_f32_e32 v1, 0x3fb8aa3b, v1
	v_mul_f32_e32 v4, 0x3fb8aa3b, v4
	v_exp_f32_e32 v3, v1
	v_sub_f32_e32 v1, v25, v34
	v_exp_f32_e32 v4, v4
	v_mul_f32_e32 v1, 0x3fb8aa3b, v1
	v_exp_f32_e32 v24, v1
	v_sub_f32_e32 v1, v26, v34
	v_mul_f32_e32 v0, 0x3fb8aa3b, v0
	v_mul_f32_e32 v1, 0x3fb8aa3b, v1
	v_exp_f32_e32 v23, v0
	v_exp_f32_e32 v25, v1
	v_sub_f32_e32 v1, v27, v34
	v_add_f32_e32 v0, 0, v4
	v_mul_f32_e32 v1, 0x3fb8aa3b, v1
	v_add_f32_e32 v0, v5, v0
	v_exp_f32_e32 v26, v1
	v_sub_f32_e32 v1, v28, v34
	v_add_f32_e32 v0, v22, v0
	v_mul_f32_e32 v1, 0x3fb8aa3b, v1
	v_add_f32_e32 v0, v23, v0
	v_exp_f32_e32 v27, v1
; DI float sort2f(int b) { return __int_as_float(b ^ ((b >> 31) & 0x7fffffff)); }
; DI void phase5a(const Params& p, u16* smem) {
;     ...
;     for (int n = 0; n < 16; ++n) {
;       int id = Lc[n] & 255;
;       sc[n] = sort2f(Lc[n] & ~255);
;       int i1 = my[id >> 4], i2 = my[16 + (id & 15)];
;       ee[n] = i1 * 128 + i2;
;     }
;     float den = 0.f;
;     {
;       const float mxv = sc[0];
; #pragma unroll
;       for (int n = 0; n < 16; ++n) { sc[n] = __expf(sc[n] - mxv); den += sc[n]; }
;     }
;     const float dinv = 1.0f / den;
;     if (h == 0) {
;       const int t = t0 + 32 * w + r;
;       u16* de = (u16*)(ws + OFF_SELE) + (size_t)t * 128 + hd * 16;
;       float* dg = (float*)(ws + OFF_SELG) + (size_t)t * 128 + hd * 16;
; #pragma unroll
;       for (int n = 0; n < 4; ++n) {
;         uint2 pe; pe.x = (unsigned)ee[4 * n] | ((unsigned)ee[4 * n + 1] << 16); pe.y = (unsigned)ee[4 * n + 2] | ((unsigned)ee[4 * n + 3] << 16);
;         *(uint2*)(de + 4 * n) = pe;
;         *(float4*)(dg + 4 * n) = make_float4(sc[4 * n] * dinv, sc[4 * n + 1] * dinv, sc[4 * n + 2] * dinv, sc[4 * n + 3] * dinv);
;       }
;     }
	v_sub_f32_e32 v1, v29, v34
	v_add_f32_e32 v0, v2, v0
	v_mul_f32_e32 v1, 0x3fb8aa3b, v1
	v_add_f32_e32 v0, v3, v0
	v_exp_f32_e32 v28, v1
	v_sub_f32_e32 v1, v30, v34
	v_add_f32_e32 v0, v24, v0
	v_mul_f32_e32 v1, 0x3fb8aa3b, v1
	v_add_f32_e32 v0, v25, v0
	v_exp_f32_e32 v29, v1
	v_add_f32_e32 v0, v26, v0
	v_add_f32_e32 v0, v27, v0
	v_add_f32_e32 v0, v28, v0
	v_add_f32_e32 v36, v29, v0
	v_sub_f32_e32 v0, v31, v34
	v_mul_f32_e32 v0, 0x3fb8aa3b, v0
	v_sub_f32_e32 v1, v32, v34
	v_exp_f32_e32 v0, v0
	v_mul_f32_e32 v1, 0x3fb8aa3b, v1
	v_sub_f32_e32 v30, v33, v34
	v_exp_f32_e32 v1, v1
	v_mul_f32_e32 v30, 0x3fb8aa3b, v30
	v_sub_f32_e32 v31, v35, v34
	v_exp_f32_e32 v30, v30
	v_mul_f32_e32 v31, 0x3fb8aa3b, v31
	v_exp_f32_e32 v31, v31
	v_add_f32_e32 v32, v0, v36
	v_add_f32_e32 v32, v1, v32
	v_add_f32_e32 v32, v30, v32
	v_add_f32_e32 v32, v31, v32
	v_div_scale_f32 v33, s[30:31], v32, v32, 1.0
	v_rcp_f32_e32 v34, v33
	v_bfe_u32 v38, v19, 4, 4
	v_and_b32_e32 v19, 15, v19
	v_bfe_u32 v39, v18, 4, 4
	v_fma_f32 v35, -v33, v34, 1.0
	v_fmac_f32_e32 v34, v35, v34
	v_div_scale_f32 v35, vcc, 1.0, v32, 1.0
	v_mul_f32_e32 v36, v35, v34
	v_fma_f32 v37, -v33, v36, v35
	v_fmac_f32_e32 v36, v37, v34
	v_fma_f32 v33, -v33, v36, v35
	v_bfe_u32 v35, v21, 4, 4
	v_and_b32_e32 v21, 15, v21
	v_bfe_u32 v37, v20, 4, 4
	v_and_b32_e32 v20, 15, v20
	v_add_u32_e32 v35, v199, v35
	v_add_u32_e32 v21, v199, v21
	v_add_u32_e32 v37, v199, v37
	v_add_u32_e32 v20, v199, v20
	v_add_u32_e32 v38, v199, v38
	v_add_u32_e32 v19, v199, v19
	v_add_u32_e32 v39, v199, v39
	v_and_b32_e32 v18, 15, v18
	v_add_u32_e32 v18, v199, v18
	ds_read_u8 v35, v35 offset:33792
	ds_read_u8 v21, v21 offset:33808
	ds_read_u8 v37, v37 offset:33792
	ds_read_u8 v20, v20 offset:33808
	ds_read_u8 v38, v38 offset:33792
	ds_read_u8 v19, v19 offset:33808
	ds_read_u8 v39, v39 offset:33792
	ds_read_u8 v40, v18 offset:33808
	v_div_fmas_f32 v18, v33, v34, v36
	s_waitcnt lgkmcnt(4)
	v_lshl_add_u32 v20, v37, 7, v20
	v_bfe_u32 v33, v17, 4, 4
	v_and_b32_e32 v17, 15, v17
	v_bfe_u32 v34, v16, 4, 4
	v_and_b32_e32 v16, 15, v16
	v_bfe_u32 v36, v15, 4, 4
	v_and_b32_e32 v15, 15, v15
	v_bfe_u32 v37, v14, 4, 4
	v_and_b32_e32 v14, 15, v14
	v_add_u32_e32 v33, v199, v33
	v_add_u32_e32 v17, v199, v17
	v_add_u32_e32 v34, v199, v34
	v_add_u32_e32 v16, v199, v16
	v_add_u32_e32 v36, v199, v36
	v_add_u32_e32 v15, v199, v15
	v_add_u32_e32 v37, v199, v37
	v_add_u32_e32 v14, v199, v14
	ds_read_u8 v33, v33 offset:33792
	ds_read_u8 v17, v17 offset:33808
	ds_read_u8 v34, v34 offset:33792
	ds_read_u8 v16, v16 offset:33808
	ds_read_u8 v36, v36 offset:33792
	ds_read_u8 v15, v15 offset:33808
	ds_read_u8 v37, v37 offset:33792
	ds_read_u8 v14, v14 offset:33808
	v_div_fixup_f32 v18, v18, v32, 1.0
	s_waitcnt lgkmcnt(8)
	v_lshl_add_u32 v32, v39, 7, v40
	s_waitcnt lgkmcnt(4)
	v_lshl_add_u32 v16, v34, 7, v16
	v_bfe_u32 v34, v13, 4, 4
	v_and_b32_e32 v13, 15, v13
	v_bfe_u32 v39, v12, 4, 4
	v_and_b32_e32 v12, 15, v12
	v_bfe_u32 v40, v11, 4, 4
	v_and_b32_e32 v11, 15, v11
	v_bfe_u32 v41, v10, 4, 4
	v_and_b32_e32 v10, 15, v10
	v_add_u32_e32 v34, v199, v34
	v_add_u32_e32 v13, v199, v13
	v_add_u32_e32 v39, v199, v39
	v_add_u32_e32 v12, v199, v12
	v_add_u32_e32 v40, v199, v40
	v_add_u32_e32 v11, v199, v11
	v_add_u32_e32 v41, v199, v41
	v_add_u32_e32 v10, v199, v10
	ds_read_u8 v34, v34 offset:33792
	ds_read_u8 v13, v13 offset:33808
	ds_read_u8 v39, v39 offset:33792
	ds_read_u8 v12, v12 offset:33808
	ds_read_u8 v40, v40 offset:33792
	ds_read_u8 v42, v11 offset:33808
	ds_read_u8 v11, v41 offset:33792
	ds_read_u8 v10, v10 offset:33808
	v_bfe_u32 v41, v8, 4, 4
	v_and_b32_e32 v8, 15, v8
	v_bfe_u32 v43, v7, 4, 4
	v_and_b32_e32 v7, 15, v7
	v_bfe_u32 v44, v6, 4, 4
	v_and_b32_e32 v6, 15, v6
	v_bfe_u32 v45, v9, 4, 4
	v_and_b32_e32 v9, 15, v9
	v_add_u32_e32 v41, v199, v41
	v_add_u32_e32 v8, v199, v8
	v_add_u32_e32 v43, v199, v43
	v_add_u32_e32 v7, v199, v7
	v_add_u32_e32 v44, v199, v44
	v_add_u32_e32 v6, v199, v6
	v_add_u32_e32 v9, v199, v9
	v_add_u32_e32 v45, v199, v45
	ds_read_u8 v41, v41 offset:33792
	ds_read_u8 v46, v8 offset:33808
	ds_read_u8 v8, v43 offset:33792
	ds_read_u8 v7, v7 offset:33808
	ds_read_u8 v43, v44 offset:33792
	ds_read_u8 v44, v6 offset:33808
	ds_read_u8 v6, v45 offset:33792
	ds_read_u8 v9, v9 offset:33808
	s_waitcnt lgkmcnt(12)
	v_lshl_add_u32 v12, v39, 7, v12
	s_waitcnt lgkmcnt(4)
	v_lshl_add_u32 v39, v8, 7, v7
	s_lshl_b32 s10, s81, 5
	v_lshl_add_u32 v14, v37, 7, v14
	s_waitcnt lgkmcnt(0)
	v_lshl_add_u32 v45, v6, 7, v9
	v_lshl_add_u32 v6, s82, 7, v157
	v_ashrrev_i32_e32 v7, 31, v6
	v_lshlrev_b64 v[8:9], 8, v[6:7]
	v_lshl_add_u64 v[8:9], s[20:21], 0, v[8:9]
	v_lshlrev_b64 v[6:7], 9, v[6:7]
	v_lshl_add_u64 v[8:9], v[8:9], 0, s[10:11]
	v_lshl_add_u64 v[6:7], s[22:23], 0, v[6:7]
	s_lshl_b32 s10, s81, 6
	v_lshl_add_u32 v37, v11, 7, v10
	v_lshl_add_u64 v[10:11], v[6:7], 0, s[10:11]
	v_lshlrev_b32_e32 v6, 23, v43
	v_lshlrev_b32_e32 v7, 23, v41
	v_lshl_add_u32 v6, v44, 16, v6
	v_lshl_add_u32 v7, v46, 16, v7
	v_or_b32_e32 v6, v45, v6
	v_or_b32_e32 v7, v39, v7
	global_store_dwordx2 v[8:9], v[6:7], off
	v_pk_mul_f32 v[4:5], v[4:5], v[18:19] op_sel_hi:[1,0]
	v_pk_mul_f32 v[6:7], v[22:23], v[18:19] op_sel_hi:[1,0]
	global_store_dwordx4 v[10:11], v[4:7], off
	v_pk_mul_f32 v[2:3], v[2:3], v[18:19] op_sel_hi:[1,0]
	v_pk_mul_f32 v[0:1], v[0:1], v[18:19] op_sel_hi:[1,0]
	v_lshlrev_b32_e32 v4, 23, v40
	v_lshlrev_b32_e32 v5, 23, v34
	v_lshl_add_u32 v4, v42, 16, v4
	v_lshl_add_u32 v5, v13, 16, v5
	v_or_b32_e32 v4, v37, v4
	v_or_b32_e32 v5, v12, v5
	global_store_dwordx2 v[8:9], v[4:5], off offset:8
	v_pk_mul_f32 v[4:5], v[24:25], v[18:19] op_sel_hi:[1,0]
	global_store_dwordx4 v[10:11], v[2:5], off offset:16
	v_pk_mul_f32 v[6:7], v[28:29], v[18:19] op_sel_hi:[1,0]
	s_nop 0
	v_pk_mul_f32 v[4:5], v[26:27], v[18:19] op_sel_hi:[1,0]
	v_lshlrev_b32_e32 v2, 23, v36
	v_lshlrev_b32_e32 v3, 23, v33
	global_store_dwordx4 v[10:11], v[4:7], off offset:32
	v_lshl_add_u32 v2, v15, 16, v2
	v_lshl_add_u32 v3, v17, 16, v3
	v_lshlrev_b32_e32 v4, 23, v38
	v_lshlrev_b32_e32 v5, 23, v35
	v_lshl_add_u32 v4, v19, 16, v4
	v_lshl_add_u32 v5, v21, 16, v5
	v_or_b32_e32 v2, v14, v2
	v_or_b32_e32 v3, v16, v3
	v_or_b32_e32 v4, v32, v4
	v_or_b32_e32 v5, v20, v5
	global_store_dwordx4 v[8:9], v[2:5], off offset:16
	s_nop 1
	v_pk_mul_f32 v[2:3], v[30:31], v[18:19] op_sel_hi:[1,0]
	global_store_dwordx4 v[10:11], v[0:3], off offset:48
	s_branch .LBB0_358
